# static priority: per-phase flips deleted, one s_setprio 1 for waves 4-7 at kernel entry
# speedup vs baseline: 1.0004x; 1.0004x over previous
; #define LAS __attribute__((address_space(3)))
; __global__ void __launch_bounds__(NTHREADS, 2) fwd_megakernel(Args a) {
;     extern __shared__ __attribute__((aligned(16))) unsigned char lds_raw[];
;     LAS unsigned char* lds = (LAS unsigned char*)lds_raw;
;     cg::grid_group grid = cg::this_grid();
;     const int tid = threadIdx.x, lane = tid & 63, wave = __builtin_amdgcn_readfirstlane(tid >> 6);
;     volatile LAS unsigned* bar_st = (volatile LAS unsigned*)(lds + LDS_MAIN);
;     if (tid == 0) { bar_st[0] = 0u; bar_st[1] = 0u; }
;     __syncthreads();
;     const XcdBarrier xbar = xcd_barrier_post((unsigned*)(a.ws + WS_BAR), bar_st);
_Z14fwd_megakernel4Args:
	s_load_dwordx2 s[66:67], s[0:1], 0xd8
	s_load_dword s54, s[0:1], 0xe0
	s_add_u32 s34, s0, 0xd8
	v_and_b32_e32 v160, 0x3ff, v0
	s_addc_u32 s35, s1, 0
	v_readfirstlane_b32 s3, v160
	v_cmp_eq_u32_e64 s[4:5], 0, v160
	s_nop 0
	v_writelane_b32 v243, s3, 0
	s_nop 1
	s_lshr_b32 s98, s3, 6
	s_cmp_ge_u32 s98, 4
	s_cbranch_scc0 .Lprio_done
	s_setprio 1
.Lprio_done:
	s_mov_b64 s[6:7], exec
	v_writelane_b32 v243, s4, 1
	s_nop 1
	v_writelane_b32 v243, s5, 2
	s_and_b64 s[4:5], s[6:7], s[4:5]
	s_mov_b64 exec, s[4:5]
	s_cbranch_execz .LBB0_2
	s_add_i32 s3, 0, 0x22000
	v_mov_b32_e32 v1, 0
	v_mov_b32_e32 v2, s3
	s_add_i32 s3, 0, 0x22004
	ds_write_b32 v2, v1
	v_mov_b32_e32 v2, s3
	ds_write_b32 v2, v1

; #define PG8_STAGE(bufoff, gbase, voff) do { _Pragma("unroll") for (int _i = 0; _i < 2; ++_i) \
;         __builtin_amdgcn_global_load_lds((const unsigned*)((const char*)(gbase) + (voff)[_i]), (PG8_LAS unsigned*)(lds + (bufoff) + ldsw + _i * 8192), 16, 0, 0); } while (0)
; #define PG8_LDA(dst, b, h) do { _Pragma("unroll") for (int m = 0; m < 4; ++m) _Pragma("unroll") for (int k = 0; k < 2; ++k) dst[m][k] = *(const PG8_LAS bf16x8*)(lds + PG8_SA(b, h) + aoff + m * 2048 + k * 1024); } while (0)
; #define PG8_LDB(dst, b, h) do { _Pragma("unroll") for (int n = 0; n < 2; ++n) _Pragma("unroll") for (int k = 0; k < 2; ++k) dst[n][k] = *(const PG8_LAS bf16x8*)(lds + PG8_SB(b, h) + boff + n * 2048 + k * 1024); } while (0)
; #define PG8_MMA(ai, bj, At, Bt) do { __builtin_amdgcn_s_setprio(1); _Pragma("unroll") for (int m = 0; m < 4; ++m) _Pragma("unroll") for (int n = 0; n < 2; ++n) _Pragma("unroll") for (int k = 0; k < 2; ++k) \
;         acc[ai][bj][m][n] = __builtin_amdgcn_mfma_f32_16x16x32_bf16(Bt[n][k], At[m][k], acc[ai][bj][m][n], 0, 0, 0); __builtin_amdgcn_s_setprio(0); } while (0)
; #define PG8_WAIT_V(n) asm volatile("s_waitcnt vmcnt(" #n ")" ::: "memory")
; #define PG8_WAIT_L(n) asm volatile("s_waitcnt lgkmcnt(" #n ")" ::: "memory")
; #define PG8_BAR __builtin_amdgcn_s_barrier()
; #define PG8_SCHED __builtin_amdgcn_sched_barrier(0)
; template <class Epi, class Sched, bool ALIGN_EPI = false, bool SP2 = false>
; __device__ __forceinline__ void gemm_phase(PG8_LAS unsigned char* lds, const Gemm g, const Sched& S, const Epi& E) {
;     ...
;             PG8_LDB(B0, 0, 0); PG8_LDB(B1, 0, 1); PG8_SCHED; PG8_LDA(At, 0, 0); PG8_STAGE(PG8_SA(1, 1), a1 + hstep, voffA);
;             PG8_WAIT_V(8); PG8_WAIT_L(0); PG8_BAR; PG8_MMA(0, 0, At, B0); PG8_MMA(0, 1, At, B1); PG8_BAR; PG8_SCHED;
;             PG8_LDA(At, 0, 1); PG8_STAGE(PG8_SB(0, 0), b2, voffB); PG8_STAGE(PG8_SB(0, 1), b2 + hstep, voffB); PG8_STAGE(PG8_SA(0, 0), a2, voffA);
.LBB0_218:
	ds_read_b128 v[148:151], v157
	ds_read_b128 v[166:169], v157 offset:1024
	ds_read_b128 v[172:175], v157 offset:2048
	ds_read_b128 v[176:179], v157 offset:3072
	ds_read_b128 v[180:183], v158
	ds_read_b128 v[184:187], v158 offset:1024
	ds_read_b128 v[188:191], v158 offset:2048
	ds_read_b128 v[196:199], v158 offset:3072
	s_add_u32 s6, s52, 0xfffc0080
	s_addc_u32 s7, s53, -1
	s_cmp_eq_u32 s72, 12
	s_cselect_b32 s57, s4, s7
	s_cselect_b32 s56, s41, s6
	s_cselect_b32 s55, s39, s33
	s_cselect_b32 s54, s78, s79
	v_lshl_add_u64 v[152:153], s[52:53], 0, v[140:141]
	s_add_i32 m0, s37, 0xc000
	ds_read_b128 v[200:203], v159
	ds_read_b128 v[204:207], v159 offset:1024
	ds_read_b128 v[208:211], v159 offset:2048
	ds_read_b128 v[212:215], v159 offset:3072
	ds_read_b128 v[216:219], v159 offset:4096
	ds_read_b128 v[220:223], v159 offset:5120
	ds_read_b128 v[224:227], v159 offset:6144
	ds_read_b128 v[228:231], v159 offset:7168
	global_load_lds_dwordx4 v[152:153], off
	v_lshl_add_u64 v[152:153], s[52:53], 0, v[142:143]
	s_add_i32 m0, s37, 0xe000
	s_nop 0
	global_load_lds_dwordx4 v[152:153], off
	s_waitcnt vmcnt(8)
	s_waitcnt lgkmcnt(0)
	s_barrier
	s_waitcnt lgkmcnt(0)
	v_mfma_f32_16x16x32_bf16 v[124:127], v[148:151], v[200:203], v[124:127]
	v_mfma_f32_16x16x32_bf16 v[116:119], v[172:175], v[200:203], v[116:119]
	v_mfma_f32_16x16x32_bf16 v[108:111], v[148:151], v[208:211], v[108:111]
	v_mfma_f32_16x16x32_bf16 v[100:103], v[172:175], v[208:211], v[100:103]
	v_mfma_f32_16x16x32_bf16 v[92:95], v[148:151], v[216:219], v[92:95]
	v_mfma_f32_16x16x32_bf16 v[84:87], v[172:175], v[216:219], v[84:87]
	v_mfma_f32_16x16x32_bf16 v[76:79], v[148:151], v[224:227], v[76:79]
	v_mfma_f32_16x16x32_bf16 v[68:71], v[172:175], v[224:227], v[68:71]
	v_mfma_f32_16x16x32_bf16 v[124:127], v[166:169], v[204:207], v[124:127]
	v_mfma_f32_16x16x32_bf16 v[116:119], v[176:179], v[204:207], v[116:119]
	v_mfma_f32_16x16x32_bf16 v[108:111], v[166:169], v[212:215], v[108:111]
	v_mfma_f32_16x16x32_bf16 v[100:103], v[176:179], v[212:215], v[100:103]
	v_mfma_f32_16x16x32_bf16 v[92:95], v[166:169], v[220:223], v[92:95]
	v_mfma_f32_16x16x32_bf16 v[84:87], v[176:179], v[220:223], v[84:87]
	v_mfma_f32_16x16x32_bf16 v[76:79], v[166:169], v[228:231], v[76:79]
	v_mfma_f32_16x16x32_bf16 v[68:71], v[176:179], v[228:231], v[68:71]
	v_mfma_f32_16x16x32_bf16 v[120:123], v[180:183], v[200:203], v[120:123]
	v_mfma_f32_16x16x32_bf16 v[112:115], v[188:191], v[200:203], v[112:115]
	v_mfma_f32_16x16x32_bf16 v[104:107], v[180:183], v[208:211], v[104:107]
	v_mfma_f32_16x16x32_bf16 v[96:99], v[188:191], v[208:211], v[96:99]
	v_mfma_f32_16x16x32_bf16 v[88:91], v[180:183], v[216:219], v[88:91]
	v_mfma_f32_16x16x32_bf16 v[80:83], v[188:191], v[216:219], v[80:83]
	v_mfma_f32_16x16x32_bf16 v[72:75], v[180:183], v[224:227], v[72:75]
	v_mfma_f32_16x16x32_bf16 v[64:67], v[188:191], v[224:227], v[64:67]
	v_mfma_f32_16x16x32_bf16 v[120:123], v[184:187], v[204:207], v[120:123]
	v_mfma_f32_16x16x32_bf16 v[112:115], v[196:199], v[204:207], v[112:115]
	v_mfma_f32_16x16x32_bf16 v[104:107], v[184:187], v[212:215], v[104:107]
	v_mfma_f32_16x16x32_bf16 v[96:99], v[196:199], v[212:215], v[96:99]
	v_mfma_f32_16x16x32_bf16 v[88:91], v[184:187], v[220:223], v[88:91]
	v_mfma_f32_16x16x32_bf16 v[80:83], v[196:199], v[220:223], v[80:83]
	v_mfma_f32_16x16x32_bf16 v[72:75], v[184:187], v[228:231], v[72:75]
	v_mfma_f32_16x16x32_bf16 v[64:67], v[196:199], v[228:231], v[64:67]
	s_barrier
	s_add_i32 s6, s69, s36
	v_lshl_add_u64 v[152:153], s[54:55], 0, v[136:137]
	s_mov_b32 m0, s6
	ds_read_b128 v[200:203], v159 offset:16384
	ds_read_b128 v[204:207], v159 offset:17408
	ds_read_b128 v[208:211], v159 offset:18432
	ds_read_b128 v[212:215], v159 offset:19456
	ds_read_b128 v[216:219], v159 offset:20480
	ds_read_b128 v[220:223], v159 offset:21504
	ds_read_b128 v[224:227], v159 offset:22528
	ds_read_b128 v[228:231], v159 offset:23552
	global_load_lds_dwordx4 v[152:153], off
	s_add_i32 m0, s6, 0x2000
	s_add_u32 s6, s54, 0x40000
	v_lshl_add_u64 v[162:163], s[54:55], 0, v[132:133]
	s_addc_u32 s7, s55, 0
	s_add_i32 s73, s74, s36
	global_load_lds_dwordx4 v[162:163], off
	v_lshl_add_u64 v[232:233], s[6:7], 0, v[136:137]
	s_mov_b32 m0, s73
	v_lshl_add_u64 v[234:235], s[56:57], 0, v[134:135]
	global_load_lds_dwordx4 v[232:233], off
	v_lshl_add_u64 v[232:233], s[6:7], 0, v[132:133]
	s_add_i32 m0, s73, 0x2000
	s_nop 0
	global_load_lds_dwordx4 v[232:233], off
	v_lshl_add_u64 v[232:233], s[56:57], 0, v[138:139]
	s_mov_b32 m0, s37
	s_nop 0
	global_load_lds_dwordx4 v[232:233], off
	s_mov_b32 m0, s59
	s_nop 0
	global_load_lds_dwordx4 v[234:235], off
	s_waitcnt vmcnt(8)
	s_waitcnt lgkmcnt(0)
	s_barrier
; #define PG8_STAGE(bufoff, gbase, voff) do { _Pragma("unroll") for (int _i = 0; _i < 2; ++_i) \
;         __builtin_amdgcn_global_load_lds((const unsigned*)((const char*)(gbase) + (voff)[_i]), (PG8_LAS unsigned*)(lds + (bufoff) + ldsw + _i * 8192), 16, 0, 0); } while (0)
; #define PG8_LDA(dst, b, h) do { _Pragma("unroll") for (int m = 0; m < 4; ++m) _Pragma("unroll") for (int k = 0; k < 2; ++k) dst[m][k] = *(const PG8_LAS bf16x8*)(lds + PG8_SA(b, h) + aoff + m * 2048 + k * 1024); } while (0)
; #define PG8_LDB(dst, b, h) do { _Pragma("unroll") for (int n = 0; n < 2; ++n) _Pragma("unroll") for (int k = 0; k < 2; ++k) dst[n][k] = *(const PG8_LAS bf16x8*)(lds + PG8_SB(b, h) + boff + n * 2048 + k * 1024); } while (0)
; #define PG8_MMA(ai, bj, At, Bt) do { __builtin_amdgcn_s_setprio(1); _Pragma("unroll") for (int m = 0; m < 4; ++m) _Pragma("unroll") for (int n = 0; n < 2; ++n) _Pragma("unroll") for (int k = 0; k < 2; ++k) \
;         acc[ai][bj][m][n] = __builtin_amdgcn_mfma_f32_16x16x32_bf16(Bt[n][k], At[m][k], acc[ai][bj][m][n], 0, 0, 0); __builtin_amdgcn_s_setprio(0); } while (0)
; #define PG8_WAIT_V(n) asm volatile("s_waitcnt vmcnt(" #n ")" ::: "memory")
; #define PG8_WAIT_L(n) asm volatile("s_waitcnt lgkmcnt(" #n ")" ::: "memory")
; #define PG8_BAR __builtin_amdgcn_s_barrier()
; #define PG8_SCHED __builtin_amdgcn_sched_barrier(0)
; template <class Epi, class Sched, bool ALIGN_EPI = false, bool SP2 = false>
; __device__ __forceinline__ void gemm_phase(PG8_LAS unsigned char* lds, const Gemm g, const Sched& S, const Epi& E) {
;     ...
;             PG8_WAIT_V(8); PG8_WAIT_L(0); PG8_BAR; PG8_MMA(1, 0, At, B0); PG8_MMA(1, 1, At, B1); PG8_BAR; PG8_SCHED;
;             PG8_LDB(B0, 1, 0); PG8_LDB(B1, 1, 1); PG8_SCHED; PG8_LDA(At, 1, 0); PG8_STAGE(PG8_SA(0, 1), a2 + hstep, voffA);
;             PG8_WAIT_V(8); PG8_WAIT_L(0); PG8_BAR; PG8_MMA(0, 0, At, B0); PG8_MMA(0, 1, At, B1); PG8_BAR; PG8_SCHED;
	s_waitcnt lgkmcnt(0)
	v_mfma_f32_16x16x32_bf16 v[60:63], v[148:151], v[200:203], v[60:63]
	v_mfma_f32_16x16x32_bf16 v[52:55], v[172:175], v[200:203], v[52:55]
	v_mfma_f32_16x16x32_bf16 v[44:47], v[148:151], v[208:211], v[44:47]
	v_mfma_f32_16x16x32_bf16 v[36:39], v[172:175], v[208:211], v[36:39]
	v_mfma_f32_16x16x32_bf16 v[28:31], v[148:151], v[216:219], v[28:31]
	v_mfma_f32_16x16x32_bf16 v[20:23], v[172:175], v[216:219], v[20:23]
	v_mfma_f32_16x16x32_bf16 v[12:15], v[148:151], v[224:227], v[12:15]
	v_mfma_f32_16x16x32_bf16 v[4:7], v[172:175], v[224:227], v[4:7]
	v_mfma_f32_16x16x32_bf16 v[60:63], v[166:169], v[204:207], v[60:63]
	v_mfma_f32_16x16x32_bf16 v[52:55], v[176:179], v[204:207], v[52:55]
	v_mfma_f32_16x16x32_bf16 v[44:47], v[166:169], v[212:215], v[44:47]
	v_mfma_f32_16x16x32_bf16 v[36:39], v[176:179], v[212:215], v[36:39]
	v_mfma_f32_16x16x32_bf16 v[28:31], v[166:169], v[220:223], v[28:31]
	v_mfma_f32_16x16x32_bf16 v[20:23], v[176:179], v[220:223], v[20:23]
	v_mfma_f32_16x16x32_bf16 v[12:15], v[166:169], v[228:231], v[12:15]
	v_mfma_f32_16x16x32_bf16 v[4:7], v[176:179], v[228:231], v[4:7]
	v_mfma_f32_16x16x32_bf16 v[56:59], v[180:183], v[200:203], v[56:59]
	v_mfma_f32_16x16x32_bf16 v[48:51], v[188:191], v[200:203], v[48:51]
	v_mfma_f32_16x16x32_bf16 v[40:43], v[180:183], v[208:211], v[40:43]
	v_mfma_f32_16x16x32_bf16 v[32:35], v[188:191], v[208:211], v[32:35]
	v_mfma_f32_16x16x32_bf16 v[24:27], v[180:183], v[216:219], v[24:27]
	v_mfma_f32_16x16x32_bf16 v[16:19], v[188:191], v[216:219], v[16:19]
	v_mfma_f32_16x16x32_bf16 v[8:11], v[180:183], v[224:227], v[8:11]
	v_mfma_f32_16x16x32_bf16 v[0:3], v[188:191], v[224:227], v[0:3]
	v_mfma_f32_16x16x32_bf16 v[56:59], v[184:187], v[204:207], v[56:59]
	v_mfma_f32_16x16x32_bf16 v[48:51], v[196:199], v[204:207], v[48:51]
	v_mfma_f32_16x16x32_bf16 v[40:43], v[184:187], v[212:215], v[40:43]
	v_mfma_f32_16x16x32_bf16 v[32:35], v[196:199], v[212:215], v[32:35]
	v_mfma_f32_16x16x32_bf16 v[24:27], v[184:187], v[220:223], v[24:27]
	v_mfma_f32_16x16x32_bf16 v[16:19], v[196:199], v[220:223], v[16:19]
	v_mfma_f32_16x16x32_bf16 v[8:11], v[184:187], v[228:231], v[8:11]
	v_mfma_f32_16x16x32_bf16 v[0:3], v[196:199], v[228:231], v[0:3]
	s_barrier
	s_add_i32 s73, 0, 0x18000
	v_add_u32_e32 v161, s73, v154
	s_add_i32 s80, 0, 0x1c000
	ds_read_b128 v[148:151], v161
	ds_read_b128 v[166:169], v161 offset:1024
	ds_read_b128 v[172:175], v161 offset:2048
	ds_read_b128 v[176:179], v161 offset:3072
	v_add_u32_e32 v161, s80, v154
	ds_read_b128 v[180:183], v161
	ds_read_b128 v[184:187], v161 offset:1024
	ds_read_b128 v[188:191], v161 offset:2048
	ds_read_b128 v[196:199], v161 offset:3072
	s_add_u32 s6, s56, 0x40000
	s_addc_u32 s7, s57, 0
	s_mov_b32 m0, s60
	v_lshl_add_u64 v[236:237], s[6:7], 0, v[138:139]
	ds_read_b128 v[200:203], v159 offset:32768
	ds_read_b128 v[204:207], v159 offset:33792
	ds_read_b128 v[208:211], v159 offset:34816
	ds_read_b128 v[212:215], v159 offset:35840
	ds_read_b128 v[216:219], v159 offset:36864
	ds_read_b128 v[220:223], v159 offset:37888
	ds_read_b128 v[224:227], v159 offset:38912
	ds_read_b128 v[228:231], v159 offset:39936
	global_load_lds_dwordx4 v[236:237], off
	v_lshl_add_u64 v[236:237], s[6:7], 0, v[134:135]
	s_mov_b32 m0, s61
	s_nop 0
	global_load_lds_dwordx4 v[236:237], off
	s_waitcnt vmcnt(8)
	s_waitcnt lgkmcnt(0)
	s_barrier
	s_waitcnt lgkmcnt(0)
	v_mfma_f32_16x16x32_bf16 v[124:127], v[148:151], v[200:203], v[124:127]
	v_mfma_f32_16x16x32_bf16 v[116:119], v[172:175], v[200:203], v[116:119]
	v_mfma_f32_16x16x32_bf16 v[108:111], v[148:151], v[208:211], v[108:111]
	v_mfma_f32_16x16x32_bf16 v[100:103], v[172:175], v[208:211], v[100:103]
	v_mfma_f32_16x16x32_bf16 v[92:95], v[148:151], v[216:219], v[92:95]
	v_mfma_f32_16x16x32_bf16 v[84:87], v[172:175], v[216:219], v[84:87]
	v_mfma_f32_16x16x32_bf16 v[76:79], v[148:151], v[224:227], v[76:79]
	v_mfma_f32_16x16x32_bf16 v[68:71], v[172:175], v[224:227], v[68:71]
	v_mfma_f32_16x16x32_bf16 v[124:127], v[166:169], v[204:207], v[124:127]
	v_mfma_f32_16x16x32_bf16 v[116:119], v[176:179], v[204:207], v[116:119]
	v_mfma_f32_16x16x32_bf16 v[108:111], v[166:169], v[212:215], v[108:111]
	v_mfma_f32_16x16x32_bf16 v[100:103], v[176:179], v[212:215], v[100:103]
	v_mfma_f32_16x16x32_bf16 v[92:95], v[166:169], v[220:223], v[92:95]
	v_mfma_f32_16x16x32_bf16 v[84:87], v[176:179], v[220:223], v[84:87]
	v_mfma_f32_16x16x32_bf16 v[76:79], v[166:169], v[228:231], v[76:79]
	v_mfma_f32_16x16x32_bf16 v[68:71], v[176:179], v[228:231], v[68:71]
	v_mfma_f32_16x16x32_bf16 v[120:123], v[180:183], v[200:203], v[120:123]
	v_mfma_f32_16x16x32_bf16 v[112:115], v[188:191], v[200:203], v[112:115]
	v_mfma_f32_16x16x32_bf16 v[104:107], v[180:183], v[208:211], v[104:107]
	v_mfma_f32_16x16x32_bf16 v[96:99], v[188:191], v[208:211], v[96:99]
	v_mfma_f32_16x16x32_bf16 v[88:91], v[180:183], v[216:219], v[88:91]
	v_mfma_f32_16x16x32_bf16 v[80:83], v[188:191], v[216:219], v[80:83]
	v_mfma_f32_16x16x32_bf16 v[72:75], v[180:183], v[224:227], v[72:75]
	v_mfma_f32_16x16x32_bf16 v[64:67], v[188:191], v[224:227], v[64:67]
	v_mfma_f32_16x16x32_bf16 v[120:123], v[184:187], v[204:207], v[120:123]
	v_mfma_f32_16x16x32_bf16 v[112:115], v[196:199], v[204:207], v[112:115]
	v_mfma_f32_16x16x32_bf16 v[104:107], v[184:187], v[212:215], v[104:107]
	v_mfma_f32_16x16x32_bf16 v[96:99], v[196:199], v[212:215], v[96:99]
	v_mfma_f32_16x16x32_bf16 v[88:91], v[184:187], v[220:223], v[88:91]
	v_mfma_f32_16x16x32_bf16 v[80:83], v[196:199], v[220:223], v[80:83]
	v_mfma_f32_16x16x32_bf16 v[72:75], v[184:187], v[228:231], v[72:75]
	v_mfma_f32_16x16x32_bf16 v[64:67], v[196:199], v[228:231], v[64:67]
	s_barrier
; #define PG8_STAGE(bufoff, gbase, voff) do { _Pragma("unroll") for (int _i = 0; _i < 2; ++_i) \
;         __builtin_amdgcn_global_load_lds((const unsigned*)((const char*)(gbase) + (voff)[_i]), (PG8_LAS unsigned*)(lds + (bufoff) + ldsw + _i * 8192), 16, 0, 0); } while (0)
; #define PG8_LDA(dst, b, h) do { _Pragma("unroll") for (int m = 0; m < 4; ++m) _Pragma("unroll") for (int k = 0; k < 2; ++k) dst[m][k] = *(const PG8_LAS bf16x8*)(lds + PG8_SA(b, h) + aoff + m * 2048 + k * 1024); } while (0)
; #define PG8_MMA(ai, bj, At, Bt) do { __builtin_amdgcn_s_setprio(1); _Pragma("unroll") for (int m = 0; m < 4; ++m) _Pragma("unroll") for (int n = 0; n < 2; ++n) _Pragma("unroll") for (int k = 0; k < 2; ++k) \
;         acc[ai][bj][m][n] = __builtin_amdgcn_mfma_f32_16x16x32_bf16(Bt[n][k], At[m][k], acc[ai][bj][m][n], 0, 0, 0); __builtin_amdgcn_s_setprio(0); } while (0)
; #define PG8_WAIT_V(n) asm volatile("s_waitcnt vmcnt(" #n ")" ::: "memory")
; #define PG8_WAIT_L(n) asm volatile("s_waitcnt lgkmcnt(" #n ")" ::: "memory")
; #define PG8_BAR __builtin_amdgcn_s_barrier()
; #define PG8_SCHED __builtin_amdgcn_sched_barrier(0)
; template <class Epi, class Sched, bool ALIGN_EPI = false, bool SP2 = false>
; __device__ __forceinline__ void gemm_phase(PG8_LAS unsigned char* lds, const Gemm g, const Sched& S, const Epi& E) {
;     ...
;             PG8_LDA(At, 1, 1); PG8_STAGE(PG8_SB(1, 0), b3, voffB); PG8_STAGE(PG8_SB(1, 1), b3 + hstep, voffB); PG8_STAGE(PG8_SA(1, 0), a3, voffA);
;             PG8_WAIT_V(8); PG8_WAIT_L(0); PG8_BAR; PG8_MMA(1, 0, At, B0); PG8_MMA(1, 1, At, B1); PG8_BAR; PG8_SCHED;
	s_add_i32 s6, s73, s36
	v_lshl_add_u64 v[152:153], v[152:153], 0, s[30:31]
	s_mov_b32 m0, s6
	ds_read_b128 v[200:203], v159 offset:49152
	ds_read_b128 v[204:207], v159 offset:50176
	ds_read_b128 v[208:211], v159 offset:51200
	ds_read_b128 v[212:215], v159 offset:52224
	ds_read_b128 v[216:219], v159 offset:53248
	ds_read_b128 v[220:223], v159 offset:54272
	ds_read_b128 v[224:227], v159 offset:55296
	ds_read_b128 v[228:231], v159 offset:56320
	global_load_lds_dwordx4 v[152:153], off
	s_add_i32 m0, s6, 0x2000
	s_add_u32 s6, s54, 0x40080
	v_lshl_add_u64 v[152:153], v[162:163], 0, s[30:31]
	s_addc_u32 s7, s55, 0
	s_add_i32 s54, s80, s36
	global_load_lds_dwordx4 v[152:153], off
	v_lshl_add_u64 v[152:153], s[6:7], 0, v[136:137]
	s_mov_b32 m0, s54
	s_nop 0
	global_load_lds_dwordx4 v[152:153], off
	v_lshl_add_u64 v[152:153], s[6:7], 0, v[132:133]
	s_add_i32 m0, s54, 0x2000
	s_nop 0
	global_load_lds_dwordx4 v[152:153], off
	v_lshl_add_u64 v[152:153], v[232:233], 0, s[30:31]
	s_mov_b32 m0, s67
	s_nop 0
	global_load_lds_dwordx4 v[152:153], off
	v_lshl_add_u64 v[152:153], v[234:235], 0, s[30:31]
	s_mov_b32 m0, s68
	s_nop 0
	global_load_lds_dwordx4 v[152:153], off
	s_waitcnt vmcnt(8)
	s_waitcnt lgkmcnt(0)
	s_barrier
	s_waitcnt lgkmcnt(0)
	v_mfma_f32_16x16x32_bf16 v[60:63], v[148:151], v[200:203], v[60:63]
	v_mfma_f32_16x16x32_bf16 v[52:55], v[172:175], v[200:203], v[52:55]
	v_mfma_f32_16x16x32_bf16 v[44:47], v[148:151], v[208:211], v[44:47]
	v_mfma_f32_16x16x32_bf16 v[36:39], v[172:175], v[208:211], v[36:39]
	v_mfma_f32_16x16x32_bf16 v[28:31], v[148:151], v[216:219], v[28:31]
	v_mfma_f32_16x16x32_bf16 v[20:23], v[172:175], v[216:219], v[20:23]
	v_mfma_f32_16x16x32_bf16 v[12:15], v[148:151], v[224:227], v[12:15]
	v_mfma_f32_16x16x32_bf16 v[4:7], v[172:175], v[224:227], v[4:7]
	v_mfma_f32_16x16x32_bf16 v[60:63], v[166:169], v[204:207], v[60:63]
	v_mfma_f32_16x16x32_bf16 v[52:55], v[176:179], v[204:207], v[52:55]
	v_mfma_f32_16x16x32_bf16 v[44:47], v[166:169], v[212:215], v[44:47]
	v_mfma_f32_16x16x32_bf16 v[36:39], v[176:179], v[212:215], v[36:39]
	v_mfma_f32_16x16x32_bf16 v[28:31], v[166:169], v[220:223], v[28:31]
	v_mfma_f32_16x16x32_bf16 v[20:23], v[176:179], v[220:223], v[20:23]
	v_mfma_f32_16x16x32_bf16 v[12:15], v[166:169], v[228:231], v[12:15]
	v_mfma_f32_16x16x32_bf16 v[4:7], v[176:179], v[228:231], v[4:7]
	v_mfma_f32_16x16x32_bf16 v[56:59], v[180:183], v[200:203], v[56:59]
	v_mfma_f32_16x16x32_bf16 v[48:51], v[188:191], v[200:203], v[48:51]
	v_mfma_f32_16x16x32_bf16 v[40:43], v[180:183], v[208:211], v[40:43]
	v_mfma_f32_16x16x32_bf16 v[32:35], v[188:191], v[208:211], v[32:35]
	v_mfma_f32_16x16x32_bf16 v[24:27], v[180:183], v[216:219], v[24:27]
	v_mfma_f32_16x16x32_bf16 v[16:19], v[188:191], v[216:219], v[16:19]
	v_mfma_f32_16x16x32_bf16 v[8:11], v[180:183], v[224:227], v[8:11]
	v_mfma_f32_16x16x32_bf16 v[0:3], v[188:191], v[224:227], v[0:3]
	v_mfma_f32_16x16x32_bf16 v[56:59], v[184:187], v[204:207], v[56:59]
	v_mfma_f32_16x16x32_bf16 v[48:51], v[196:199], v[204:207], v[48:51]
	v_mfma_f32_16x16x32_bf16 v[40:43], v[184:187], v[212:215], v[40:43]
	v_mfma_f32_16x16x32_bf16 v[32:35], v[196:199], v[212:215], v[32:35]
	v_mfma_f32_16x16x32_bf16 v[24:27], v[184:187], v[220:223], v[24:27]
	v_mfma_f32_16x16x32_bf16 v[16:19], v[196:199], v[220:223], v[16:19]
	v_mfma_f32_16x16x32_bf16 v[8:11], v[184:187], v[228:231], v[8:11]
	v_mfma_f32_16x16x32_bf16 v[0:3], v[196:199], v[228:231], v[0:3]
	s_barrier
	s_add_i32 s72, s72, 2
	s_add_u32 s52, s52, 0x100
	s_addc_u32 s53, s53, 0
	s_add_u32 s79, s79, 0x100
	s_addc_u32 s33, s33, 0
	s_cmp_gt_u32 s72, 13
	s_cbranch_scc0 .LBB0_218
	s_and_b64 vcc, exec, s[34:35]
	s_cbranch_vccz .LBB0_221
	s_barrier

; #define PG8_STAGE(bufoff, gbase, voff) do { _Pragma("unroll") for (int _i = 0; _i < 2; ++_i) \
;         __builtin_amdgcn_global_load_lds((const unsigned*)((const char*)(gbase) + (voff)[_i]), (PG8_LAS unsigned*)(lds + (bufoff) + ldsw + _i * 8192), 16, 0, 0); } while (0)
; #define PG8_LDA(dst, b, h) do { _Pragma("unroll") for (int m = 0; m < 4; ++m) _Pragma("unroll") for (int k = 0; k < 2; ++k) dst[m][k] = *(const PG8_LAS bf16x8*)(lds + PG8_SA(b, h) + aoff + m * 2048 + k * 1024); } while (0)
; #define PG8_LDB(dst, b, h) do { _Pragma("unroll") for (int n = 0; n < 2; ++n) _Pragma("unroll") for (int k = 0; k < 2; ++k) dst[n][k] = *(const PG8_LAS bf16x8*)(lds + PG8_SB(b, h) + boff + n * 2048 + k * 1024); } while (0)
; #define PG8_MMA(ai, bj, At, Bt) do { __builtin_amdgcn_s_setprio(1); _Pragma("unroll") for (int m = 0; m < 4; ++m) _Pragma("unroll") for (int n = 0; n < 2; ++n) _Pragma("unroll") for (int k = 0; k < 2; ++k) \
;         acc[ai][bj][m][n] = __builtin_amdgcn_mfma_f32_16x16x32_bf16(Bt[n][k], At[m][k], acc[ai][bj][m][n], 0, 0, 0); __builtin_amdgcn_s_setprio(0); } while (0)
; #define PG8_WAIT_V(n) asm volatile("s_waitcnt vmcnt(" #n ")" ::: "memory")
; #define PG8_WAIT_L(n) asm volatile("s_waitcnt lgkmcnt(" #n ")" ::: "memory")
; #define PG8_BAR __builtin_amdgcn_s_barrier()
; #define PG8_SCHED __builtin_amdgcn_sched_barrier(0)
; template <class Epi, class Sched, bool ALIGN_EPI = false, bool SP2 = false>
; __device__ __forceinline__ void gemm_phase(PG8_LAS unsigned char* lds, const Gemm g, const Sched& S, const Epi& E) {
;     ...
;             const bool last = (t == nt - 2);
;             const char* a1 = cA + (size_t)(t + 1) * kstep;
;             const char* a2 = last ? nA : cA + (size_t)(t + 2) * kstep; const char* b2 = last ? nB : cB + (size_t)(t + 2) * kstep;
;             const char* a3 = a2 + kstep; const char* b3 = b2 + kstep;
;             if (last && has_next) S.a_ready(nxt);
;             if constexpr (SP2) {
;             PG8_LDB(B0, 0, 0); PG8_LDB(B1, 0, 1); PG8_SCHED; PG8_LDA(At, 0, 0); PG8_STAGE(PG8_SA(1, 1), a1 + hstep, voffA);
;             PG8_WAIT_V(8); PG8_WAIT_L(0); PG8_BAR; PG8_MMA(0, 0, At, B0); PG8_MMA(0, 1, At, B1); PG8_BAR; PG8_SCHED;
;             PG8_LDA(At, 0, 1); PG8_STAGE(PG8_SB(0, 0), b2, voffB); PG8_STAGE(PG8_SB(0, 1), b2 + hstep, voffB); PG8_STAGE(PG8_SA(0, 0), a2, voffA);
.LBB0_323:
	ds_read_b128 v[148:151], v156
	ds_read_b128 v[166:169], v156 offset:1024
	ds_read_b128 v[172:175], v156 offset:2048
	ds_read_b128 v[176:179], v156 offset:3072
	ds_read_b128 v[180:183], v157
	ds_read_b128 v[184:187], v157 offset:1024
	ds_read_b128 v[188:191], v157 offset:2048
	ds_read_b128 v[196:199], v157 offset:3072
	s_add_u32 s56, s54, 0x100
	s_addc_u32 s57, s55, 0
	s_cmp_eq_u32 s69, 40
	s_cselect_b32 s61, s51, s57
	s_cselect_b32 s60, s50, s56
	s_cselect_b32 s59, s53, s33
	s_cselect_b32 s58, s52, s4
	v_lshl_add_u64 v[152:153], s[54:55], 0, v[140:141]
	s_add_i32 m0, s37, 0xc000
	ds_read_b128 v[200:203], v158
	ds_read_b128 v[204:207], v158 offset:1024
	ds_read_b128 v[208:211], v158 offset:2048
	ds_read_b128 v[212:215], v158 offset:3072
	ds_read_b128 v[216:219], v158 offset:4096
	ds_read_b128 v[220:223], v158 offset:5120
	ds_read_b128 v[224:227], v158 offset:6144
	ds_read_b128 v[228:231], v158 offset:7168
	global_load_lds_dwordx4 v[152:153], off
	v_lshl_add_u64 v[152:153], s[54:55], 0, v[142:143]
	s_add_i32 m0, s37, 0xe000
	s_nop 0
	global_load_lds_dwordx4 v[152:153], off
	s_waitcnt vmcnt(8)
	s_waitcnt lgkmcnt(0)
	s_barrier
	s_waitcnt lgkmcnt(0)
	v_mfma_f32_16x16x32_bf16 v[124:127], v[148:151], v[200:203], v[124:127]
	v_mfma_f32_16x16x32_bf16 v[120:123], v[172:175], v[200:203], v[120:123]
	v_mfma_f32_16x16x32_bf16 v[108:111], v[148:151], v[208:211], v[108:111]
	v_mfma_f32_16x16x32_bf16 v[104:107], v[172:175], v[208:211], v[104:107]
	v_mfma_f32_16x16x32_bf16 v[92:95], v[148:151], v[216:219], v[92:95]
	v_mfma_f32_16x16x32_bf16 v[88:91], v[172:175], v[216:219], v[88:91]
	v_mfma_f32_16x16x32_bf16 v[76:79], v[148:151], v[224:227], v[76:79]
	v_mfma_f32_16x16x32_bf16 v[72:75], v[172:175], v[224:227], v[72:75]
	v_mfma_f32_16x16x32_bf16 v[124:127], v[166:169], v[204:207], v[124:127]
	v_mfma_f32_16x16x32_bf16 v[120:123], v[176:179], v[204:207], v[120:123]
	v_mfma_f32_16x16x32_bf16 v[108:111], v[166:169], v[212:215], v[108:111]
	v_mfma_f32_16x16x32_bf16 v[104:107], v[176:179], v[212:215], v[104:107]
	v_mfma_f32_16x16x32_bf16 v[92:95], v[166:169], v[220:223], v[92:95]
	v_mfma_f32_16x16x32_bf16 v[88:91], v[176:179], v[220:223], v[88:91]
	v_mfma_f32_16x16x32_bf16 v[76:79], v[166:169], v[228:231], v[76:79]
	v_mfma_f32_16x16x32_bf16 v[72:75], v[176:179], v[228:231], v[72:75]
	v_mfma_f32_16x16x32_bf16 v[116:119], v[180:183], v[200:203], v[116:119]
	v_mfma_f32_16x16x32_bf16 v[112:115], v[188:191], v[200:203], v[112:115]
	v_mfma_f32_16x16x32_bf16 v[100:103], v[180:183], v[208:211], v[100:103]
	v_mfma_f32_16x16x32_bf16 v[96:99], v[188:191], v[208:211], v[96:99]
	v_mfma_f32_16x16x32_bf16 v[84:87], v[180:183], v[216:219], v[84:87]
	v_mfma_f32_16x16x32_bf16 v[80:83], v[188:191], v[216:219], v[80:83]
	v_mfma_f32_16x16x32_bf16 v[68:71], v[180:183], v[224:227], v[68:71]
	v_mfma_f32_16x16x32_bf16 v[64:67], v[188:191], v[224:227], v[64:67]
	v_mfma_f32_16x16x32_bf16 v[116:119], v[184:187], v[204:207], v[116:119]
	v_mfma_f32_16x16x32_bf16 v[112:115], v[196:199], v[204:207], v[112:115]
	v_mfma_f32_16x16x32_bf16 v[100:103], v[184:187], v[212:215], v[100:103]
	v_mfma_f32_16x16x32_bf16 v[96:99], v[196:199], v[212:215], v[96:99]
	v_mfma_f32_16x16x32_bf16 v[84:87], v[184:187], v[220:223], v[84:87]
	v_mfma_f32_16x16x32_bf16 v[80:83], v[196:199], v[220:223], v[80:83]
	v_mfma_f32_16x16x32_bf16 v[68:71], v[184:187], v[228:231], v[68:71]
	v_mfma_f32_16x16x32_bf16 v[64:67], v[196:199], v[228:231], v[64:67]
	s_barrier
	s_add_i32 s6, s74, s36
	v_lshl_add_u64 v[152:153], s[58:59], 0, v[134:135]
	s_mov_b32 m0, s6
	ds_read_b128 v[200:203], v158 offset:16384
	ds_read_b128 v[204:207], v158 offset:17408
	ds_read_b128 v[208:211], v158 offset:18432
	ds_read_b128 v[212:215], v158 offset:19456
	ds_read_b128 v[216:219], v158 offset:20480
	ds_read_b128 v[220:223], v158 offset:21504
	ds_read_b128 v[224:227], v158 offset:22528
	ds_read_b128 v[228:231], v158 offset:23552
	global_load_lds_dwordx4 v[152:153], off
	s_add_i32 m0, s6, 0x2000
	s_add_u32 s54, s58, 0xb0000
	v_lshl_add_u64 v[162:163], s[58:59], 0, v[138:139]
	s_addc_u32 s55, s59, 0
	s_add_i32 s6, s75, s36
	global_load_lds_dwordx4 v[162:163], off
	v_lshl_add_u64 v[232:233], s[54:55], 0, v[134:135]
	s_mov_b32 m0, s6
	v_lshl_add_u64 v[234:235], s[60:61], 0, v[136:137]
	global_load_lds_dwordx4 v[232:233], off
	v_lshl_add_u64 v[232:233], s[54:55], 0, v[138:139]
	s_add_i32 m0, s6, 0x2000
	s_nop 0
	global_load_lds_dwordx4 v[232:233], off
	v_lshl_add_u64 v[232:233], s[60:61], 0, v[132:133]
	s_mov_b32 m0, s37
	s_nop 0
	global_load_lds_dwordx4 v[232:233], off
	s_mov_b32 m0, s30
	s_nop 0
	global_load_lds_dwordx4 v[234:235], off
	s_waitcnt vmcnt(8)
	s_waitcnt lgkmcnt(0)
	s_barrier
; #define PG8_STAGE(bufoff, gbase, voff) do { _Pragma("unroll") for (int _i = 0; _i < 2; ++_i) \
;         __builtin_amdgcn_global_load_lds((const unsigned*)((const char*)(gbase) + (voff)[_i]), (PG8_LAS unsigned*)(lds + (bufoff) + ldsw + _i * 8192), 16, 0, 0); } while (0)
; #define PG8_LDA(dst, b, h) do { _Pragma("unroll") for (int m = 0; m < 4; ++m) _Pragma("unroll") for (int k = 0; k < 2; ++k) dst[m][k] = *(const PG8_LAS bf16x8*)(lds + PG8_SA(b, h) + aoff + m * 2048 + k * 1024); } while (0)
; #define PG8_LDB(dst, b, h) do { _Pragma("unroll") for (int n = 0; n < 2; ++n) _Pragma("unroll") for (int k = 0; k < 2; ++k) dst[n][k] = *(const PG8_LAS bf16x8*)(lds + PG8_SB(b, h) + boff + n * 2048 + k * 1024); } while (0)
; #define PG8_MMA(ai, bj, At, Bt) do { __builtin_amdgcn_s_setprio(1); _Pragma("unroll") for (int m = 0; m < 4; ++m) _Pragma("unroll") for (int n = 0; n < 2; ++n) _Pragma("unroll") for (int k = 0; k < 2; ++k) \
;         acc[ai][bj][m][n] = __builtin_amdgcn_mfma_f32_16x16x32_bf16(Bt[n][k], At[m][k], acc[ai][bj][m][n], 0, 0, 0); __builtin_amdgcn_s_setprio(0); } while (0)
; #define PG8_WAIT_V(n) asm volatile("s_waitcnt vmcnt(" #n ")" ::: "memory")
; #define PG8_WAIT_L(n) asm volatile("s_waitcnt lgkmcnt(" #n ")" ::: "memory")
; #define PG8_BAR __builtin_amdgcn_s_barrier()
; #define PG8_SCHED __builtin_amdgcn_sched_barrier(0)
; template <class Epi, class Sched, bool ALIGN_EPI = false, bool SP2 = false>
; __device__ __forceinline__ void gemm_phase(PG8_LAS unsigned char* lds, const Gemm g, const Sched& S, const Epi& E) {
;     ...
;             PG8_WAIT_V(8); PG8_WAIT_L(0); PG8_BAR; PG8_MMA(1, 0, At, B0); PG8_MMA(1, 1, At, B1); PG8_BAR; PG8_SCHED;
;             PG8_LDB(B0, 1, 0); PG8_LDB(B1, 1, 1); PG8_SCHED; PG8_LDA(At, 1, 0); PG8_STAGE(PG8_SA(0, 1), a2 + hstep, voffA);
;             PG8_WAIT_V(8); PG8_WAIT_L(0); PG8_BAR; PG8_MMA(0, 0, At, B0); PG8_MMA(0, 1, At, B1); PG8_BAR; PG8_SCHED;
	s_waitcnt lgkmcnt(0)
	v_mfma_f32_16x16x32_bf16 v[60:63], v[148:151], v[200:203], v[60:63]
	v_mfma_f32_16x16x32_bf16 v[56:59], v[172:175], v[200:203], v[56:59]
	v_mfma_f32_16x16x32_bf16 v[44:47], v[148:151], v[208:211], v[44:47]
	v_mfma_f32_16x16x32_bf16 v[40:43], v[172:175], v[208:211], v[40:43]
	v_mfma_f32_16x16x32_bf16 v[28:31], v[148:151], v[216:219], v[28:31]
	v_mfma_f32_16x16x32_bf16 v[24:27], v[172:175], v[216:219], v[24:27]
	v_mfma_f32_16x16x32_bf16 v[12:15], v[148:151], v[224:227], v[12:15]
	v_mfma_f32_16x16x32_bf16 v[8:11], v[172:175], v[224:227], v[8:11]
	v_mfma_f32_16x16x32_bf16 v[60:63], v[166:169], v[204:207], v[60:63]
	v_mfma_f32_16x16x32_bf16 v[56:59], v[176:179], v[204:207], v[56:59]
	v_mfma_f32_16x16x32_bf16 v[44:47], v[166:169], v[212:215], v[44:47]
	v_mfma_f32_16x16x32_bf16 v[40:43], v[176:179], v[212:215], v[40:43]
	v_mfma_f32_16x16x32_bf16 v[28:31], v[166:169], v[220:223], v[28:31]
	v_mfma_f32_16x16x32_bf16 v[24:27], v[176:179], v[220:223], v[24:27]
	v_mfma_f32_16x16x32_bf16 v[12:15], v[166:169], v[228:231], v[12:15]
	v_mfma_f32_16x16x32_bf16 v[8:11], v[176:179], v[228:231], v[8:11]
	v_mfma_f32_16x16x32_bf16 v[52:55], v[180:183], v[200:203], v[52:55]
	v_mfma_f32_16x16x32_bf16 v[48:51], v[188:191], v[200:203], v[48:51]
	v_mfma_f32_16x16x32_bf16 v[36:39], v[180:183], v[208:211], v[36:39]
	v_mfma_f32_16x16x32_bf16 v[32:35], v[188:191], v[208:211], v[32:35]
	v_mfma_f32_16x16x32_bf16 v[20:23], v[180:183], v[216:219], v[20:23]
	v_mfma_f32_16x16x32_bf16 v[16:19], v[188:191], v[216:219], v[16:19]
	v_mfma_f32_16x16x32_bf16 v[4:7], v[180:183], v[224:227], v[4:7]
	v_mfma_f32_16x16x32_bf16 v[0:3], v[188:191], v[224:227], v[0:3]
	v_mfma_f32_16x16x32_bf16 v[52:55], v[184:187], v[204:207], v[52:55]
	v_mfma_f32_16x16x32_bf16 v[48:51], v[196:199], v[204:207], v[48:51]
	v_mfma_f32_16x16x32_bf16 v[36:39], v[184:187], v[212:215], v[36:39]
	v_mfma_f32_16x16x32_bf16 v[32:35], v[196:199], v[212:215], v[32:35]
	v_mfma_f32_16x16x32_bf16 v[20:23], v[184:187], v[220:223], v[20:23]
	v_mfma_f32_16x16x32_bf16 v[16:19], v[196:199], v[220:223], v[16:19]
	v_mfma_f32_16x16x32_bf16 v[4:7], v[184:187], v[228:231], v[4:7]
	v_mfma_f32_16x16x32_bf16 v[0:3], v[196:199], v[228:231], v[0:3]
	s_barrier
	s_add_i32 s6, 0, 0x18000
	v_add_u32_e32 v161, s6, v154
	s_add_i32 s7, 0, 0x1c000
	ds_read_b128 v[148:151], v161
	ds_read_b128 v[166:169], v161 offset:1024
	ds_read_b128 v[172:175], v161 offset:2048
	ds_read_b128 v[176:179], v161 offset:3072
	v_add_u32_e32 v161, s7, v154
	ds_read_b128 v[180:183], v161
	ds_read_b128 v[184:187], v161 offset:1024
	ds_read_b128 v[188:191], v161 offset:2048
	ds_read_b128 v[196:199], v161 offset:3072
	s_add_u32 s54, s60, 0xb0000
	s_addc_u32 s55, s61, 0
	s_mov_b32 m0, s31
	v_lshl_add_u64 v[236:237], s[54:55], 0, v[132:133]
	ds_read_b128 v[200:203], v158 offset:32768
	ds_read_b128 v[204:207], v158 offset:33792
	ds_read_b128 v[208:211], v158 offset:34816
	ds_read_b128 v[212:215], v158 offset:35840
	ds_read_b128 v[216:219], v158 offset:36864
	ds_read_b128 v[220:223], v158 offset:37888
	ds_read_b128 v[224:227], v158 offset:38912
	ds_read_b128 v[228:231], v158 offset:39936
	global_load_lds_dwordx4 v[236:237], off
	v_lshl_add_u64 v[236:237], s[54:55], 0, v[136:137]
	s_mov_b32 m0, s76
	s_nop 0
	global_load_lds_dwordx4 v[236:237], off
	s_waitcnt vmcnt(8)
	s_waitcnt lgkmcnt(0)
	s_barrier
	s_waitcnt lgkmcnt(0)
	v_mfma_f32_16x16x32_bf16 v[124:127], v[148:151], v[200:203], v[124:127]
	v_mfma_f32_16x16x32_bf16 v[120:123], v[172:175], v[200:203], v[120:123]
	v_mfma_f32_16x16x32_bf16 v[108:111], v[148:151], v[208:211], v[108:111]
	v_mfma_f32_16x16x32_bf16 v[104:107], v[172:175], v[208:211], v[104:107]
	v_mfma_f32_16x16x32_bf16 v[92:95], v[148:151], v[216:219], v[92:95]
	v_mfma_f32_16x16x32_bf16 v[88:91], v[172:175], v[216:219], v[88:91]
	v_mfma_f32_16x16x32_bf16 v[76:79], v[148:151], v[224:227], v[76:79]
	v_mfma_f32_16x16x32_bf16 v[72:75], v[172:175], v[224:227], v[72:75]
	v_mfma_f32_16x16x32_bf16 v[124:127], v[166:169], v[204:207], v[124:127]
	v_mfma_f32_16x16x32_bf16 v[120:123], v[176:179], v[204:207], v[120:123]
	v_mfma_f32_16x16x32_bf16 v[108:111], v[166:169], v[212:215], v[108:111]
	v_mfma_f32_16x16x32_bf16 v[104:107], v[176:179], v[212:215], v[104:107]
	v_mfma_f32_16x16x32_bf16 v[92:95], v[166:169], v[220:223], v[92:95]
	v_mfma_f32_16x16x32_bf16 v[88:91], v[176:179], v[220:223], v[88:91]
	v_mfma_f32_16x16x32_bf16 v[76:79], v[166:169], v[228:231], v[76:79]
	v_mfma_f32_16x16x32_bf16 v[72:75], v[176:179], v[228:231], v[72:75]
	v_mfma_f32_16x16x32_bf16 v[116:119], v[180:183], v[200:203], v[116:119]
	v_mfma_f32_16x16x32_bf16 v[112:115], v[188:191], v[200:203], v[112:115]
	v_mfma_f32_16x16x32_bf16 v[100:103], v[180:183], v[208:211], v[100:103]
	v_mfma_f32_16x16x32_bf16 v[96:99], v[188:191], v[208:211], v[96:99]
	v_mfma_f32_16x16x32_bf16 v[84:87], v[180:183], v[216:219], v[84:87]
	v_mfma_f32_16x16x32_bf16 v[80:83], v[188:191], v[216:219], v[80:83]
	v_mfma_f32_16x16x32_bf16 v[68:71], v[180:183], v[224:227], v[68:71]
	v_mfma_f32_16x16x32_bf16 v[64:67], v[188:191], v[224:227], v[64:67]
	v_mfma_f32_16x16x32_bf16 v[116:119], v[184:187], v[204:207], v[116:119]
	v_mfma_f32_16x16x32_bf16 v[112:115], v[196:199], v[204:207], v[112:115]
	v_mfma_f32_16x16x32_bf16 v[100:103], v[184:187], v[212:215], v[100:103]
	v_mfma_f32_16x16x32_bf16 v[96:99], v[196:199], v[212:215], v[96:99]
	v_mfma_f32_16x16x32_bf16 v[84:87], v[184:187], v[220:223], v[84:87]
	v_mfma_f32_16x16x32_bf16 v[80:83], v[196:199], v[220:223], v[80:83]
	v_mfma_f32_16x16x32_bf16 v[68:71], v[184:187], v[228:231], v[68:71]
	v_mfma_f32_16x16x32_bf16 v[64:67], v[196:199], v[228:231], v[64:67]
	s_barrier
; #define PG8_STAGE(bufoff, gbase, voff) do { _Pragma("unroll") for (int _i = 0; _i < 2; ++_i) \
;         __builtin_amdgcn_global_load_lds((const unsigned*)((const char*)(gbase) + (voff)[_i]), (PG8_LAS unsigned*)(lds + (bufoff) + ldsw + _i * 8192), 16, 0, 0); } while (0)
; #define PG8_LDA(dst, b, h) do { _Pragma("unroll") for (int m = 0; m < 4; ++m) _Pragma("unroll") for (int k = 0; k < 2; ++k) dst[m][k] = *(const PG8_LAS bf16x8*)(lds + PG8_SA(b, h) + aoff + m * 2048 + k * 1024); } while (0)
; #define PG8_MMA(ai, bj, At, Bt) do { __builtin_amdgcn_s_setprio(1); _Pragma("unroll") for (int m = 0; m < 4; ++m) _Pragma("unroll") for (int n = 0; n < 2; ++n) _Pragma("unroll") for (int k = 0; k < 2; ++k) \
;         acc[ai][bj][m][n] = __builtin_amdgcn_mfma_f32_16x16x32_bf16(Bt[n][k], At[m][k], acc[ai][bj][m][n], 0, 0, 0); __builtin_amdgcn_s_setprio(0); } while (0)
; #define PG8_WAIT_V(n) asm volatile("s_waitcnt vmcnt(" #n ")" ::: "memory")
; #define PG8_WAIT_L(n) asm volatile("s_waitcnt lgkmcnt(" #n ")" ::: "memory")
; #define PG8_BAR __builtin_amdgcn_s_barrier()
; #define PG8_SCHED __builtin_amdgcn_sched_barrier(0)
; template <class Epi, class Sched, bool ALIGN_EPI = false, bool SP2 = false>
; __device__ __forceinline__ void gemm_phase(PG8_LAS unsigned char* lds, const Gemm g, const Sched& S, const Epi& E) {
;     ...
;             PG8_LDA(At, 1, 1); PG8_STAGE(PG8_SB(1, 0), b3, voffB); PG8_STAGE(PG8_SB(1, 1), b3 + hstep, voffB); PG8_STAGE(PG8_SA(1, 0), a3, voffA);
;             PG8_WAIT_V(8); PG8_WAIT_L(0); PG8_BAR; PG8_MMA(1, 0, At, B0); PG8_MMA(1, 1, At, B1); PG8_BAR; PG8_SCHED;
	s_add_i32 s6, s6, s36
	v_lshl_add_u64 v[152:153], v[152:153], 0, s[38:39]
	s_mov_b32 m0, s6
	ds_read_b128 v[200:203], v158 offset:49152
	ds_read_b128 v[204:207], v158 offset:50176
	ds_read_b128 v[208:211], v158 offset:51200
	ds_read_b128 v[212:215], v158 offset:52224
	ds_read_b128 v[216:219], v158 offset:53248
	ds_read_b128 v[220:223], v158 offset:54272
	ds_read_b128 v[224:227], v158 offset:55296
	ds_read_b128 v[228:231], v158 offset:56320
	global_load_lds_dwordx4 v[152:153], off
	s_add_i32 m0, s6, 0x2000
	s_add_u32 s54, s58, 0xb0080
	v_lshl_add_u64 v[152:153], v[162:163], 0, s[38:39]
	s_addc_u32 s55, s59, 0
	s_add_i32 s6, s7, s36
	global_load_lds_dwordx4 v[152:153], off
	v_lshl_add_u64 v[152:153], s[54:55], 0, v[134:135]
	s_mov_b32 m0, s6
	s_nop 0
	global_load_lds_dwordx4 v[152:153], off
	v_lshl_add_u64 v[152:153], s[54:55], 0, v[138:139]
	s_add_i32 m0, s6, 0x2000
	s_nop 0
	global_load_lds_dwordx4 v[152:153], off
	v_lshl_add_u64 v[152:153], v[232:233], 0, s[38:39]
	s_mov_b32 m0, s78
	s_nop 0
	global_load_lds_dwordx4 v[152:153], off
	v_lshl_add_u64 v[152:153], v[234:235], 0, s[38:39]
	s_mov_b32 m0, s79
	s_nop 0
	global_load_lds_dwordx4 v[152:153], off
	s_waitcnt vmcnt(8)
	s_waitcnt lgkmcnt(0)
	s_barrier
	s_waitcnt lgkmcnt(0)
	v_mfma_f32_16x16x32_bf16 v[60:63], v[148:151], v[200:203], v[60:63]
	v_mfma_f32_16x16x32_bf16 v[56:59], v[172:175], v[200:203], v[56:59]
	v_mfma_f32_16x16x32_bf16 v[44:47], v[148:151], v[208:211], v[44:47]
	v_mfma_f32_16x16x32_bf16 v[40:43], v[172:175], v[208:211], v[40:43]
	v_mfma_f32_16x16x32_bf16 v[28:31], v[148:151], v[216:219], v[28:31]
	v_mfma_f32_16x16x32_bf16 v[24:27], v[172:175], v[216:219], v[24:27]
	v_mfma_f32_16x16x32_bf16 v[12:15], v[148:151], v[224:227], v[12:15]
	v_mfma_f32_16x16x32_bf16 v[8:11], v[172:175], v[224:227], v[8:11]
	v_mfma_f32_16x16x32_bf16 v[60:63], v[166:169], v[204:207], v[60:63]
	v_mfma_f32_16x16x32_bf16 v[56:59], v[176:179], v[204:207], v[56:59]
	v_mfma_f32_16x16x32_bf16 v[44:47], v[166:169], v[212:215], v[44:47]
	v_mfma_f32_16x16x32_bf16 v[40:43], v[176:179], v[212:215], v[40:43]
	v_mfma_f32_16x16x32_bf16 v[28:31], v[166:169], v[220:223], v[28:31]
	v_mfma_f32_16x16x32_bf16 v[24:27], v[176:179], v[220:223], v[24:27]
	v_mfma_f32_16x16x32_bf16 v[12:15], v[166:169], v[228:231], v[12:15]
	v_mfma_f32_16x16x32_bf16 v[8:11], v[176:179], v[228:231], v[8:11]
	v_mfma_f32_16x16x32_bf16 v[52:55], v[180:183], v[200:203], v[52:55]
	v_mfma_f32_16x16x32_bf16 v[48:51], v[188:191], v[200:203], v[48:51]
	v_mfma_f32_16x16x32_bf16 v[36:39], v[180:183], v[208:211], v[36:39]
	v_mfma_f32_16x16x32_bf16 v[32:35], v[188:191], v[208:211], v[32:35]
	v_mfma_f32_16x16x32_bf16 v[20:23], v[180:183], v[216:219], v[20:23]
	v_mfma_f32_16x16x32_bf16 v[16:19], v[188:191], v[216:219], v[16:19]
	v_mfma_f32_16x16x32_bf16 v[4:7], v[180:183], v[224:227], v[4:7]
	v_mfma_f32_16x16x32_bf16 v[0:3], v[188:191], v[224:227], v[0:3]
	v_mfma_f32_16x16x32_bf16 v[52:55], v[184:187], v[204:207], v[52:55]
	v_mfma_f32_16x16x32_bf16 v[48:51], v[196:199], v[204:207], v[48:51]
	v_mfma_f32_16x16x32_bf16 v[36:39], v[184:187], v[212:215], v[36:39]
	v_mfma_f32_16x16x32_bf16 v[32:35], v[196:199], v[212:215], v[32:35]
	v_mfma_f32_16x16x32_bf16 v[20:23], v[184:187], v[220:223], v[20:23]
	v_mfma_f32_16x16x32_bf16 v[16:19], v[196:199], v[220:223], v[16:19]
	v_mfma_f32_16x16x32_bf16 v[4:7], v[184:187], v[228:231], v[4:7]
	v_mfma_f32_16x16x32_bf16 v[0:3], v[196:199], v[228:231], v[0:3]
	s_barrier
	s_add_i32 s69, s69, 2
	s_add_u32 s4, s4, 0x100
	s_addc_u32 s33, s33, 0
	s_cmp_gt_u32 s69, 41
	s_mov_b64 s[54:55], s[56:57]
	s_cbranch_scc0 .LBB0_323
	s_and_b64 vcc, exec, s[40:41]
	s_cbranch_vccz .LBB0_326
	s_barrier

; #define PG8_STAGE(bufoff, gbase, voff) do { _Pragma("unroll") for (int _i = 0; _i < 2; ++_i) \
;         __builtin_amdgcn_global_load_lds((const unsigned*)((const char*)(gbase) + (voff)[_i]), (PG8_LAS unsigned*)(lds + (bufoff) + ldsw + _i * 8192), 16, 0, 0); } while (0)
; #define PG8_LDA(dst, b, h) do { _Pragma("unroll") for (int m = 0; m < 4; ++m) _Pragma("unroll") for (int k = 0; k < 2; ++k) dst[m][k] = *(const PG8_LAS bf16x8*)(lds + PG8_SA(b, h) + aoff + m * 2048 + k * 1024); } while (0)
; #define PG8_LDB(dst, b, h) do { _Pragma("unroll") for (int n = 0; n < 2; ++n) _Pragma("unroll") for (int k = 0; k < 2; ++k) dst[n][k] = *(const PG8_LAS bf16x8*)(lds + PG8_SB(b, h) + boff + n * 2048 + k * 1024); } while (0)
; #define PG8_MMA(ai, bj, At, Bt) do { __builtin_amdgcn_s_setprio(1); _Pragma("unroll") for (int m = 0; m < 4; ++m) _Pragma("unroll") for (int n = 0; n < 2; ++n) _Pragma("unroll") for (int k = 0; k < 2; ++k) \
;         acc[ai][bj][m][n] = __builtin_amdgcn_mfma_f32_16x16x32_bf16(Bt[n][k], At[m][k], acc[ai][bj][m][n], 0, 0, 0); __builtin_amdgcn_s_setprio(0); } while (0)
; #define PG8_WAIT_V(n) asm volatile("s_waitcnt vmcnt(" #n ")" ::: "memory")
; #define PG8_WAIT_L(n) asm volatile("s_waitcnt lgkmcnt(" #n ")" ::: "memory")
; #define PG8_BAR __builtin_amdgcn_s_barrier()
; #define PG8_SCHED __builtin_amdgcn_sched_barrier(0)
; template <class Epi, class Sched, bool ALIGN_EPI = false, bool SP2 = false>
; __device__ __forceinline__ void gemm_phase(PG8_LAS unsigned char* lds, const Gemm g, const Sched& S, const Epi& E) {
;     ...
;             const bool last = (t == nt - 2);
;             const char* a1 = cA + (size_t)(t + 1) * kstep;
;             const char* a2 = last ? nA : cA + (size_t)(t + 2) * kstep; const char* b2 = last ? nB : cB + (size_t)(t + 2) * kstep;
;             const char* a3 = a2 + kstep; const char* b3 = b2 + kstep;
;             if (last && has_next) S.a_ready(nxt);
;             if constexpr (SP2) {
;             PG8_LDB(B0, 0, 0); PG8_LDB(B1, 0, 1); PG8_SCHED; PG8_LDA(At, 0, 0); PG8_STAGE(PG8_SA(1, 1), a1 + hstep, voffA);
;             PG8_WAIT_V(8); PG8_WAIT_L(0); PG8_BAR; PG8_MMA(0, 0, At, B0); PG8_MMA(0, 1, At, B1); PG8_BAR; PG8_SCHED;
;             PG8_LDA(At, 0, 1); PG8_STAGE(PG8_SB(0, 0), b2, voffB); PG8_STAGE(PG8_SB(0, 1), b2 + hstep, voffB); PG8_STAGE(PG8_SA(0, 0), a2, voffA);
.LBB0_463:
	ds_read_b128 v[152:155], v172
	ds_read_b128 v[156:159], v172 offset:1024
	ds_read_b128 v[166:169], v172 offset:2048
	ds_read_b128 v[176:179], v172 offset:3072
	ds_read_b128 v[180:183], v173
	ds_read_b128 v[184:187], v173 offset:1024
	ds_read_b128 v[188:191], v173 offset:2048
	ds_read_b128 v[196:199], v173 offset:3072
	s_add_u32 s6, s60, 0xfffc0080
	s_addc_u32 s7, s61, -1
	s_cmp_eq_u32 s72, 12
	s_cselect_b32 s81, s49, s7
	s_cselect_b32 s80, s55, s6
	s_cselect_b32 s79, s53, s33
	s_cselect_b32 s78, vcc_lo, vcc_hi
	v_lshl_add_u64 v[232:233], s[60:61], 0, v[144:145]
	s_add_i32 m0, s31, 0xc000
	ds_read_b128 v[200:203], v174
	ds_read_b128 v[204:207], v174 offset:1024
	ds_read_b128 v[208:211], v174 offset:2048
	ds_read_b128 v[212:215], v174 offset:3072
	ds_read_b128 v[216:219], v174 offset:4096
	ds_read_b128 v[220:223], v174 offset:5120
	ds_read_b128 v[224:227], v174 offset:6144
	ds_read_b128 v[228:231], v174 offset:7168
	global_load_lds_dwordx4 v[232:233], off
	v_lshl_add_u64 v[232:233], s[60:61], 0, v[146:147]
	s_add_i32 m0, s31, 0xe000
	s_nop 0
	global_load_lds_dwordx4 v[232:233], off
	s_waitcnt vmcnt(8)
	s_waitcnt lgkmcnt(0)
	s_barrier
	s_waitcnt lgkmcnt(0)
	v_mfma_f32_16x16x32_bf16 v[124:127], v[152:155], v[200:203], v[124:127]
	v_mfma_f32_16x16x32_bf16 v[120:123], v[166:169], v[200:203], v[120:123]
	v_mfma_f32_16x16x32_bf16 v[108:111], v[152:155], v[208:211], v[108:111]
	v_mfma_f32_16x16x32_bf16 v[104:107], v[166:169], v[208:211], v[104:107]
	v_mfma_f32_16x16x32_bf16 v[92:95], v[152:155], v[216:219], v[92:95]
	v_mfma_f32_16x16x32_bf16 v[88:91], v[166:169], v[216:219], v[88:91]
	v_mfma_f32_16x16x32_bf16 v[76:79], v[152:155], v[224:227], v[76:79]
	v_mfma_f32_16x16x32_bf16 v[72:75], v[166:169], v[224:227], v[72:75]
	v_mfma_f32_16x16x32_bf16 v[124:127], v[156:159], v[204:207], v[124:127]
	v_mfma_f32_16x16x32_bf16 v[120:123], v[176:179], v[204:207], v[120:123]
	v_mfma_f32_16x16x32_bf16 v[108:111], v[156:159], v[212:215], v[108:111]
	v_mfma_f32_16x16x32_bf16 v[104:107], v[176:179], v[212:215], v[104:107]
	v_mfma_f32_16x16x32_bf16 v[92:95], v[156:159], v[220:223], v[92:95]
	v_mfma_f32_16x16x32_bf16 v[88:91], v[176:179], v[220:223], v[88:91]
	v_mfma_f32_16x16x32_bf16 v[76:79], v[156:159], v[228:231], v[76:79]
	v_mfma_f32_16x16x32_bf16 v[72:75], v[176:179], v[228:231], v[72:75]
	v_mfma_f32_16x16x32_bf16 v[116:119], v[180:183], v[200:203], v[116:119]
	v_mfma_f32_16x16x32_bf16 v[112:115], v[188:191], v[200:203], v[112:115]
	v_mfma_f32_16x16x32_bf16 v[100:103], v[180:183], v[208:211], v[100:103]
	v_mfma_f32_16x16x32_bf16 v[96:99], v[188:191], v[208:211], v[96:99]
	v_mfma_f32_16x16x32_bf16 v[84:87], v[180:183], v[216:219], v[84:87]
	v_mfma_f32_16x16x32_bf16 v[80:83], v[188:191], v[216:219], v[80:83]
	v_mfma_f32_16x16x32_bf16 v[68:71], v[180:183], v[224:227], v[68:71]
	v_mfma_f32_16x16x32_bf16 v[64:67], v[188:191], v[224:227], v[64:67]
	v_mfma_f32_16x16x32_bf16 v[116:119], v[184:187], v[204:207], v[116:119]
	v_mfma_f32_16x16x32_bf16 v[112:115], v[196:199], v[204:207], v[112:115]
	v_mfma_f32_16x16x32_bf16 v[100:103], v[184:187], v[212:215], v[100:103]
	v_mfma_f32_16x16x32_bf16 v[96:99], v[196:199], v[212:215], v[96:99]
	v_mfma_f32_16x16x32_bf16 v[84:87], v[184:187], v[220:223], v[84:87]
	v_mfma_f32_16x16x32_bf16 v[80:83], v[196:199], v[220:223], v[80:83]
	v_mfma_f32_16x16x32_bf16 v[68:71], v[184:187], v[228:231], v[68:71]
	v_mfma_f32_16x16x32_bf16 v[64:67], v[196:199], v[228:231], v[64:67]
	s_barrier
	s_add_i32 s6, s69, s30
	v_lshl_add_u64 v[232:233], s[78:79], 0, v[134:135]
	s_mov_b32 m0, s6
	ds_read_b128 v[200:203], v174 offset:16384
	ds_read_b128 v[204:207], v174 offset:17408
	ds_read_b128 v[208:211], v174 offset:18432
	ds_read_b128 v[212:215], v174 offset:19456
	ds_read_b128 v[216:219], v174 offset:20480
	ds_read_b128 v[220:223], v174 offset:21504
	ds_read_b128 v[224:227], v174 offset:22528
	ds_read_b128 v[228:231], v174 offset:23552
	global_load_lds_dwordx4 v[232:233], off
	s_add_i32 m0, s6, 0x2000
	s_add_u32 s6, s78, 0x40000
	v_lshl_add_u64 v[234:235], s[78:79], 0, v[138:139]
	s_addc_u32 s7, s79, 0
	s_add_i32 s73, s74, s30
	global_load_lds_dwordx4 v[234:235], off
	v_lshl_add_u64 v[236:237], s[6:7], 0, v[134:135]
	s_mov_b32 m0, s73
	v_lshl_add_u64 v[238:239], s[80:81], 0, v[136:137]
	global_load_lds_dwordx4 v[236:237], off
	v_lshl_add_u64 v[236:237], s[6:7], 0, v[138:139]
	s_add_i32 m0, s73, 0x2000
	s_nop 0
	global_load_lds_dwordx4 v[236:237], off
	v_lshl_add_u64 v[236:237], s[80:81], 0, v[132:133]
	s_mov_b32 m0, s31
	s_nop 0
	global_load_lds_dwordx4 v[236:237], off
	s_mov_b32 m0, s36
	s_nop 0
	global_load_lds_dwordx4 v[238:239], off
	s_waitcnt vmcnt(8)
	s_waitcnt lgkmcnt(0)
	s_barrier
; #define PG8_STAGE(bufoff, gbase, voff) do { _Pragma("unroll") for (int _i = 0; _i < 2; ++_i) \
;         __builtin_amdgcn_global_load_lds((const unsigned*)((const char*)(gbase) + (voff)[_i]), (PG8_LAS unsigned*)(lds + (bufoff) + ldsw + _i * 8192), 16, 0, 0); } while (0)
; #define PG8_LDA(dst, b, h) do { _Pragma("unroll") for (int m = 0; m < 4; ++m) _Pragma("unroll") for (int k = 0; k < 2; ++k) dst[m][k] = *(const PG8_LAS bf16x8*)(lds + PG8_SA(b, h) + aoff + m * 2048 + k * 1024); } while (0)
; #define PG8_LDB(dst, b, h) do { _Pragma("unroll") for (int n = 0; n < 2; ++n) _Pragma("unroll") for (int k = 0; k < 2; ++k) dst[n][k] = *(const PG8_LAS bf16x8*)(lds + PG8_SB(b, h) + boff + n * 2048 + k * 1024); } while (0)
; #define PG8_MMA(ai, bj, At, Bt) do { __builtin_amdgcn_s_setprio(1); _Pragma("unroll") for (int m = 0; m < 4; ++m) _Pragma("unroll") for (int n = 0; n < 2; ++n) _Pragma("unroll") for (int k = 0; k < 2; ++k) \
;         acc[ai][bj][m][n] = __builtin_amdgcn_mfma_f32_16x16x32_bf16(Bt[n][k], At[m][k], acc[ai][bj][m][n], 0, 0, 0); __builtin_amdgcn_s_setprio(0); } while (0)
; #define PG8_WAIT_V(n) asm volatile("s_waitcnt vmcnt(" #n ")" ::: "memory")
; #define PG8_WAIT_L(n) asm volatile("s_waitcnt lgkmcnt(" #n ")" ::: "memory")
; #define PG8_BAR __builtin_amdgcn_s_barrier()
; #define PG8_SCHED __builtin_amdgcn_sched_barrier(0)
; template <class Epi, class Sched, bool ALIGN_EPI = false, bool SP2 = false>
; __device__ __forceinline__ void gemm_phase(PG8_LAS unsigned char* lds, const Gemm g, const Sched& S, const Epi& E) {
;     ...
;             PG8_WAIT_V(8); PG8_WAIT_L(0); PG8_BAR; PG8_MMA(1, 0, At, B0); PG8_MMA(1, 1, At, B1); PG8_BAR; PG8_SCHED;
;             PG8_LDB(B0, 1, 0); PG8_LDB(B1, 1, 1); PG8_SCHED; PG8_LDA(At, 1, 0); PG8_STAGE(PG8_SA(0, 1), a2 + hstep, voffA);
;             PG8_WAIT_V(8); PG8_WAIT_L(0); PG8_BAR; PG8_MMA(0, 0, At, B0); PG8_MMA(0, 1, At, B1); PG8_BAR; PG8_SCHED;
	s_waitcnt lgkmcnt(0)
	v_mfma_f32_16x16x32_bf16 v[60:63], v[152:155], v[200:203], v[60:63]
	v_mfma_f32_16x16x32_bf16 v[56:59], v[166:169], v[200:203], v[56:59]
	v_mfma_f32_16x16x32_bf16 v[44:47], v[152:155], v[208:211], v[44:47]
	v_mfma_f32_16x16x32_bf16 v[40:43], v[166:169], v[208:211], v[40:43]
	v_mfma_f32_16x16x32_bf16 v[28:31], v[152:155], v[216:219], v[28:31]
	v_mfma_f32_16x16x32_bf16 v[24:27], v[166:169], v[216:219], v[24:27]
	v_mfma_f32_16x16x32_bf16 v[12:15], v[152:155], v[224:227], v[12:15]
	v_mfma_f32_16x16x32_bf16 v[8:11], v[166:169], v[224:227], v[8:11]
	v_mfma_f32_16x16x32_bf16 v[60:63], v[156:159], v[204:207], v[60:63]
	v_mfma_f32_16x16x32_bf16 v[56:59], v[176:179], v[204:207], v[56:59]
	v_mfma_f32_16x16x32_bf16 v[44:47], v[156:159], v[212:215], v[44:47]
	v_mfma_f32_16x16x32_bf16 v[40:43], v[176:179], v[212:215], v[40:43]
	v_mfma_f32_16x16x32_bf16 v[28:31], v[156:159], v[220:223], v[28:31]
	v_mfma_f32_16x16x32_bf16 v[24:27], v[176:179], v[220:223], v[24:27]
	v_mfma_f32_16x16x32_bf16 v[12:15], v[156:159], v[228:231], v[12:15]
	v_mfma_f32_16x16x32_bf16 v[8:11], v[176:179], v[228:231], v[8:11]
	v_mfma_f32_16x16x32_bf16 v[52:55], v[180:183], v[200:203], v[52:55]
	v_mfma_f32_16x16x32_bf16 v[48:51], v[188:191], v[200:203], v[48:51]
	v_mfma_f32_16x16x32_bf16 v[36:39], v[180:183], v[208:211], v[36:39]
	v_mfma_f32_16x16x32_bf16 v[32:35], v[188:191], v[208:211], v[32:35]
	v_mfma_f32_16x16x32_bf16 v[20:23], v[180:183], v[216:219], v[20:23]
	v_mfma_f32_16x16x32_bf16 v[16:19], v[188:191], v[216:219], v[16:19]
	v_mfma_f32_16x16x32_bf16 v[4:7], v[180:183], v[224:227], v[4:7]
	v_mfma_f32_16x16x32_bf16 v[0:3], v[188:191], v[224:227], v[0:3]
	v_mfma_f32_16x16x32_bf16 v[52:55], v[184:187], v[204:207], v[52:55]
	v_mfma_f32_16x16x32_bf16 v[48:51], v[196:199], v[204:207], v[48:51]
	v_mfma_f32_16x16x32_bf16 v[36:39], v[184:187], v[212:215], v[36:39]
	v_mfma_f32_16x16x32_bf16 v[32:35], v[196:199], v[212:215], v[32:35]
	v_mfma_f32_16x16x32_bf16 v[20:23], v[184:187], v[220:223], v[20:23]
	v_mfma_f32_16x16x32_bf16 v[16:19], v[196:199], v[220:223], v[16:19]
	v_mfma_f32_16x16x32_bf16 v[4:7], v[184:187], v[228:231], v[4:7]
	v_mfma_f32_16x16x32_bf16 v[0:3], v[196:199], v[228:231], v[0:3]
	s_barrier
	s_add_i32 s73, 0, 0x18000
	v_add_u32_e32 v175, s73, v143
	s_add_i32 s82, 0, 0x1c000
	ds_read_b128 v[152:155], v175
	ds_read_b128 v[156:159], v175 offset:1024
	ds_read_b128 v[166:169], v175 offset:2048
	ds_read_b128 v[176:179], v175 offset:3072
	v_add_u32_e32 v175, s82, v143
	ds_read_b128 v[180:183], v175
	ds_read_b128 v[184:187], v175 offset:1024
	ds_read_b128 v[188:191], v175 offset:2048
	ds_read_b128 v[196:199], v175 offset:3072
	s_add_u32 s6, s80, 0x40000
	s_addc_u32 s7, s81, 0
	s_mov_b32 m0, s37
	v_lshl_add_u64 v[240:241], s[6:7], 0, v[132:133]
	ds_read_b128 v[200:203], v174 offset:32768
	ds_read_b128 v[204:207], v174 offset:33792
	ds_read_b128 v[208:211], v174 offset:34816
	ds_read_b128 v[212:215], v174 offset:35840
	ds_read_b128 v[216:219], v174 offset:36864
	ds_read_b128 v[220:223], v174 offset:37888
	ds_read_b128 v[224:227], v174 offset:38912
	ds_read_b128 v[228:231], v174 offset:39936
	global_load_lds_dwordx4 v[240:241], off
	v_lshl_add_u64 v[240:241], s[6:7], 0, v[136:137]
	s_mov_b32 m0, s42
	s_nop 0
	global_load_lds_dwordx4 v[240:241], off
	s_waitcnt vmcnt(8)
	s_waitcnt lgkmcnt(0)
	s_barrier
	s_waitcnt lgkmcnt(0)
	v_mfma_f32_16x16x32_bf16 v[124:127], v[152:155], v[200:203], v[124:127]
	v_mfma_f32_16x16x32_bf16 v[120:123], v[166:169], v[200:203], v[120:123]
	v_mfma_f32_16x16x32_bf16 v[108:111], v[152:155], v[208:211], v[108:111]
	v_mfma_f32_16x16x32_bf16 v[104:107], v[166:169], v[208:211], v[104:107]
	v_mfma_f32_16x16x32_bf16 v[92:95], v[152:155], v[216:219], v[92:95]
	v_mfma_f32_16x16x32_bf16 v[88:91], v[166:169], v[216:219], v[88:91]
	v_mfma_f32_16x16x32_bf16 v[76:79], v[152:155], v[224:227], v[76:79]
	v_mfma_f32_16x16x32_bf16 v[72:75], v[166:169], v[224:227], v[72:75]
	v_mfma_f32_16x16x32_bf16 v[124:127], v[156:159], v[204:207], v[124:127]
	v_mfma_f32_16x16x32_bf16 v[120:123], v[176:179], v[204:207], v[120:123]
	v_mfma_f32_16x16x32_bf16 v[108:111], v[156:159], v[212:215], v[108:111]
	v_mfma_f32_16x16x32_bf16 v[104:107], v[176:179], v[212:215], v[104:107]
	v_mfma_f32_16x16x32_bf16 v[92:95], v[156:159], v[220:223], v[92:95]
	v_mfma_f32_16x16x32_bf16 v[88:91], v[176:179], v[220:223], v[88:91]
	v_mfma_f32_16x16x32_bf16 v[76:79], v[156:159], v[228:231], v[76:79]
	v_mfma_f32_16x16x32_bf16 v[72:75], v[176:179], v[228:231], v[72:75]
	v_mfma_f32_16x16x32_bf16 v[116:119], v[180:183], v[200:203], v[116:119]
	v_mfma_f32_16x16x32_bf16 v[112:115], v[188:191], v[200:203], v[112:115]
	v_mfma_f32_16x16x32_bf16 v[100:103], v[180:183], v[208:211], v[100:103]
	v_mfma_f32_16x16x32_bf16 v[96:99], v[188:191], v[208:211], v[96:99]
	v_mfma_f32_16x16x32_bf16 v[84:87], v[180:183], v[216:219], v[84:87]
	v_mfma_f32_16x16x32_bf16 v[80:83], v[188:191], v[216:219], v[80:83]
	v_mfma_f32_16x16x32_bf16 v[68:71], v[180:183], v[224:227], v[68:71]
	v_mfma_f32_16x16x32_bf16 v[64:67], v[188:191], v[224:227], v[64:67]
	v_mfma_f32_16x16x32_bf16 v[116:119], v[184:187], v[204:207], v[116:119]
	v_mfma_f32_16x16x32_bf16 v[112:115], v[196:199], v[204:207], v[112:115]
	v_mfma_f32_16x16x32_bf16 v[100:103], v[184:187], v[212:215], v[100:103]
	v_mfma_f32_16x16x32_bf16 v[96:99], v[196:199], v[212:215], v[96:99]
	v_mfma_f32_16x16x32_bf16 v[84:87], v[184:187], v[220:223], v[84:87]
	v_mfma_f32_16x16x32_bf16 v[80:83], v[196:199], v[220:223], v[80:83]
	v_mfma_f32_16x16x32_bf16 v[68:71], v[184:187], v[228:231], v[68:71]
	v_mfma_f32_16x16x32_bf16 v[64:67], v[196:199], v[228:231], v[64:67]
	s_barrier
; #define PG8_STAGE(bufoff, gbase, voff) do { _Pragma("unroll") for (int _i = 0; _i < 2; ++_i) \
;         __builtin_amdgcn_global_load_lds((const unsigned*)((const char*)(gbase) + (voff)[_i]), (PG8_LAS unsigned*)(lds + (bufoff) + ldsw + _i * 8192), 16, 0, 0); } while (0)
; #define PG8_LDA(dst, b, h) do { _Pragma("unroll") for (int m = 0; m < 4; ++m) _Pragma("unroll") for (int k = 0; k < 2; ++k) dst[m][k] = *(const PG8_LAS bf16x8*)(lds + PG8_SA(b, h) + aoff + m * 2048 + k * 1024); } while (0)
; #define PG8_MMA(ai, bj, At, Bt) do { __builtin_amdgcn_s_setprio(1); _Pragma("unroll") for (int m = 0; m < 4; ++m) _Pragma("unroll") for (int n = 0; n < 2; ++n) _Pragma("unroll") for (int k = 0; k < 2; ++k) \
;         acc[ai][bj][m][n] = __builtin_amdgcn_mfma_f32_16x16x32_bf16(Bt[n][k], At[m][k], acc[ai][bj][m][n], 0, 0, 0); __builtin_amdgcn_s_setprio(0); } while (0)
; #define PG8_WAIT_V(n) asm volatile("s_waitcnt vmcnt(" #n ")" ::: "memory")
; #define PG8_WAIT_L(n) asm volatile("s_waitcnt lgkmcnt(" #n ")" ::: "memory")
; #define PG8_BAR __builtin_amdgcn_s_barrier()
; #define PG8_SCHED __builtin_amdgcn_sched_barrier(0)
; template <class Epi, class Sched, bool ALIGN_EPI = false, bool SP2 = false>
; __device__ __forceinline__ void gemm_phase(PG8_LAS unsigned char* lds, const Gemm g, const Sched& S, const Epi& E) {
;     ...
;             PG8_LDA(At, 1, 1); PG8_STAGE(PG8_SB(1, 0), b3, voffB); PG8_STAGE(PG8_SB(1, 1), b3 + hstep, voffB); PG8_STAGE(PG8_SA(1, 0), a3, voffA);
;             PG8_WAIT_V(8); PG8_WAIT_L(0); PG8_BAR; PG8_MMA(1, 0, At, B0); PG8_MMA(1, 1, At, B1); PG8_BAR; PG8_SCHED;
	s_add_i32 s6, s73, s30
	v_lshl_add_u64 v[232:233], v[232:233], 0, s[40:41]
	s_mov_b32 m0, s6
	ds_read_b128 v[200:203], v174 offset:49152
	ds_read_b128 v[204:207], v174 offset:50176
	ds_read_b128 v[208:211], v174 offset:51200
	ds_read_b128 v[212:215], v174 offset:52224
	ds_read_b128 v[216:219], v174 offset:53248
	ds_read_b128 v[220:223], v174 offset:54272
	ds_read_b128 v[224:227], v174 offset:55296
	ds_read_b128 v[228:231], v174 offset:56320
	global_load_lds_dwordx4 v[232:233], off
	s_add_i32 m0, s6, 0x2000
	s_add_u32 s6, s78, 0x40080
	v_lshl_add_u64 v[232:233], v[234:235], 0, s[40:41]
	s_addc_u32 s7, s79, 0
	s_add_i32 s73, s82, s30
	global_load_lds_dwordx4 v[232:233], off
	v_lshl_add_u64 v[232:233], s[6:7], 0, v[134:135]
	s_mov_b32 m0, s73
	s_nop 0
	global_load_lds_dwordx4 v[232:233], off
	v_lshl_add_u64 v[232:233], s[6:7], 0, v[138:139]
	s_add_i32 m0, s73, 0x2000
	s_nop 0
	global_load_lds_dwordx4 v[232:233], off
	v_lshl_add_u64 v[232:233], v[236:237], 0, s[40:41]
	s_mov_b32 m0, s67
	s_nop 0
	global_load_lds_dwordx4 v[232:233], off
	v_lshl_add_u64 v[232:233], v[238:239], 0, s[40:41]
	s_mov_b32 m0, s68
	s_nop 0
	global_load_lds_dwordx4 v[232:233], off
	s_waitcnt vmcnt(8)
	s_waitcnt lgkmcnt(0)
	s_barrier
	s_waitcnt lgkmcnt(0)
	v_mfma_f32_16x16x32_bf16 v[60:63], v[152:155], v[200:203], v[60:63]
	v_mfma_f32_16x16x32_bf16 v[56:59], v[166:169], v[200:203], v[56:59]
	v_mfma_f32_16x16x32_bf16 v[44:47], v[152:155], v[208:211], v[44:47]
	v_mfma_f32_16x16x32_bf16 v[40:43], v[166:169], v[208:211], v[40:43]
	v_mfma_f32_16x16x32_bf16 v[28:31], v[152:155], v[216:219], v[28:31]
	v_mfma_f32_16x16x32_bf16 v[24:27], v[166:169], v[216:219], v[24:27]
	v_mfma_f32_16x16x32_bf16 v[12:15], v[152:155], v[224:227], v[12:15]
	v_mfma_f32_16x16x32_bf16 v[8:11], v[166:169], v[224:227], v[8:11]
	v_mfma_f32_16x16x32_bf16 v[60:63], v[156:159], v[204:207], v[60:63]
	v_mfma_f32_16x16x32_bf16 v[56:59], v[176:179], v[204:207], v[56:59]
	v_mfma_f32_16x16x32_bf16 v[44:47], v[156:159], v[212:215], v[44:47]
	v_mfma_f32_16x16x32_bf16 v[40:43], v[176:179], v[212:215], v[40:43]
	v_mfma_f32_16x16x32_bf16 v[28:31], v[156:159], v[220:223], v[28:31]
	v_mfma_f32_16x16x32_bf16 v[24:27], v[176:179], v[220:223], v[24:27]
	v_mfma_f32_16x16x32_bf16 v[12:15], v[156:159], v[228:231], v[12:15]
	v_mfma_f32_16x16x32_bf16 v[8:11], v[176:179], v[228:231], v[8:11]
	v_mfma_f32_16x16x32_bf16 v[52:55], v[180:183], v[200:203], v[52:55]
	v_mfma_f32_16x16x32_bf16 v[48:51], v[188:191], v[200:203], v[48:51]
	v_mfma_f32_16x16x32_bf16 v[36:39], v[180:183], v[208:211], v[36:39]
	v_mfma_f32_16x16x32_bf16 v[32:35], v[188:191], v[208:211], v[32:35]
	v_mfma_f32_16x16x32_bf16 v[20:23], v[180:183], v[216:219], v[20:23]
	v_mfma_f32_16x16x32_bf16 v[16:19], v[188:191], v[216:219], v[16:19]
	v_mfma_f32_16x16x32_bf16 v[4:7], v[180:183], v[224:227], v[4:7]
	v_mfma_f32_16x16x32_bf16 v[0:3], v[188:191], v[224:227], v[0:3]
	v_mfma_f32_16x16x32_bf16 v[52:55], v[184:187], v[204:207], v[52:55]
	v_mfma_f32_16x16x32_bf16 v[48:51], v[196:199], v[204:207], v[48:51]
	v_mfma_f32_16x16x32_bf16 v[36:39], v[184:187], v[212:215], v[36:39]
	v_mfma_f32_16x16x32_bf16 v[32:35], v[196:199], v[212:215], v[32:35]
	v_mfma_f32_16x16x32_bf16 v[20:23], v[184:187], v[220:223], v[20:23]
	v_mfma_f32_16x16x32_bf16 v[16:19], v[196:199], v[220:223], v[16:19]
	v_mfma_f32_16x16x32_bf16 v[4:7], v[184:187], v[228:231], v[4:7]
	v_mfma_f32_16x16x32_bf16 v[0:3], v[196:199], v[228:231], v[0:3]
	s_barrier
	s_add_i32 s72, s72, 2
	s_add_u32 s60, s60, 0x100
	s_addc_u32 s61, s61, 0
	s_add_u32 vcc_hi, vcc_hi, 0x100
	s_addc_u32 s33, s33, 0
	s_cmp_gt_u32 s72, 13
	s_cbranch_scc0 .LBB0_463
	s_and_b64 vcc, exec, s[50:51]
	s_cbranch_vccz .LBB0_466
	s_barrier

; #define PG8_STAGE(bufoff, gbase, voff) do { _Pragma("unroll") for (int _i = 0; _i < 2; ++_i) \
;         __builtin_amdgcn_global_load_lds((const unsigned*)((const char*)(gbase) + (voff)[_i]), (PG8_LAS unsigned*)(lds + (bufoff) + ldsw + _i * 8192), 16, 0, 0); } while (0)
; #define PG8_LDA(dst, b, h) do { _Pragma("unroll") for (int m = 0; m < 4; ++m) _Pragma("unroll") for (int k = 0; k < 2; ++k) dst[m][k] = *(const PG8_LAS bf16x8*)(lds + PG8_SA(b, h) + aoff + m * 2048 + k * 1024); } while (0)
; #define PG8_LDB(dst, b, h) do { _Pragma("unroll") for (int n = 0; n < 2; ++n) _Pragma("unroll") for (int k = 0; k < 2; ++k) dst[n][k] = *(const PG8_LAS bf16x8*)(lds + PG8_SB(b, h) + boff + n * 2048 + k * 1024); } while (0)
; #define PG8_MMA(ai, bj, At, Bt) do { __builtin_amdgcn_s_setprio(1); _Pragma("unroll") for (int m = 0; m < 4; ++m) _Pragma("unroll") for (int n = 0; n < 2; ++n) _Pragma("unroll") for (int k = 0; k < 2; ++k) \
;         acc[ai][bj][m][n] = __builtin_amdgcn_mfma_f32_16x16x32_bf16(Bt[n][k], At[m][k], acc[ai][bj][m][n], 0, 0, 0); __builtin_amdgcn_s_setprio(0); } while (0)
; #define PG8_WAIT_V(n) asm volatile("s_waitcnt vmcnt(" #n ")" ::: "memory")
; #define PG8_WAIT_L(n) asm volatile("s_waitcnt lgkmcnt(" #n ")" ::: "memory")
; #define PG8_BAR __builtin_amdgcn_s_barrier()
; #define PG8_SCHED __builtin_amdgcn_sched_barrier(0)
; template <class Epi, class Sched, bool ALIGN_EPI = false, bool SP2 = false>
; __device__ __forceinline__ void gemm_phase(PG8_LAS unsigned char* lds, const Gemm g, const Sched& S, const Epi& E) {
;     ...
;             const bool last = (t == nt - 2);
;             const char* a1 = cA + (size_t)(t + 1) * kstep;
;             const char* a2 = last ? nA : cA + (size_t)(t + 2) * kstep; const char* b2 = last ? nB : cB + (size_t)(t + 2) * kstep;
;             const char* a3 = a2 + kstep; const char* b3 = b2 + kstep;
;             if (last && has_next) S.a_ready(nxt);
;             if constexpr (SP2) {
;             PG8_LDB(B0, 0, 0); PG8_LDB(B1, 0, 1); PG8_SCHED; PG8_LDA(At, 0, 0); PG8_STAGE(PG8_SA(1, 1), a1 + hstep, voffA);
;             PG8_WAIT_V(8); PG8_WAIT_L(0); PG8_BAR; PG8_MMA(0, 0, At, B0); PG8_MMA(0, 1, At, B1); PG8_BAR; PG8_SCHED;
;             PG8_LDA(At, 0, 1); PG8_STAGE(PG8_SB(0, 0), b2, voffB); PG8_STAGE(PG8_SB(0, 1), b2 + hstep, voffB); PG8_STAGE(PG8_SA(0, 0), a2, voffA);
.LBB0_777:
	ds_read_b128 v[144:147], v158
	ds_read_b128 v[168:171], v158 offset:1024
	ds_read_b128 v[172:175], v158 offset:2048
	ds_read_b128 v[176:179], v158 offset:3072
	ds_read_b128 v[180:183], v159
	ds_read_b128 v[184:187], v159 offset:1024
	ds_read_b128 v[188:191], v159 offset:2048
	ds_read_b128 v[196:199], v159 offset:3072
	s_add_u32 s60, s58, 0x100
	s_addc_u32 s61, s59, 0
	s_cmp_eq_u32 s72, 8
	s_cselect_b32 s81, s49, s61
	s_cselect_b32 s80, s48, s60
	s_cselect_b32 s79, s57, vcc_lo
	s_cselect_b32 s78, s56, s33
	v_lshl_add_u64 v[148:149], s[58:59], 0, v[136:137]
	s_add_i32 m0, s76, 0xc000
	ds_read_b128 v[200:203], v163
	ds_read_b128 v[204:207], v163 offset:1024
	ds_read_b128 v[208:211], v163 offset:2048
	ds_read_b128 v[212:215], v163 offset:3072
	ds_read_b128 v[216:219], v163 offset:4096
	ds_read_b128 v[220:223], v163 offset:5120
	ds_read_b128 v[224:227], v163 offset:6144
	ds_read_b128 v[228:231], v163 offset:7168
	global_load_lds_dwordx4 v[148:149], off
	v_lshl_add_u64 v[148:149], s[58:59], 0, v[138:139]
	s_add_i32 m0, s76, 0xe000
	s_nop 0
	global_load_lds_dwordx4 v[148:149], off
	s_waitcnt vmcnt(8)
	s_waitcnt lgkmcnt(0)
	s_barrier
	s_waitcnt lgkmcnt(0)
	v_mfma_f32_16x16x32_bf16 v[124:127], v[144:147], v[200:203], v[124:127]
	v_mfma_f32_16x16x32_bf16 v[120:123], v[172:175], v[200:203], v[120:123]
	v_mfma_f32_16x16x32_bf16 v[108:111], v[144:147], v[208:211], v[108:111]
	v_mfma_f32_16x16x32_bf16 v[104:107], v[172:175], v[208:211], v[104:107]
	v_mfma_f32_16x16x32_bf16 v[92:95], v[144:147], v[216:219], v[92:95]
	v_mfma_f32_16x16x32_bf16 v[88:91], v[172:175], v[216:219], v[88:91]
	v_mfma_f32_16x16x32_bf16 v[76:79], v[144:147], v[224:227], v[76:79]
	v_mfma_f32_16x16x32_bf16 v[72:75], v[172:175], v[224:227], v[72:75]
	v_mfma_f32_16x16x32_bf16 v[124:127], v[168:171], v[204:207], v[124:127]
	v_mfma_f32_16x16x32_bf16 v[120:123], v[176:179], v[204:207], v[120:123]
	v_mfma_f32_16x16x32_bf16 v[108:111], v[168:171], v[212:215], v[108:111]
	v_mfma_f32_16x16x32_bf16 v[104:107], v[176:179], v[212:215], v[104:107]
	v_mfma_f32_16x16x32_bf16 v[92:95], v[168:171], v[220:223], v[92:95]
	v_mfma_f32_16x16x32_bf16 v[88:91], v[176:179], v[220:223], v[88:91]
	v_mfma_f32_16x16x32_bf16 v[76:79], v[168:171], v[228:231], v[76:79]
	v_mfma_f32_16x16x32_bf16 v[72:75], v[176:179], v[228:231], v[72:75]
	v_mfma_f32_16x16x32_bf16 v[116:119], v[180:183], v[200:203], v[116:119]
	v_mfma_f32_16x16x32_bf16 v[112:115], v[188:191], v[200:203], v[112:115]
	v_mfma_f32_16x16x32_bf16 v[100:103], v[180:183], v[208:211], v[100:103]
	v_mfma_f32_16x16x32_bf16 v[96:99], v[188:191], v[208:211], v[96:99]
	v_mfma_f32_16x16x32_bf16 v[84:87], v[180:183], v[216:219], v[84:87]
	v_mfma_f32_16x16x32_bf16 v[80:83], v[188:191], v[216:219], v[80:83]
	v_mfma_f32_16x16x32_bf16 v[68:71], v[180:183], v[224:227], v[68:71]
	v_mfma_f32_16x16x32_bf16 v[64:67], v[188:191], v[224:227], v[64:67]
	v_mfma_f32_16x16x32_bf16 v[116:119], v[184:187], v[204:207], v[116:119]
	v_mfma_f32_16x16x32_bf16 v[112:115], v[196:199], v[204:207], v[112:115]
	v_mfma_f32_16x16x32_bf16 v[100:103], v[184:187], v[212:215], v[100:103]
	v_mfma_f32_16x16x32_bf16 v[96:99], v[196:199], v[212:215], v[96:99]
	v_mfma_f32_16x16x32_bf16 v[84:87], v[184:187], v[220:223], v[84:87]
	v_mfma_f32_16x16x32_bf16 v[80:83], v[196:199], v[220:223], v[80:83]
	v_mfma_f32_16x16x32_bf16 v[68:71], v[184:187], v[228:231], v[68:71]
	v_mfma_f32_16x16x32_bf16 v[64:67], v[196:199], v[228:231], v[64:67]
	s_barrier
	s_add_i32 s6, s26, s67
	v_lshl_add_u64 v[148:149], s[78:79], 0, v[130:131]
	s_mov_b32 m0, s6
	ds_read_b128 v[200:203], v163 offset:16384
	ds_read_b128 v[204:207], v163 offset:17408
	ds_read_b128 v[208:211], v163 offset:18432
	ds_read_b128 v[212:215], v163 offset:19456
	ds_read_b128 v[216:219], v163 offset:20480
	ds_read_b128 v[220:223], v163 offset:21504
	ds_read_b128 v[224:227], v163 offset:22528
	ds_read_b128 v[228:231], v163 offset:23552
	global_load_lds_dwordx4 v[148:149], off
	s_add_i32 m0, s6, 0x2000
	s_add_u32 s6, s78, 0x30000
	v_lshl_add_u64 v[232:233], s[78:79], 0, v[134:135]
	s_addc_u32 s7, s79, 0
	s_add_i32 s58, s74, s67
	global_load_lds_dwordx4 v[232:233], off
	v_lshl_add_u64 v[234:235], s[6:7], 0, v[130:131]
	s_mov_b32 m0, s58
	v_lshl_add_u64 v[236:237], s[80:81], 0, v[132:133]
	global_load_lds_dwordx4 v[234:235], off
	v_lshl_add_u64 v[234:235], s[6:7], 0, v[134:135]
	s_add_i32 m0, s58, 0x2000
	s_nop 0
	global_load_lds_dwordx4 v[234:235], off
	v_lshl_add_u64 v[234:235], s[80:81], 0, v[128:129]
	s_mov_b32 m0, s76
	s_nop 0
	global_load_lds_dwordx4 v[234:235], off
	s_mov_b32 m0, s77
	s_nop 0
	global_load_lds_dwordx4 v[236:237], off
	s_waitcnt vmcnt(8)
	s_waitcnt lgkmcnt(0)
	s_barrier
; #define PG8_STAGE(bufoff, gbase, voff) do { _Pragma("unroll") for (int _i = 0; _i < 2; ++_i) \
;         __builtin_amdgcn_global_load_lds((const unsigned*)((const char*)(gbase) + (voff)[_i]), (PG8_LAS unsigned*)(lds + (bufoff) + ldsw + _i * 8192), 16, 0, 0); } while (0)
; #define PG8_LDA(dst, b, h) do { _Pragma("unroll") for (int m = 0; m < 4; ++m) _Pragma("unroll") for (int k = 0; k < 2; ++k) dst[m][k] = *(const PG8_LAS bf16x8*)(lds + PG8_SA(b, h) + aoff + m * 2048 + k * 1024); } while (0)
; #define PG8_LDB(dst, b, h) do { _Pragma("unroll") for (int n = 0; n < 2; ++n) _Pragma("unroll") for (int k = 0; k < 2; ++k) dst[n][k] = *(const PG8_LAS bf16x8*)(lds + PG8_SB(b, h) + boff + n * 2048 + k * 1024); } while (0)
; #define PG8_MMA(ai, bj, At, Bt) do { __builtin_amdgcn_s_setprio(1); _Pragma("unroll") for (int m = 0; m < 4; ++m) _Pragma("unroll") for (int n = 0; n < 2; ++n) _Pragma("unroll") for (int k = 0; k < 2; ++k) \
;         acc[ai][bj][m][n] = __builtin_amdgcn_mfma_f32_16x16x32_bf16(Bt[n][k], At[m][k], acc[ai][bj][m][n], 0, 0, 0); __builtin_amdgcn_s_setprio(0); } while (0)
; #define PG8_WAIT_V(n) asm volatile("s_waitcnt vmcnt(" #n ")" ::: "memory")
; #define PG8_WAIT_L(n) asm volatile("s_waitcnt lgkmcnt(" #n ")" ::: "memory")
; #define PG8_BAR __builtin_amdgcn_s_barrier()
; #define PG8_SCHED __builtin_amdgcn_sched_barrier(0)
; template <class Epi, class Sched, bool ALIGN_EPI = false, bool SP2 = false>
; __device__ __forceinline__ void gemm_phase(PG8_LAS unsigned char* lds, const Gemm g, const Sched& S, const Epi& E) {
;     ...
;             PG8_WAIT_V(8); PG8_WAIT_L(0); PG8_BAR; PG8_MMA(1, 0, At, B0); PG8_MMA(1, 1, At, B1); PG8_BAR; PG8_SCHED;
;             PG8_LDB(B0, 1, 0); PG8_LDB(B1, 1, 1); PG8_SCHED; PG8_LDA(At, 1, 0); PG8_STAGE(PG8_SA(0, 1), a2 + hstep, voffA);
;             PG8_WAIT_V(8); PG8_WAIT_L(0); PG8_BAR; PG8_MMA(0, 0, At, B0); PG8_MMA(0, 1, At, B1); PG8_BAR; PG8_SCHED;
	s_waitcnt lgkmcnt(0)
	v_mfma_f32_16x16x32_bf16 v[60:63], v[144:147], v[200:203], v[60:63]
	v_mfma_f32_16x16x32_bf16 v[56:59], v[172:175], v[200:203], v[56:59]
	v_mfma_f32_16x16x32_bf16 v[44:47], v[144:147], v[208:211], v[44:47]
	v_mfma_f32_16x16x32_bf16 v[40:43], v[172:175], v[208:211], v[40:43]
	v_mfma_f32_16x16x32_bf16 v[28:31], v[144:147], v[216:219], v[28:31]
	v_mfma_f32_16x16x32_bf16 v[24:27], v[172:175], v[216:219], v[24:27]
	v_mfma_f32_16x16x32_bf16 v[12:15], v[144:147], v[224:227], v[12:15]
	v_mfma_f32_16x16x32_bf16 v[8:11], v[172:175], v[224:227], v[8:11]
	v_mfma_f32_16x16x32_bf16 v[60:63], v[168:171], v[204:207], v[60:63]
	v_mfma_f32_16x16x32_bf16 v[56:59], v[176:179], v[204:207], v[56:59]
	v_mfma_f32_16x16x32_bf16 v[44:47], v[168:171], v[212:215], v[44:47]
	v_mfma_f32_16x16x32_bf16 v[40:43], v[176:179], v[212:215], v[40:43]
	v_mfma_f32_16x16x32_bf16 v[28:31], v[168:171], v[220:223], v[28:31]
	v_mfma_f32_16x16x32_bf16 v[24:27], v[176:179], v[220:223], v[24:27]
	v_mfma_f32_16x16x32_bf16 v[12:15], v[168:171], v[228:231], v[12:15]
	v_mfma_f32_16x16x32_bf16 v[8:11], v[176:179], v[228:231], v[8:11]
	v_mfma_f32_16x16x32_bf16 v[52:55], v[180:183], v[200:203], v[52:55]
	v_mfma_f32_16x16x32_bf16 v[48:51], v[188:191], v[200:203], v[48:51]
	v_mfma_f32_16x16x32_bf16 v[36:39], v[180:183], v[208:211], v[36:39]
	v_mfma_f32_16x16x32_bf16 v[32:35], v[188:191], v[208:211], v[32:35]
	v_mfma_f32_16x16x32_bf16 v[20:23], v[180:183], v[216:219], v[20:23]
	v_mfma_f32_16x16x32_bf16 v[16:19], v[188:191], v[216:219], v[16:19]
	v_mfma_f32_16x16x32_bf16 v[4:7], v[180:183], v[224:227], v[4:7]
	v_mfma_f32_16x16x32_bf16 v[0:3], v[188:191], v[224:227], v[0:3]
	v_mfma_f32_16x16x32_bf16 v[52:55], v[184:187], v[204:207], v[52:55]
	v_mfma_f32_16x16x32_bf16 v[48:51], v[196:199], v[204:207], v[48:51]
	v_mfma_f32_16x16x32_bf16 v[36:39], v[184:187], v[212:215], v[36:39]
	v_mfma_f32_16x16x32_bf16 v[32:35], v[196:199], v[212:215], v[32:35]
	v_mfma_f32_16x16x32_bf16 v[20:23], v[184:187], v[220:223], v[20:23]
	v_mfma_f32_16x16x32_bf16 v[16:19], v[196:199], v[220:223], v[16:19]
	v_mfma_f32_16x16x32_bf16 v[4:7], v[184:187], v[228:231], v[4:7]
	v_mfma_f32_16x16x32_bf16 v[0:3], v[196:199], v[228:231], v[0:3]
	s_barrier
	s_add_i32 s58, 0, 0x18000
	v_add_u32_e32 v167, s58, v156
	s_add_i32 s59, 0, 0x1c000
	ds_read_b128 v[144:147], v167
	ds_read_b128 v[168:171], v167 offset:1024
	ds_read_b128 v[172:175], v167 offset:2048
	ds_read_b128 v[176:179], v167 offset:3072
	v_add_u32_e32 v167, s59, v156
	ds_read_b128 v[180:183], v167
	ds_read_b128 v[184:187], v167 offset:1024
	ds_read_b128 v[188:191], v167 offset:2048
	ds_read_b128 v[196:199], v167 offset:3072
	s_add_u32 s6, s80, 0x30000
	s_addc_u32 s7, s81, 0
	s_mov_b32 m0, s36
	v_lshl_add_u64 v[238:239], s[6:7], 0, v[128:129]
	ds_read_b128 v[200:203], v163 offset:32768
	ds_read_b128 v[204:207], v163 offset:33792
	ds_read_b128 v[208:211], v163 offset:34816
	ds_read_b128 v[212:215], v163 offset:35840
	ds_read_b128 v[216:219], v163 offset:36864
	ds_read_b128 v[220:223], v163 offset:37888
	ds_read_b128 v[224:227], v163 offset:38912
	ds_read_b128 v[228:231], v163 offset:39936
	global_load_lds_dwordx4 v[238:239], off
	v_lshl_add_u64 v[238:239], s[6:7], 0, v[132:133]
	s_mov_b32 m0, s37
	s_nop 0
	global_load_lds_dwordx4 v[238:239], off
	s_waitcnt vmcnt(8)
	s_waitcnt lgkmcnt(0)
	s_barrier
	s_waitcnt lgkmcnt(0)
	v_mfma_f32_16x16x32_bf16 v[124:127], v[144:147], v[200:203], v[124:127]
	v_mfma_f32_16x16x32_bf16 v[120:123], v[172:175], v[200:203], v[120:123]
	v_mfma_f32_16x16x32_bf16 v[108:111], v[144:147], v[208:211], v[108:111]
	v_mfma_f32_16x16x32_bf16 v[104:107], v[172:175], v[208:211], v[104:107]
	v_mfma_f32_16x16x32_bf16 v[92:95], v[144:147], v[216:219], v[92:95]
	v_mfma_f32_16x16x32_bf16 v[88:91], v[172:175], v[216:219], v[88:91]
	v_mfma_f32_16x16x32_bf16 v[76:79], v[144:147], v[224:227], v[76:79]
	v_mfma_f32_16x16x32_bf16 v[72:75], v[172:175], v[224:227], v[72:75]
	v_mfma_f32_16x16x32_bf16 v[124:127], v[168:171], v[204:207], v[124:127]
	v_mfma_f32_16x16x32_bf16 v[120:123], v[176:179], v[204:207], v[120:123]
	v_mfma_f32_16x16x32_bf16 v[108:111], v[168:171], v[212:215], v[108:111]
	v_mfma_f32_16x16x32_bf16 v[104:107], v[176:179], v[212:215], v[104:107]
	v_mfma_f32_16x16x32_bf16 v[92:95], v[168:171], v[220:223], v[92:95]
	v_mfma_f32_16x16x32_bf16 v[88:91], v[176:179], v[220:223], v[88:91]
	v_mfma_f32_16x16x32_bf16 v[76:79], v[168:171], v[228:231], v[76:79]
	v_mfma_f32_16x16x32_bf16 v[72:75], v[176:179], v[228:231], v[72:75]
	v_mfma_f32_16x16x32_bf16 v[116:119], v[180:183], v[200:203], v[116:119]
	v_mfma_f32_16x16x32_bf16 v[112:115], v[188:191], v[200:203], v[112:115]
	v_mfma_f32_16x16x32_bf16 v[100:103], v[180:183], v[208:211], v[100:103]
	v_mfma_f32_16x16x32_bf16 v[96:99], v[188:191], v[208:211], v[96:99]
	v_mfma_f32_16x16x32_bf16 v[84:87], v[180:183], v[216:219], v[84:87]
	v_mfma_f32_16x16x32_bf16 v[80:83], v[188:191], v[216:219], v[80:83]
	v_mfma_f32_16x16x32_bf16 v[68:71], v[180:183], v[224:227], v[68:71]
	v_mfma_f32_16x16x32_bf16 v[64:67], v[188:191], v[224:227], v[64:67]
	v_mfma_f32_16x16x32_bf16 v[116:119], v[184:187], v[204:207], v[116:119]
	v_mfma_f32_16x16x32_bf16 v[112:115], v[196:199], v[204:207], v[112:115]
	v_mfma_f32_16x16x32_bf16 v[100:103], v[184:187], v[212:215], v[100:103]
	v_mfma_f32_16x16x32_bf16 v[96:99], v[196:199], v[212:215], v[96:99]
	v_mfma_f32_16x16x32_bf16 v[84:87], v[184:187], v[220:223], v[84:87]
	v_mfma_f32_16x16x32_bf16 v[80:83], v[196:199], v[220:223], v[80:83]
	v_mfma_f32_16x16x32_bf16 v[68:71], v[184:187], v[228:231], v[68:71]
	v_mfma_f32_16x16x32_bf16 v[64:67], v[196:199], v[228:231], v[64:67]
	s_barrier
; #define PG8_STAGE(bufoff, gbase, voff) do { _Pragma("unroll") for (int _i = 0; _i < 2; ++_i) \
;         __builtin_amdgcn_global_load_lds((const unsigned*)((const char*)(gbase) + (voff)[_i]), (PG8_LAS unsigned*)(lds + (bufoff) + ldsw + _i * 8192), 16, 0, 0); } while (0)
; #define PG8_LDA(dst, b, h) do { _Pragma("unroll") for (int m = 0; m < 4; ++m) _Pragma("unroll") for (int k = 0; k < 2; ++k) dst[m][k] = *(const PG8_LAS bf16x8*)(lds + PG8_SA(b, h) + aoff + m * 2048 + k * 1024); } while (0)
; #define PG8_MMA(ai, bj, At, Bt) do { __builtin_amdgcn_s_setprio(1); _Pragma("unroll") for (int m = 0; m < 4; ++m) _Pragma("unroll") for (int n = 0; n < 2; ++n) _Pragma("unroll") for (int k = 0; k < 2; ++k) \
;         acc[ai][bj][m][n] = __builtin_amdgcn_mfma_f32_16x16x32_bf16(Bt[n][k], At[m][k], acc[ai][bj][m][n], 0, 0, 0); __builtin_amdgcn_s_setprio(0); } while (0)
; #define PG8_WAIT_V(n) asm volatile("s_waitcnt vmcnt(" #n ")" ::: "memory")
; #define PG8_WAIT_L(n) asm volatile("s_waitcnt lgkmcnt(" #n ")" ::: "memory")
; #define PG8_BAR __builtin_amdgcn_s_barrier()
; #define PG8_SCHED __builtin_amdgcn_sched_barrier(0)
; template <class Epi, class Sched, bool ALIGN_EPI = false, bool SP2 = false>
; __device__ __forceinline__ void gemm_phase(PG8_LAS unsigned char* lds, const Gemm g, const Sched& S, const Epi& E) {
;     ...
;             PG8_LDA(At, 1, 1); PG8_STAGE(PG8_SB(1, 0), b3, voffB); PG8_STAGE(PG8_SB(1, 1), b3 + hstep, voffB); PG8_STAGE(PG8_SA(1, 0), a3, voffA);
;             PG8_WAIT_V(8); PG8_WAIT_L(0); PG8_BAR; PG8_MMA(1, 0, At, B0); PG8_MMA(1, 1, At, B1); PG8_BAR; PG8_SCHED;
	s_add_i32 s6, s58, s67
	v_lshl_add_u64 v[148:149], v[148:149], 0, s[52:53]
	s_mov_b32 m0, s6
	ds_read_b128 v[200:203], v163 offset:49152
	ds_read_b128 v[204:207], v163 offset:50176
	ds_read_b128 v[208:211], v163 offset:51200
	ds_read_b128 v[212:215], v163 offset:52224
	ds_read_b128 v[216:219], v163 offset:53248
	ds_read_b128 v[220:223], v163 offset:54272
	ds_read_b128 v[224:227], v163 offset:55296
	ds_read_b128 v[228:231], v163 offset:56320
	global_load_lds_dwordx4 v[148:149], off
	s_add_i32 m0, s6, 0x2000
	s_add_u32 s6, s78, 0x30080
	v_lshl_add_u64 v[148:149], v[232:233], 0, s[52:53]
	s_addc_u32 s7, s79, 0
	s_add_i32 s58, s59, s67
	global_load_lds_dwordx4 v[148:149], off
	v_lshl_add_u64 v[148:149], s[6:7], 0, v[130:131]
	s_mov_b32 m0, s58
	s_nop 0
	global_load_lds_dwordx4 v[148:149], off
	v_lshl_add_u64 v[148:149], s[6:7], 0, v[134:135]
	s_add_i32 m0, s58, 0x2000
	s_nop 0
	global_load_lds_dwordx4 v[148:149], off
	v_lshl_add_u64 v[148:149], v[234:235], 0, s[52:53]
	s_mov_b32 m0, s31
	s_nop 0
	global_load_lds_dwordx4 v[148:149], off
	v_lshl_add_u64 v[148:149], v[236:237], 0, s[52:53]
	s_mov_b32 m0, s4
	s_nop 0
	global_load_lds_dwordx4 v[148:149], off
	s_waitcnt vmcnt(8)
	s_waitcnt lgkmcnt(0)
	s_barrier
	s_waitcnt lgkmcnt(0)
	v_mfma_f32_16x16x32_bf16 v[60:63], v[144:147], v[200:203], v[60:63]
	v_mfma_f32_16x16x32_bf16 v[56:59], v[172:175], v[200:203], v[56:59]
	v_mfma_f32_16x16x32_bf16 v[44:47], v[144:147], v[208:211], v[44:47]
	v_mfma_f32_16x16x32_bf16 v[40:43], v[172:175], v[208:211], v[40:43]
	v_mfma_f32_16x16x32_bf16 v[28:31], v[144:147], v[216:219], v[28:31]
	v_mfma_f32_16x16x32_bf16 v[24:27], v[172:175], v[216:219], v[24:27]
	v_mfma_f32_16x16x32_bf16 v[12:15], v[144:147], v[224:227], v[12:15]
	v_mfma_f32_16x16x32_bf16 v[8:11], v[172:175], v[224:227], v[8:11]
	v_mfma_f32_16x16x32_bf16 v[60:63], v[168:171], v[204:207], v[60:63]
	v_mfma_f32_16x16x32_bf16 v[56:59], v[176:179], v[204:207], v[56:59]
	v_mfma_f32_16x16x32_bf16 v[44:47], v[168:171], v[212:215], v[44:47]
	v_mfma_f32_16x16x32_bf16 v[40:43], v[176:179], v[212:215], v[40:43]
	v_mfma_f32_16x16x32_bf16 v[28:31], v[168:171], v[220:223], v[28:31]
	v_mfma_f32_16x16x32_bf16 v[24:27], v[176:179], v[220:223], v[24:27]
	v_mfma_f32_16x16x32_bf16 v[12:15], v[168:171], v[228:231], v[12:15]
	v_mfma_f32_16x16x32_bf16 v[8:11], v[176:179], v[228:231], v[8:11]
	v_mfma_f32_16x16x32_bf16 v[52:55], v[180:183], v[200:203], v[52:55]
	v_mfma_f32_16x16x32_bf16 v[48:51], v[188:191], v[200:203], v[48:51]
	v_mfma_f32_16x16x32_bf16 v[36:39], v[180:183], v[208:211], v[36:39]
	v_mfma_f32_16x16x32_bf16 v[32:35], v[188:191], v[208:211], v[32:35]
	v_mfma_f32_16x16x32_bf16 v[20:23], v[180:183], v[216:219], v[20:23]
	v_mfma_f32_16x16x32_bf16 v[16:19], v[188:191], v[216:219], v[16:19]
	v_mfma_f32_16x16x32_bf16 v[4:7], v[180:183], v[224:227], v[4:7]
	v_mfma_f32_16x16x32_bf16 v[0:3], v[188:191], v[224:227], v[0:3]
	v_mfma_f32_16x16x32_bf16 v[52:55], v[184:187], v[204:207], v[52:55]
	v_mfma_f32_16x16x32_bf16 v[48:51], v[196:199], v[204:207], v[48:51]
	v_mfma_f32_16x16x32_bf16 v[36:39], v[184:187], v[212:215], v[36:39]
	v_mfma_f32_16x16x32_bf16 v[32:35], v[196:199], v[212:215], v[32:35]
	v_mfma_f32_16x16x32_bf16 v[20:23], v[184:187], v[220:223], v[20:23]
	v_mfma_f32_16x16x32_bf16 v[16:19], v[196:199], v[220:223], v[16:19]
	v_mfma_f32_16x16x32_bf16 v[4:7], v[184:187], v[228:231], v[4:7]
	v_mfma_f32_16x16x32_bf16 v[0:3], v[196:199], v[228:231], v[0:3]
	s_barrier
	s_add_i32 s72, s72, 2
	s_add_u32 s33, s33, 0x100
	s_addc_u32 vcc_lo, vcc_lo, 0
	s_cmp_gt_u32 s72, 9
	s_mov_b64 s[58:59], s[60:61]
	s_cbranch_scc0 .LBB0_777
	s_and_b64 vcc, exec, s[54:55]
	s_cbranch_vccz .LBB0_780
	s_barrier

; #define PG8_STAGE(bufoff, gbase, voff) do { _Pragma("unroll") for (int _i = 0; _i < 2; ++_i) \
;         __builtin_amdgcn_global_load_lds((const unsigned*)((const char*)(gbase) + (voff)[_i]), (PG8_LAS unsigned*)(lds + (bufoff) + ldsw + _i * 8192), 16, 0, 0); } while (0)
; #define PG8_LDA(dst, b, h) do { _Pragma("unroll") for (int m = 0; m < 4; ++m) _Pragma("unroll") for (int k = 0; k < 2; ++k) dst[m][k] = *(const PG8_LAS bf16x8*)(lds + PG8_SA(b, h) + aoff + m * 2048 + k * 1024); } while (0)
; #define PG8_LDB(dst, b, h) do { _Pragma("unroll") for (int n = 0; n < 2; ++n) _Pragma("unroll") for (int k = 0; k < 2; ++k) dst[n][k] = *(const PG8_LAS bf16x8*)(lds + PG8_SB(b, h) + boff + n * 2048 + k * 1024); } while (0)
; #define PG8_MMA(ai, bj, At, Bt) do { __builtin_amdgcn_s_setprio(1); _Pragma("unroll") for (int m = 0; m < 4; ++m) _Pragma("unroll") for (int n = 0; n < 2; ++n) _Pragma("unroll") for (int k = 0; k < 2; ++k) \
;         acc[ai][bj][m][n] = __builtin_amdgcn_mfma_f32_16x16x32_bf16(Bt[n][k], At[m][k], acc[ai][bj][m][n], 0, 0, 0); __builtin_amdgcn_s_setprio(0); } while (0)
; #define PG8_WAIT_V(n) asm volatile("s_waitcnt vmcnt(" #n ")" ::: "memory")
; #define PG8_WAIT_L(n) asm volatile("s_waitcnt lgkmcnt(" #n ")" ::: "memory")
; #define PG8_BAR __builtin_amdgcn_s_barrier()
; #define PG8_SCHED __builtin_amdgcn_sched_barrier(0)
; template <class Epi, class Sched, bool ALIGN_EPI = false, bool SP2 = false>
; __device__ __forceinline__ void gemm_phase(PG8_LAS unsigned char* lds, const Gemm g, const Sched& S, const Epi& E) {
;     ...
;             const bool last = (t == nt - 2);
;             const char* a1 = cA + (size_t)(t + 1) * kstep;
;             const char* a2 = last ? nA : cA + (size_t)(t + 2) * kstep; const char* b2 = last ? nB : cB + (size_t)(t + 2) * kstep;
;             const char* a3 = a2 + kstep; const char* b3 = b2 + kstep;
;             if (last && has_next) S.a_ready(nxt);
;             if constexpr (SP2) {
;             PG8_LDB(B0, 0, 0); PG8_LDB(B1, 0, 1); PG8_SCHED; PG8_LDA(At, 0, 0); PG8_STAGE(PG8_SA(1, 1), a1 + hstep, voffA);
;             PG8_WAIT_V(8); PG8_WAIT_L(0); PG8_BAR; PG8_MMA(0, 0, At, B0); PG8_MMA(0, 1, At, B1); PG8_BAR; PG8_SCHED;
;             PG8_LDA(At, 0, 1); PG8_STAGE(PG8_SB(0, 0), b2, voffB); PG8_STAGE(PG8_SB(0, 1), b2 + hstep, voffB); PG8_STAGE(PG8_SA(0, 0), a2, voffA);
.LBB0_901:
	ds_read_b128 v[144:147], v159
	ds_read_b128 v[168:171], v159 offset:1024
	ds_read_b128 v[172:175], v159 offset:2048
	ds_read_b128 v[176:179], v159 offset:3072
	ds_read_b128 v[180:183], v163
	ds_read_b128 v[184:187], v163 offset:1024
	ds_read_b128 v[188:191], v163 offset:2048
	ds_read_b128 v[196:199], v163 offset:3072
	s_add_u32 s6, s56, 0xfffc0080
	s_addc_u32 s7, s57, -1
	s_cmp_eq_u32 s72, 12
	s_cselect_b32 s61, s49, s7
	s_cselect_b32 s60, s76, s6
	s_cselect_b32 s59, s41, s33
	s_cselect_b32 s58, s77, s78
	v_lshl_add_u64 v[148:149], s[56:57], 0, v[136:137]
	s_add_i32 m0, s30, 0xc000
	ds_read_b128 v[200:203], v166
	ds_read_b128 v[204:207], v166 offset:1024
	ds_read_b128 v[208:211], v166 offset:2048
	ds_read_b128 v[212:215], v166 offset:3072
	ds_read_b128 v[216:219], v166 offset:4096
	ds_read_b128 v[220:223], v166 offset:5120
	ds_read_b128 v[224:227], v166 offset:6144
	ds_read_b128 v[228:231], v166 offset:7168
	global_load_lds_dwordx4 v[148:149], off
	v_lshl_add_u64 v[148:149], s[56:57], 0, v[138:139]
	s_add_i32 m0, s30, 0xe000
	s_nop 0
	global_load_lds_dwordx4 v[148:149], off
	s_waitcnt vmcnt(8)
	s_waitcnt lgkmcnt(0)
	s_barrier
	s_waitcnt lgkmcnt(0)
	v_mfma_f32_16x16x32_bf16 v[124:127], v[144:147], v[200:203], v[124:127]
	v_mfma_f32_16x16x32_bf16 v[116:119], v[172:175], v[200:203], v[116:119]
	v_mfma_f32_16x16x32_bf16 v[108:111], v[144:147], v[208:211], v[108:111]
	v_mfma_f32_16x16x32_bf16 v[100:103], v[172:175], v[208:211], v[100:103]
	v_mfma_f32_16x16x32_bf16 v[92:95], v[144:147], v[216:219], v[92:95]
	v_mfma_f32_16x16x32_bf16 v[84:87], v[172:175], v[216:219], v[84:87]
	v_mfma_f32_16x16x32_bf16 v[76:79], v[144:147], v[224:227], v[76:79]
	v_mfma_f32_16x16x32_bf16 v[68:71], v[172:175], v[224:227], v[68:71]
	v_mfma_f32_16x16x32_bf16 v[124:127], v[168:171], v[204:207], v[124:127]
	v_mfma_f32_16x16x32_bf16 v[116:119], v[176:179], v[204:207], v[116:119]
	v_mfma_f32_16x16x32_bf16 v[108:111], v[168:171], v[212:215], v[108:111]
	v_mfma_f32_16x16x32_bf16 v[100:103], v[176:179], v[212:215], v[100:103]
	v_mfma_f32_16x16x32_bf16 v[92:95], v[168:171], v[220:223], v[92:95]
	v_mfma_f32_16x16x32_bf16 v[84:87], v[176:179], v[220:223], v[84:87]
	v_mfma_f32_16x16x32_bf16 v[76:79], v[168:171], v[228:231], v[76:79]
	v_mfma_f32_16x16x32_bf16 v[68:71], v[176:179], v[228:231], v[68:71]
	v_mfma_f32_16x16x32_bf16 v[120:123], v[180:183], v[200:203], v[120:123]
	v_mfma_f32_16x16x32_bf16 v[112:115], v[188:191], v[200:203], v[112:115]
	v_mfma_f32_16x16x32_bf16 v[104:107], v[180:183], v[208:211], v[104:107]
	v_mfma_f32_16x16x32_bf16 v[96:99], v[188:191], v[208:211], v[96:99]
	v_mfma_f32_16x16x32_bf16 v[88:91], v[180:183], v[216:219], v[88:91]
	v_mfma_f32_16x16x32_bf16 v[80:83], v[188:191], v[216:219], v[80:83]
	v_mfma_f32_16x16x32_bf16 v[72:75], v[180:183], v[224:227], v[72:75]
	v_mfma_f32_16x16x32_bf16 v[64:67], v[188:191], v[224:227], v[64:67]
	v_mfma_f32_16x16x32_bf16 v[120:123], v[184:187], v[204:207], v[120:123]
	v_mfma_f32_16x16x32_bf16 v[112:115], v[196:199], v[204:207], v[112:115]
	v_mfma_f32_16x16x32_bf16 v[104:107], v[184:187], v[212:215], v[104:107]
	v_mfma_f32_16x16x32_bf16 v[96:99], v[196:199], v[212:215], v[96:99]
	v_mfma_f32_16x16x32_bf16 v[88:91], v[184:187], v[220:223], v[88:91]
	v_mfma_f32_16x16x32_bf16 v[80:83], v[196:199], v[220:223], v[80:83]
	v_mfma_f32_16x16x32_bf16 v[72:75], v[184:187], v[228:231], v[72:75]
	v_mfma_f32_16x16x32_bf16 v[64:67], v[196:199], v[228:231], v[64:67]
	s_barrier
	s_add_i32 s6, s67, s27
	v_lshl_add_u64 v[148:149], s[58:59], 0, v[132:133]
	s_mov_b32 m0, s6
	ds_read_b128 v[200:203], v166 offset:16384
	ds_read_b128 v[204:207], v166 offset:17408
	ds_read_b128 v[208:211], v166 offset:18432
	ds_read_b128 v[212:215], v166 offset:19456
	ds_read_b128 v[216:219], v166 offset:20480
	ds_read_b128 v[220:223], v166 offset:21504
	ds_read_b128 v[224:227], v166 offset:22528
	ds_read_b128 v[228:231], v166 offset:23552
	global_load_lds_dwordx4 v[148:149], off
	s_add_i32 m0, s6, 0x2000
	s_add_u32 s6, s58, 0x40000
	v_lshl_add_u64 v[232:233], s[58:59], 0, v[128:129]
	s_addc_u32 s7, s59, 0
	s_add_i32 s73, s68, s27
	global_load_lds_dwordx4 v[232:233], off
	v_lshl_add_u64 v[234:235], s[6:7], 0, v[132:133]
	s_mov_b32 m0, s73
	v_lshl_add_u64 v[236:237], s[60:61], 0, v[130:131]
	global_load_lds_dwordx4 v[234:235], off
	v_lshl_add_u64 v[234:235], s[6:7], 0, v[128:129]
	s_add_i32 m0, s73, 0x2000
	s_nop 0
	global_load_lds_dwordx4 v[234:235], off
	v_lshl_add_u64 v[234:235], s[60:61], 0, v[134:135]
	s_mov_b32 m0, s30
	s_nop 0
	global_load_lds_dwordx4 v[234:235], off
	s_mov_b32 m0, s31
	s_nop 0
	global_load_lds_dwordx4 v[236:237], off
	s_waitcnt vmcnt(8)
	s_waitcnt lgkmcnt(0)
	s_barrier
; #define PG8_STAGE(bufoff, gbase, voff) do { _Pragma("unroll") for (int _i = 0; _i < 2; ++_i) \
;         __builtin_amdgcn_global_load_lds((const unsigned*)((const char*)(gbase) + (voff)[_i]), (PG8_LAS unsigned*)(lds + (bufoff) + ldsw + _i * 8192), 16, 0, 0); } while (0)
; #define PG8_LDA(dst, b, h) do { _Pragma("unroll") for (int m = 0; m < 4; ++m) _Pragma("unroll") for (int k = 0; k < 2; ++k) dst[m][k] = *(const PG8_LAS bf16x8*)(lds + PG8_SA(b, h) + aoff + m * 2048 + k * 1024); } while (0)
; #define PG8_LDB(dst, b, h) do { _Pragma("unroll") for (int n = 0; n < 2; ++n) _Pragma("unroll") for (int k = 0; k < 2; ++k) dst[n][k] = *(const PG8_LAS bf16x8*)(lds + PG8_SB(b, h) + boff + n * 2048 + k * 1024); } while (0)
; #define PG8_MMA(ai, bj, At, Bt) do { __builtin_amdgcn_s_setprio(1); _Pragma("unroll") for (int m = 0; m < 4; ++m) _Pragma("unroll") for (int n = 0; n < 2; ++n) _Pragma("unroll") for (int k = 0; k < 2; ++k) \
;         acc[ai][bj][m][n] = __builtin_amdgcn_mfma_f32_16x16x32_bf16(Bt[n][k], At[m][k], acc[ai][bj][m][n], 0, 0, 0); __builtin_amdgcn_s_setprio(0); } while (0)
; #define PG8_WAIT_V(n) asm volatile("s_waitcnt vmcnt(" #n ")" ::: "memory")
; #define PG8_WAIT_L(n) asm volatile("s_waitcnt lgkmcnt(" #n ")" ::: "memory")
; #define PG8_BAR __builtin_amdgcn_s_barrier()
; #define PG8_SCHED __builtin_amdgcn_sched_barrier(0)
; template <class Epi, class Sched, bool ALIGN_EPI = false, bool SP2 = false>
; __device__ __forceinline__ void gemm_phase(PG8_LAS unsigned char* lds, const Gemm g, const Sched& S, const Epi& E) {
;     ...
;             PG8_WAIT_V(8); PG8_WAIT_L(0); PG8_BAR; PG8_MMA(1, 0, At, B0); PG8_MMA(1, 1, At, B1); PG8_BAR; PG8_SCHED;
;             PG8_LDB(B0, 1, 0); PG8_LDB(B1, 1, 1); PG8_SCHED; PG8_LDA(At, 1, 0); PG8_STAGE(PG8_SA(0, 1), a2 + hstep, voffA);
;             PG8_WAIT_V(8); PG8_WAIT_L(0); PG8_BAR; PG8_MMA(0, 0, At, B0); PG8_MMA(0, 1, At, B1); PG8_BAR; PG8_SCHED;
	s_waitcnt lgkmcnt(0)
	v_mfma_f32_16x16x32_bf16 v[60:63], v[144:147], v[200:203], v[60:63]
	v_mfma_f32_16x16x32_bf16 v[52:55], v[172:175], v[200:203], v[52:55]
	v_mfma_f32_16x16x32_bf16 v[44:47], v[144:147], v[208:211], v[44:47]
	v_mfma_f32_16x16x32_bf16 v[36:39], v[172:175], v[208:211], v[36:39]
	v_mfma_f32_16x16x32_bf16 v[28:31], v[144:147], v[216:219], v[28:31]
	v_mfma_f32_16x16x32_bf16 v[20:23], v[172:175], v[216:219], v[20:23]
	v_mfma_f32_16x16x32_bf16 v[12:15], v[144:147], v[224:227], v[12:15]
	v_mfma_f32_16x16x32_bf16 v[4:7], v[172:175], v[224:227], v[4:7]
	v_mfma_f32_16x16x32_bf16 v[60:63], v[168:171], v[204:207], v[60:63]
	v_mfma_f32_16x16x32_bf16 v[52:55], v[176:179], v[204:207], v[52:55]
	v_mfma_f32_16x16x32_bf16 v[44:47], v[168:171], v[212:215], v[44:47]
	v_mfma_f32_16x16x32_bf16 v[36:39], v[176:179], v[212:215], v[36:39]
	v_mfma_f32_16x16x32_bf16 v[28:31], v[168:171], v[220:223], v[28:31]
	v_mfma_f32_16x16x32_bf16 v[20:23], v[176:179], v[220:223], v[20:23]
	v_mfma_f32_16x16x32_bf16 v[12:15], v[168:171], v[228:231], v[12:15]
	v_mfma_f32_16x16x32_bf16 v[4:7], v[176:179], v[228:231], v[4:7]
	v_mfma_f32_16x16x32_bf16 v[56:59], v[180:183], v[200:203], v[56:59]
	v_mfma_f32_16x16x32_bf16 v[48:51], v[188:191], v[200:203], v[48:51]
	v_mfma_f32_16x16x32_bf16 v[40:43], v[180:183], v[208:211], v[40:43]
	v_mfma_f32_16x16x32_bf16 v[32:35], v[188:191], v[208:211], v[32:35]
	v_mfma_f32_16x16x32_bf16 v[24:27], v[180:183], v[216:219], v[24:27]
	v_mfma_f32_16x16x32_bf16 v[16:19], v[188:191], v[216:219], v[16:19]
	v_mfma_f32_16x16x32_bf16 v[8:11], v[180:183], v[224:227], v[8:11]
	v_mfma_f32_16x16x32_bf16 v[0:3], v[188:191], v[224:227], v[0:3]
	v_mfma_f32_16x16x32_bf16 v[56:59], v[184:187], v[204:207], v[56:59]
	v_mfma_f32_16x16x32_bf16 v[48:51], v[196:199], v[204:207], v[48:51]
	v_mfma_f32_16x16x32_bf16 v[40:43], v[184:187], v[212:215], v[40:43]
	v_mfma_f32_16x16x32_bf16 v[32:35], v[196:199], v[212:215], v[32:35]
	v_mfma_f32_16x16x32_bf16 v[24:27], v[184:187], v[220:223], v[24:27]
	v_mfma_f32_16x16x32_bf16 v[16:19], v[196:199], v[220:223], v[16:19]
	v_mfma_f32_16x16x32_bf16 v[8:11], v[184:187], v[228:231], v[8:11]
	v_mfma_f32_16x16x32_bf16 v[0:3], v[196:199], v[228:231], v[0:3]
	s_barrier
	s_add_i32 s73, 0, 0x18000
	v_add_u32_e32 v167, s73, v156
	s_add_i32 s79, 0, 0x1c000
	ds_read_b128 v[144:147], v167
	ds_read_b128 v[168:171], v167 offset:1024
	ds_read_b128 v[172:175], v167 offset:2048
	ds_read_b128 v[176:179], v167 offset:3072
	v_add_u32_e32 v167, s79, v156
	ds_read_b128 v[180:183], v167
	ds_read_b128 v[184:187], v167 offset:1024
	ds_read_b128 v[188:191], v167 offset:2048
	ds_read_b128 v[196:199], v167 offset:3072
	s_add_u32 s6, s60, 0x40000
	s_addc_u32 s7, s61, 0
	s_mov_b32 m0, s42
	v_lshl_add_u64 v[238:239], s[6:7], 0, v[134:135]
	ds_read_b128 v[200:203], v166 offset:32768
	ds_read_b128 v[204:207], v166 offset:33792
	ds_read_b128 v[208:211], v166 offset:34816
	ds_read_b128 v[212:215], v166 offset:35840
	ds_read_b128 v[216:219], v166 offset:36864
	ds_read_b128 v[220:223], v166 offset:37888
	ds_read_b128 v[224:227], v166 offset:38912
	ds_read_b128 v[228:231], v166 offset:39936
	global_load_lds_dwordx4 v[238:239], off
	v_lshl_add_u64 v[238:239], s[6:7], 0, v[130:131]
	s_mov_b32 m0, s43
	s_nop 0
	global_load_lds_dwordx4 v[238:239], off
	s_waitcnt vmcnt(8)
	s_waitcnt lgkmcnt(0)
	s_barrier
	s_waitcnt lgkmcnt(0)
	v_mfma_f32_16x16x32_bf16 v[124:127], v[144:147], v[200:203], v[124:127]
	v_mfma_f32_16x16x32_bf16 v[116:119], v[172:175], v[200:203], v[116:119]
	v_mfma_f32_16x16x32_bf16 v[108:111], v[144:147], v[208:211], v[108:111]
	v_mfma_f32_16x16x32_bf16 v[100:103], v[172:175], v[208:211], v[100:103]
	v_mfma_f32_16x16x32_bf16 v[92:95], v[144:147], v[216:219], v[92:95]
	v_mfma_f32_16x16x32_bf16 v[84:87], v[172:175], v[216:219], v[84:87]
	v_mfma_f32_16x16x32_bf16 v[76:79], v[144:147], v[224:227], v[76:79]
	v_mfma_f32_16x16x32_bf16 v[68:71], v[172:175], v[224:227], v[68:71]
	v_mfma_f32_16x16x32_bf16 v[124:127], v[168:171], v[204:207], v[124:127]
	v_mfma_f32_16x16x32_bf16 v[116:119], v[176:179], v[204:207], v[116:119]
	v_mfma_f32_16x16x32_bf16 v[108:111], v[168:171], v[212:215], v[108:111]
	v_mfma_f32_16x16x32_bf16 v[100:103], v[176:179], v[212:215], v[100:103]
	v_mfma_f32_16x16x32_bf16 v[92:95], v[168:171], v[220:223], v[92:95]
	v_mfma_f32_16x16x32_bf16 v[84:87], v[176:179], v[220:223], v[84:87]
	v_mfma_f32_16x16x32_bf16 v[76:79], v[168:171], v[228:231], v[76:79]
	v_mfma_f32_16x16x32_bf16 v[68:71], v[176:179], v[228:231], v[68:71]
	v_mfma_f32_16x16x32_bf16 v[120:123], v[180:183], v[200:203], v[120:123]
	v_mfma_f32_16x16x32_bf16 v[112:115], v[188:191], v[200:203], v[112:115]
	v_mfma_f32_16x16x32_bf16 v[104:107], v[180:183], v[208:211], v[104:107]
	v_mfma_f32_16x16x32_bf16 v[96:99], v[188:191], v[208:211], v[96:99]
	v_mfma_f32_16x16x32_bf16 v[88:91], v[180:183], v[216:219], v[88:91]
	v_mfma_f32_16x16x32_bf16 v[80:83], v[188:191], v[216:219], v[80:83]
	v_mfma_f32_16x16x32_bf16 v[72:75], v[180:183], v[224:227], v[72:75]
	v_mfma_f32_16x16x32_bf16 v[64:67], v[188:191], v[224:227], v[64:67]
	v_mfma_f32_16x16x32_bf16 v[120:123], v[184:187], v[204:207], v[120:123]
	v_mfma_f32_16x16x32_bf16 v[112:115], v[196:199], v[204:207], v[112:115]
	v_mfma_f32_16x16x32_bf16 v[104:107], v[184:187], v[212:215], v[104:107]
	v_mfma_f32_16x16x32_bf16 v[96:99], v[196:199], v[212:215], v[96:99]
	v_mfma_f32_16x16x32_bf16 v[88:91], v[184:187], v[220:223], v[88:91]
	v_mfma_f32_16x16x32_bf16 v[80:83], v[196:199], v[220:223], v[80:83]
	v_mfma_f32_16x16x32_bf16 v[72:75], v[184:187], v[228:231], v[72:75]
	v_mfma_f32_16x16x32_bf16 v[64:67], v[196:199], v[228:231], v[64:67]
	s_barrier
; #define PG8_STAGE(bufoff, gbase, voff) do { _Pragma("unroll") for (int _i = 0; _i < 2; ++_i) \
;         __builtin_amdgcn_global_load_lds((const unsigned*)((const char*)(gbase) + (voff)[_i]), (PG8_LAS unsigned*)(lds + (bufoff) + ldsw + _i * 8192), 16, 0, 0); } while (0)
; #define PG8_LDA(dst, b, h) do { _Pragma("unroll") for (int m = 0; m < 4; ++m) _Pragma("unroll") for (int k = 0; k < 2; ++k) dst[m][k] = *(const PG8_LAS bf16x8*)(lds + PG8_SA(b, h) + aoff + m * 2048 + k * 1024); } while (0)
; #define PG8_MMA(ai, bj, At, Bt) do { __builtin_amdgcn_s_setprio(1); _Pragma("unroll") for (int m = 0; m < 4; ++m) _Pragma("unroll") for (int n = 0; n < 2; ++n) _Pragma("unroll") for (int k = 0; k < 2; ++k) \
;         acc[ai][bj][m][n] = __builtin_amdgcn_mfma_f32_16x16x32_bf16(Bt[n][k], At[m][k], acc[ai][bj][m][n], 0, 0, 0); __builtin_amdgcn_s_setprio(0); } while (0)
; #define PG8_WAIT_V(n) asm volatile("s_waitcnt vmcnt(" #n ")" ::: "memory")
; #define PG8_WAIT_L(n) asm volatile("s_waitcnt lgkmcnt(" #n ")" ::: "memory")
; #define PG8_BAR __builtin_amdgcn_s_barrier()
; #define PG8_SCHED __builtin_amdgcn_sched_barrier(0)
; template <class Epi, class Sched, bool ALIGN_EPI = false, bool SP2 = false>
; __device__ __forceinline__ void gemm_phase(PG8_LAS unsigned char* lds, const Gemm g, const Sched& S, const Epi& E) {
;     ...
;             PG8_LDA(At, 1, 1); PG8_STAGE(PG8_SB(1, 0), b3, voffB); PG8_STAGE(PG8_SB(1, 1), b3 + hstep, voffB); PG8_STAGE(PG8_SA(1, 0), a3, voffA);
;             PG8_WAIT_V(8); PG8_WAIT_L(0); PG8_BAR; PG8_MMA(1, 0, At, B0); PG8_MMA(1, 1, At, B1); PG8_BAR; PG8_SCHED;
	s_add_i32 s6, s73, s27
	v_lshl_add_u64 v[148:149], v[148:149], 0, s[36:37]
	s_mov_b32 m0, s6
	ds_read_b128 v[200:203], v166 offset:49152
	ds_read_b128 v[204:207], v166 offset:50176
	ds_read_b128 v[208:211], v166 offset:51200
	ds_read_b128 v[212:215], v166 offset:52224
	ds_read_b128 v[216:219], v166 offset:53248
	ds_read_b128 v[220:223], v166 offset:54272
	ds_read_b128 v[224:227], v166 offset:55296
	ds_read_b128 v[228:231], v166 offset:56320
	global_load_lds_dwordx4 v[148:149], off
	s_add_i32 m0, s6, 0x2000
	s_add_u32 s6, s58, 0x40080
	v_lshl_add_u64 v[148:149], v[232:233], 0, s[36:37]
	s_addc_u32 s7, s59, 0
	s_add_i32 s58, s79, s27
	global_load_lds_dwordx4 v[148:149], off
	v_lshl_add_u64 v[148:149], s[6:7], 0, v[132:133]
	s_mov_b32 m0, s58
	s_nop 0
	global_load_lds_dwordx4 v[148:149], off
	v_lshl_add_u64 v[148:149], s[6:7], 0, v[128:129]
	s_add_i32 m0, s58, 0x2000
	s_nop 0
	global_load_lds_dwordx4 v[148:149], off
	v_lshl_add_u64 v[148:149], v[234:235], 0, s[36:37]
	s_mov_b32 m0, s44
	s_nop 0
	global_load_lds_dwordx4 v[148:149], off
	v_lshl_add_u64 v[148:149], v[236:237], 0, s[36:37]
	s_mov_b32 m0, s45
	s_nop 0
	global_load_lds_dwordx4 v[148:149], off
	s_waitcnt vmcnt(8)
	s_waitcnt lgkmcnt(0)
	s_barrier
	s_waitcnt lgkmcnt(0)
	v_mfma_f32_16x16x32_bf16 v[60:63], v[144:147], v[200:203], v[60:63]
	v_mfma_f32_16x16x32_bf16 v[52:55], v[172:175], v[200:203], v[52:55]
	v_mfma_f32_16x16x32_bf16 v[44:47], v[144:147], v[208:211], v[44:47]
	v_mfma_f32_16x16x32_bf16 v[36:39], v[172:175], v[208:211], v[36:39]
	v_mfma_f32_16x16x32_bf16 v[28:31], v[144:147], v[216:219], v[28:31]
	v_mfma_f32_16x16x32_bf16 v[20:23], v[172:175], v[216:219], v[20:23]
	v_mfma_f32_16x16x32_bf16 v[12:15], v[144:147], v[224:227], v[12:15]
	v_mfma_f32_16x16x32_bf16 v[4:7], v[172:175], v[224:227], v[4:7]
	v_mfma_f32_16x16x32_bf16 v[60:63], v[168:171], v[204:207], v[60:63]
	v_mfma_f32_16x16x32_bf16 v[52:55], v[176:179], v[204:207], v[52:55]
	v_mfma_f32_16x16x32_bf16 v[44:47], v[168:171], v[212:215], v[44:47]
	v_mfma_f32_16x16x32_bf16 v[36:39], v[176:179], v[212:215], v[36:39]
	v_mfma_f32_16x16x32_bf16 v[28:31], v[168:171], v[220:223], v[28:31]
	v_mfma_f32_16x16x32_bf16 v[20:23], v[176:179], v[220:223], v[20:23]
	v_mfma_f32_16x16x32_bf16 v[12:15], v[168:171], v[228:231], v[12:15]
	v_mfma_f32_16x16x32_bf16 v[4:7], v[176:179], v[228:231], v[4:7]
	v_mfma_f32_16x16x32_bf16 v[56:59], v[180:183], v[200:203], v[56:59]
	v_mfma_f32_16x16x32_bf16 v[48:51], v[188:191], v[200:203], v[48:51]
	v_mfma_f32_16x16x32_bf16 v[40:43], v[180:183], v[208:211], v[40:43]
	v_mfma_f32_16x16x32_bf16 v[32:35], v[188:191], v[208:211], v[32:35]
	v_mfma_f32_16x16x32_bf16 v[24:27], v[180:183], v[216:219], v[24:27]
	v_mfma_f32_16x16x32_bf16 v[16:19], v[188:191], v[216:219], v[16:19]
	v_mfma_f32_16x16x32_bf16 v[8:11], v[180:183], v[224:227], v[8:11]
	v_mfma_f32_16x16x32_bf16 v[0:3], v[188:191], v[224:227], v[0:3]
	v_mfma_f32_16x16x32_bf16 v[56:59], v[184:187], v[204:207], v[56:59]
	v_mfma_f32_16x16x32_bf16 v[48:51], v[196:199], v[204:207], v[48:51]
	v_mfma_f32_16x16x32_bf16 v[40:43], v[184:187], v[212:215], v[40:43]
	v_mfma_f32_16x16x32_bf16 v[32:35], v[196:199], v[212:215], v[32:35]
	v_mfma_f32_16x16x32_bf16 v[24:27], v[184:187], v[220:223], v[24:27]
	v_mfma_f32_16x16x32_bf16 v[16:19], v[196:199], v[220:223], v[16:19]
	v_mfma_f32_16x16x32_bf16 v[8:11], v[184:187], v[228:231], v[8:11]
	v_mfma_f32_16x16x32_bf16 v[0:3], v[196:199], v[228:231], v[0:3]
	s_barrier
	s_add_i32 s72, s72, 2
	s_add_u32 s56, s56, 0x100
	s_addc_u32 s57, s57, 0
	s_add_u32 s78, s78, 0x100
	s_addc_u32 s33, s33, 0
	s_cmp_gt_u32 s72, 13
	s_cbranch_scc0 .LBB0_901
	s_and_b64 vcc, exec, s[38:39]
	s_cbranch_vccz .LBB0_904
	s_barrier

; #define PG8_STAGE(bufoff, gbase, voff) do { _Pragma("unroll") for (int _i = 0; _i < 2; ++_i) \
;         __builtin_amdgcn_global_load_lds((const unsigned*)((const char*)(gbase) + (voff)[_i]), (PG8_LAS unsigned*)(lds + (bufoff) + ldsw + _i * 8192), 16, 0, 0); } while (0)
; #define PG8_LDA(dst, b, h) do { _Pragma("unroll") for (int m = 0; m < 4; ++m) _Pragma("unroll") for (int k = 0; k < 2; ++k) dst[m][k] = *(const PG8_LAS bf16x8*)(lds + PG8_SA(b, h) + aoff + m * 2048 + k * 1024); } while (0)
; #define PG8_LDB(dst, b, h) do { _Pragma("unroll") for (int n = 0; n < 2; ++n) _Pragma("unroll") for (int k = 0; k < 2; ++k) dst[n][k] = *(const PG8_LAS bf16x8*)(lds + PG8_SB(b, h) + boff + n * 2048 + k * 1024); } while (0)
; #define PG8_MMA(ai, bj, At, Bt) do { __builtin_amdgcn_s_setprio(1); _Pragma("unroll") for (int m = 0; m < 4; ++m) _Pragma("unroll") for (int n = 0; n < 2; ++n) _Pragma("unroll") for (int k = 0; k < 2; ++k) \
;         acc[ai][bj][m][n] = __builtin_amdgcn_mfma_f32_16x16x32_bf16(Bt[n][k], At[m][k], acc[ai][bj][m][n], 0, 0, 0); __builtin_amdgcn_s_setprio(0); } while (0)
; #define PG8_WAIT_V(n) asm volatile("s_waitcnt vmcnt(" #n ")" ::: "memory")
; #define PG8_WAIT_L(n) asm volatile("s_waitcnt lgkmcnt(" #n ")" ::: "memory")
; #define PG8_BAR __builtin_amdgcn_s_barrier()
; #define PG8_SCHED __builtin_amdgcn_sched_barrier(0)
; template <class Epi, class Sched, bool ALIGN_EPI = false, bool SP2 = false>
; __device__ __forceinline__ void gemm_phase(PG8_LAS unsigned char* lds, const Gemm g, const Sched& S, const Epi& E) {
;     ...
;             const bool last = (t == nt - 2);
;             const char* a1 = cA + (size_t)(t + 1) * kstep;
;             const char* a2 = last ? nA : cA + (size_t)(t + 2) * kstep; const char* b2 = last ? nB : cB + (size_t)(t + 2) * kstep;
;             const char* a3 = a2 + kstep; const char* b3 = b2 + kstep;
;             if (last && has_next) S.a_ready(nxt);
;             if constexpr (SP2) {
;             PG8_LDB(B0, 0, 0); PG8_LDB(B1, 0, 1); PG8_SCHED; PG8_LDA(At, 0, 0); PG8_STAGE(PG8_SA(1, 1), a1 + hstep, voffA);
;             PG8_WAIT_V(8); PG8_WAIT_L(0); PG8_BAR; PG8_MMA(0, 0, At, B0); PG8_MMA(0, 1, At, B1); PG8_BAR; PG8_SCHED;
;             PG8_LDA(At, 0, 1); PG8_STAGE(PG8_SB(0, 0), b2, voffB); PG8_STAGE(PG8_SB(0, 1), b2 + hstep, voffB); PG8_STAGE(PG8_SA(0, 0), a2, voffA);
.LBB0_1014:
	ds_read_b128 v[144:147], v158
	ds_read_b128 v[168:171], v158 offset:1024
	ds_read_b128 v[172:175], v158 offset:2048
	ds_read_b128 v[176:179], v158 offset:3072
	ds_read_b128 v[180:183], v159
	ds_read_b128 v[184:187], v159 offset:1024
	ds_read_b128 v[188:191], v159 offset:2048
	ds_read_b128 v[196:199], v159 offset:3072
	s_add_u32 s58, s56, 0x100
	s_addc_u32 s59, s57, 0
	s_cmp_eq_u32 s72, 40
	s_cselect_b32 s79, s51, s59
	s_cselect_b32 s78, s50, s58
	s_cselect_b32 s61, s55, s80
	s_cselect_b32 s60, s54, s33
	v_lshl_add_u64 v[148:149], s[56:57], 0, v[136:137]
	s_add_i32 m0, s45, 0xc000
	ds_read_b128 v[200:203], v163
	ds_read_b128 v[204:207], v163 offset:1024
	ds_read_b128 v[208:211], v163 offset:2048
	ds_read_b128 v[212:215], v163 offset:3072
	ds_read_b128 v[216:219], v163 offset:4096
	ds_read_b128 v[220:223], v163 offset:5120
	ds_read_b128 v[224:227], v163 offset:6144
	ds_read_b128 v[228:231], v163 offset:7168
	global_load_lds_dwordx4 v[148:149], off
	v_lshl_add_u64 v[148:149], s[56:57], 0, v[138:139]
	s_add_i32 m0, s45, 0xe000
	s_nop 0
	global_load_lds_dwordx4 v[148:149], off
	s_waitcnt vmcnt(8)
	s_waitcnt lgkmcnt(0)
	s_barrier
	s_waitcnt lgkmcnt(0)
	v_mfma_f32_16x16x32_bf16 v[124:127], v[144:147], v[200:203], v[124:127]
	v_mfma_f32_16x16x32_bf16 v[120:123], v[172:175], v[200:203], v[120:123]
	v_mfma_f32_16x16x32_bf16 v[108:111], v[144:147], v[208:211], v[108:111]
	v_mfma_f32_16x16x32_bf16 v[104:107], v[172:175], v[208:211], v[104:107]
	v_mfma_f32_16x16x32_bf16 v[92:95], v[144:147], v[216:219], v[92:95]
	v_mfma_f32_16x16x32_bf16 v[88:91], v[172:175], v[216:219], v[88:91]
	v_mfma_f32_16x16x32_bf16 v[76:79], v[144:147], v[224:227], v[76:79]
	v_mfma_f32_16x16x32_bf16 v[72:75], v[172:175], v[224:227], v[72:75]
	v_mfma_f32_16x16x32_bf16 v[124:127], v[168:171], v[204:207], v[124:127]
	v_mfma_f32_16x16x32_bf16 v[120:123], v[176:179], v[204:207], v[120:123]
	v_mfma_f32_16x16x32_bf16 v[108:111], v[168:171], v[212:215], v[108:111]
	v_mfma_f32_16x16x32_bf16 v[104:107], v[176:179], v[212:215], v[104:107]
	v_mfma_f32_16x16x32_bf16 v[92:95], v[168:171], v[220:223], v[92:95]
	v_mfma_f32_16x16x32_bf16 v[88:91], v[176:179], v[220:223], v[88:91]
	v_mfma_f32_16x16x32_bf16 v[76:79], v[168:171], v[228:231], v[76:79]
	v_mfma_f32_16x16x32_bf16 v[72:75], v[176:179], v[228:231], v[72:75]
	v_mfma_f32_16x16x32_bf16 v[116:119], v[180:183], v[200:203], v[116:119]
	v_mfma_f32_16x16x32_bf16 v[112:115], v[188:191], v[200:203], v[112:115]
	v_mfma_f32_16x16x32_bf16 v[100:103], v[180:183], v[208:211], v[100:103]
	v_mfma_f32_16x16x32_bf16 v[96:99], v[188:191], v[208:211], v[96:99]
	v_mfma_f32_16x16x32_bf16 v[84:87], v[180:183], v[216:219], v[84:87]
	v_mfma_f32_16x16x32_bf16 v[80:83], v[188:191], v[216:219], v[80:83]
	v_mfma_f32_16x16x32_bf16 v[68:71], v[180:183], v[224:227], v[68:71]
	v_mfma_f32_16x16x32_bf16 v[64:67], v[188:191], v[224:227], v[64:67]
	v_mfma_f32_16x16x32_bf16 v[116:119], v[184:187], v[204:207], v[116:119]
	v_mfma_f32_16x16x32_bf16 v[112:115], v[196:199], v[204:207], v[112:115]
	v_mfma_f32_16x16x32_bf16 v[100:103], v[184:187], v[212:215], v[100:103]
	v_mfma_f32_16x16x32_bf16 v[96:99], v[196:199], v[212:215], v[96:99]
	v_mfma_f32_16x16x32_bf16 v[84:87], v[184:187], v[220:223], v[84:87]
	v_mfma_f32_16x16x32_bf16 v[80:83], v[196:199], v[220:223], v[80:83]
	v_mfma_f32_16x16x32_bf16 v[68:71], v[184:187], v[228:231], v[68:71]
	v_mfma_f32_16x16x32_bf16 v[64:67], v[196:199], v[228:231], v[64:67]
	s_barrier
	s_add_i32 s6, s26, s44
	v_lshl_add_u64 v[148:149], s[60:61], 0, v[130:131]
	s_mov_b32 m0, s6
	ds_read_b128 v[200:203], v163 offset:16384
	ds_read_b128 v[204:207], v163 offset:17408
	ds_read_b128 v[208:211], v163 offset:18432
	ds_read_b128 v[212:215], v163 offset:19456
	ds_read_b128 v[216:219], v163 offset:20480
	ds_read_b128 v[220:223], v163 offset:21504
	ds_read_b128 v[224:227], v163 offset:22528
	ds_read_b128 v[228:231], v163 offset:23552
	global_load_lds_dwordx4 v[148:149], off
	s_add_i32 m0, s6, 0x2000
	s_add_u32 s6, s60, 0xb0000
	v_lshl_add_u64 v[232:233], s[60:61], 0, v[134:135]
	s_addc_u32 s7, s61, 0
	s_add_i32 s56, s74, s44
	global_load_lds_dwordx4 v[232:233], off
	v_lshl_add_u64 v[234:235], s[6:7], 0, v[130:131]
	s_mov_b32 m0, s56
	v_lshl_add_u64 v[236:237], s[78:79], 0, v[132:133]
	global_load_lds_dwordx4 v[234:235], off
	v_lshl_add_u64 v[234:235], s[6:7], 0, v[134:135]
	s_add_i32 m0, s56, 0x2000
	s_nop 0
	global_load_lds_dwordx4 v[234:235], off
	v_lshl_add_u64 v[234:235], s[78:79], 0, v[128:129]
	s_mov_b32 m0, s45
	s_nop 0
	global_load_lds_dwordx4 v[234:235], off
	s_mov_b32 m0, s67
	s_nop 0
	global_load_lds_dwordx4 v[236:237], off
	s_waitcnt vmcnt(8)
	s_waitcnt lgkmcnt(0)
	s_barrier
; #define PG8_STAGE(bufoff, gbase, voff) do { _Pragma("unroll") for (int _i = 0; _i < 2; ++_i) \
;         __builtin_amdgcn_global_load_lds((const unsigned*)((const char*)(gbase) + (voff)[_i]), (PG8_LAS unsigned*)(lds + (bufoff) + ldsw + _i * 8192), 16, 0, 0); } while (0)
; #define PG8_LDA(dst, b, h) do { _Pragma("unroll") for (int m = 0; m < 4; ++m) _Pragma("unroll") for (int k = 0; k < 2; ++k) dst[m][k] = *(const PG8_LAS bf16x8*)(lds + PG8_SA(b, h) + aoff + m * 2048 + k * 1024); } while (0)
; #define PG8_LDB(dst, b, h) do { _Pragma("unroll") for (int n = 0; n < 2; ++n) _Pragma("unroll") for (int k = 0; k < 2; ++k) dst[n][k] = *(const PG8_LAS bf16x8*)(lds + PG8_SB(b, h) + boff + n * 2048 + k * 1024); } while (0)
; #define PG8_MMA(ai, bj, At, Bt) do { __builtin_amdgcn_s_setprio(1); _Pragma("unroll") for (int m = 0; m < 4; ++m) _Pragma("unroll") for (int n = 0; n < 2; ++n) _Pragma("unroll") for (int k = 0; k < 2; ++k) \
;         acc[ai][bj][m][n] = __builtin_amdgcn_mfma_f32_16x16x32_bf16(Bt[n][k], At[m][k], acc[ai][bj][m][n], 0, 0, 0); __builtin_amdgcn_s_setprio(0); } while (0)
; #define PG8_WAIT_V(n) asm volatile("s_waitcnt vmcnt(" #n ")" ::: "memory")
; #define PG8_WAIT_L(n) asm volatile("s_waitcnt lgkmcnt(" #n ")" ::: "memory")
; #define PG8_BAR __builtin_amdgcn_s_barrier()
; #define PG8_SCHED __builtin_amdgcn_sched_barrier(0)
; template <class Epi, class Sched, bool ALIGN_EPI = false, bool SP2 = false>
; __device__ __forceinline__ void gemm_phase(PG8_LAS unsigned char* lds, const Gemm g, const Sched& S, const Epi& E) {
;     ...
;             PG8_WAIT_V(8); PG8_WAIT_L(0); PG8_BAR; PG8_MMA(1, 0, At, B0); PG8_MMA(1, 1, At, B1); PG8_BAR; PG8_SCHED;
;             PG8_LDB(B0, 1, 0); PG8_LDB(B1, 1, 1); PG8_SCHED; PG8_LDA(At, 1, 0); PG8_STAGE(PG8_SA(0, 1), a2 + hstep, voffA);
;             PG8_WAIT_V(8); PG8_WAIT_L(0); PG8_BAR; PG8_MMA(0, 0, At, B0); PG8_MMA(0, 1, At, B1); PG8_BAR; PG8_SCHED;
	s_waitcnt lgkmcnt(0)
	v_mfma_f32_16x16x32_bf16 v[60:63], v[144:147], v[200:203], v[60:63]
	v_mfma_f32_16x16x32_bf16 v[56:59], v[172:175], v[200:203], v[56:59]
	v_mfma_f32_16x16x32_bf16 v[44:47], v[144:147], v[208:211], v[44:47]
	v_mfma_f32_16x16x32_bf16 v[40:43], v[172:175], v[208:211], v[40:43]
	v_mfma_f32_16x16x32_bf16 v[28:31], v[144:147], v[216:219], v[28:31]
	v_mfma_f32_16x16x32_bf16 v[24:27], v[172:175], v[216:219], v[24:27]
	v_mfma_f32_16x16x32_bf16 v[12:15], v[144:147], v[224:227], v[12:15]
	v_mfma_f32_16x16x32_bf16 v[8:11], v[172:175], v[224:227], v[8:11]
	v_mfma_f32_16x16x32_bf16 v[60:63], v[168:171], v[204:207], v[60:63]
	v_mfma_f32_16x16x32_bf16 v[56:59], v[176:179], v[204:207], v[56:59]
	v_mfma_f32_16x16x32_bf16 v[44:47], v[168:171], v[212:215], v[44:47]
	v_mfma_f32_16x16x32_bf16 v[40:43], v[176:179], v[212:215], v[40:43]
	v_mfma_f32_16x16x32_bf16 v[28:31], v[168:171], v[220:223], v[28:31]
	v_mfma_f32_16x16x32_bf16 v[24:27], v[176:179], v[220:223], v[24:27]
	v_mfma_f32_16x16x32_bf16 v[12:15], v[168:171], v[228:231], v[12:15]
	v_mfma_f32_16x16x32_bf16 v[8:11], v[176:179], v[228:231], v[8:11]
	v_mfma_f32_16x16x32_bf16 v[52:55], v[180:183], v[200:203], v[52:55]
	v_mfma_f32_16x16x32_bf16 v[48:51], v[188:191], v[200:203], v[48:51]
	v_mfma_f32_16x16x32_bf16 v[36:39], v[180:183], v[208:211], v[36:39]
	v_mfma_f32_16x16x32_bf16 v[32:35], v[188:191], v[208:211], v[32:35]
	v_mfma_f32_16x16x32_bf16 v[20:23], v[180:183], v[216:219], v[20:23]
	v_mfma_f32_16x16x32_bf16 v[16:19], v[188:191], v[216:219], v[16:19]
	v_mfma_f32_16x16x32_bf16 v[4:7], v[180:183], v[224:227], v[4:7]
	v_mfma_f32_16x16x32_bf16 v[0:3], v[188:191], v[224:227], v[0:3]
	v_mfma_f32_16x16x32_bf16 v[52:55], v[184:187], v[204:207], v[52:55]
	v_mfma_f32_16x16x32_bf16 v[48:51], v[196:199], v[204:207], v[48:51]
	v_mfma_f32_16x16x32_bf16 v[36:39], v[184:187], v[212:215], v[36:39]
	v_mfma_f32_16x16x32_bf16 v[32:35], v[196:199], v[212:215], v[32:35]
	v_mfma_f32_16x16x32_bf16 v[20:23], v[184:187], v[220:223], v[20:23]
	v_mfma_f32_16x16x32_bf16 v[16:19], v[196:199], v[220:223], v[16:19]
	v_mfma_f32_16x16x32_bf16 v[4:7], v[184:187], v[228:231], v[4:7]
	v_mfma_f32_16x16x32_bf16 v[0:3], v[196:199], v[228:231], v[0:3]
	s_barrier
	s_add_i32 s56, 0, 0x18000
	v_add_u32_e32 v167, s56, v156
	s_add_i32 s57, 0, 0x1c000
	ds_read_b128 v[144:147], v167
	ds_read_b128 v[168:171], v167 offset:1024
	ds_read_b128 v[172:175], v167 offset:2048
	ds_read_b128 v[176:179], v167 offset:3072
	v_add_u32_e32 v167, s57, v156
	ds_read_b128 v[180:183], v167
	ds_read_b128 v[184:187], v167 offset:1024
	ds_read_b128 v[188:191], v167 offset:2048
	ds_read_b128 v[196:199], v167 offset:3072
	s_add_u32 s6, s78, 0xb0000
	s_addc_u32 s7, s79, 0
	s_mov_b32 m0, s76
	v_lshl_add_u64 v[238:239], s[6:7], 0, v[128:129]
	ds_read_b128 v[200:203], v163 offset:32768
	ds_read_b128 v[204:207], v163 offset:33792
	ds_read_b128 v[208:211], v163 offset:34816
	ds_read_b128 v[212:215], v163 offset:35840
	ds_read_b128 v[216:219], v163 offset:36864
	ds_read_b128 v[220:223], v163 offset:37888
	ds_read_b128 v[224:227], v163 offset:38912
	ds_read_b128 v[228:231], v163 offset:39936
	global_load_lds_dwordx4 v[238:239], off
	v_lshl_add_u64 v[238:239], s[6:7], 0, v[132:133]
	s_mov_b32 m0, s77
	s_nop 0
	global_load_lds_dwordx4 v[238:239], off
	s_waitcnt vmcnt(8)
	s_waitcnt lgkmcnt(0)
	s_barrier
	s_waitcnt lgkmcnt(0)
	v_mfma_f32_16x16x32_bf16 v[124:127], v[144:147], v[200:203], v[124:127]
	v_mfma_f32_16x16x32_bf16 v[120:123], v[172:175], v[200:203], v[120:123]
	v_mfma_f32_16x16x32_bf16 v[108:111], v[144:147], v[208:211], v[108:111]
	v_mfma_f32_16x16x32_bf16 v[104:107], v[172:175], v[208:211], v[104:107]
	v_mfma_f32_16x16x32_bf16 v[92:95], v[144:147], v[216:219], v[92:95]
	v_mfma_f32_16x16x32_bf16 v[88:91], v[172:175], v[216:219], v[88:91]
	v_mfma_f32_16x16x32_bf16 v[76:79], v[144:147], v[224:227], v[76:79]
	v_mfma_f32_16x16x32_bf16 v[72:75], v[172:175], v[224:227], v[72:75]
	v_mfma_f32_16x16x32_bf16 v[124:127], v[168:171], v[204:207], v[124:127]
	v_mfma_f32_16x16x32_bf16 v[120:123], v[176:179], v[204:207], v[120:123]
	v_mfma_f32_16x16x32_bf16 v[108:111], v[168:171], v[212:215], v[108:111]
	v_mfma_f32_16x16x32_bf16 v[104:107], v[176:179], v[212:215], v[104:107]
	v_mfma_f32_16x16x32_bf16 v[92:95], v[168:171], v[220:223], v[92:95]
	v_mfma_f32_16x16x32_bf16 v[88:91], v[176:179], v[220:223], v[88:91]
	v_mfma_f32_16x16x32_bf16 v[76:79], v[168:171], v[228:231], v[76:79]
	v_mfma_f32_16x16x32_bf16 v[72:75], v[176:179], v[228:231], v[72:75]
	v_mfma_f32_16x16x32_bf16 v[116:119], v[180:183], v[200:203], v[116:119]
	v_mfma_f32_16x16x32_bf16 v[112:115], v[188:191], v[200:203], v[112:115]
	v_mfma_f32_16x16x32_bf16 v[100:103], v[180:183], v[208:211], v[100:103]
	v_mfma_f32_16x16x32_bf16 v[96:99], v[188:191], v[208:211], v[96:99]
	v_mfma_f32_16x16x32_bf16 v[84:87], v[180:183], v[216:219], v[84:87]
	v_mfma_f32_16x16x32_bf16 v[80:83], v[188:191], v[216:219], v[80:83]
	v_mfma_f32_16x16x32_bf16 v[68:71], v[180:183], v[224:227], v[68:71]
	v_mfma_f32_16x16x32_bf16 v[64:67], v[188:191], v[224:227], v[64:67]
	v_mfma_f32_16x16x32_bf16 v[116:119], v[184:187], v[204:207], v[116:119]
	v_mfma_f32_16x16x32_bf16 v[112:115], v[196:199], v[204:207], v[112:115]
	v_mfma_f32_16x16x32_bf16 v[100:103], v[184:187], v[212:215], v[100:103]
	v_mfma_f32_16x16x32_bf16 v[96:99], v[196:199], v[212:215], v[96:99]
	v_mfma_f32_16x16x32_bf16 v[84:87], v[184:187], v[220:223], v[84:87]
	v_mfma_f32_16x16x32_bf16 v[80:83], v[196:199], v[220:223], v[80:83]
	v_mfma_f32_16x16x32_bf16 v[68:71], v[184:187], v[228:231], v[68:71]
	v_mfma_f32_16x16x32_bf16 v[64:67], v[196:199], v[228:231], v[64:67]
	s_barrier
; #define PG8_STAGE(bufoff, gbase, voff) do { _Pragma("unroll") for (int _i = 0; _i < 2; ++_i) \
;         __builtin_amdgcn_global_load_lds((const unsigned*)((const char*)(gbase) + (voff)[_i]), (PG8_LAS unsigned*)(lds + (bufoff) + ldsw + _i * 8192), 16, 0, 0); } while (0)
; #define PG8_LDA(dst, b, h) do { _Pragma("unroll") for (int m = 0; m < 4; ++m) _Pragma("unroll") for (int k = 0; k < 2; ++k) dst[m][k] = *(const PG8_LAS bf16x8*)(lds + PG8_SA(b, h) + aoff + m * 2048 + k * 1024); } while (0)
; #define PG8_MMA(ai, bj, At, Bt) do { __builtin_amdgcn_s_setprio(1); _Pragma("unroll") for (int m = 0; m < 4; ++m) _Pragma("unroll") for (int n = 0; n < 2; ++n) _Pragma("unroll") for (int k = 0; k < 2; ++k) \
;         acc[ai][bj][m][n] = __builtin_amdgcn_mfma_f32_16x16x32_bf16(Bt[n][k], At[m][k], acc[ai][bj][m][n], 0, 0, 0); __builtin_amdgcn_s_setprio(0); } while (0)
; #define PG8_WAIT_V(n) asm volatile("s_waitcnt vmcnt(" #n ")" ::: "memory")
; #define PG8_WAIT_L(n) asm volatile("s_waitcnt lgkmcnt(" #n ")" ::: "memory")
; #define PG8_BAR __builtin_amdgcn_s_barrier()
; #define PG8_SCHED __builtin_amdgcn_sched_barrier(0)
; template <class Epi, class Sched, bool ALIGN_EPI = false, bool SP2 = false>
; __device__ __forceinline__ void gemm_phase(PG8_LAS unsigned char* lds, const Gemm g, const Sched& S, const Epi& E) {
;     ...
;             PG8_LDA(At, 1, 1); PG8_STAGE(PG8_SB(1, 0), b3, voffB); PG8_STAGE(PG8_SB(1, 1), b3 + hstep, voffB); PG8_STAGE(PG8_SA(1, 0), a3, voffA);
;             PG8_WAIT_V(8); PG8_WAIT_L(0); PG8_BAR; PG8_MMA(1, 0, At, B0); PG8_MMA(1, 1, At, B1); PG8_BAR; PG8_SCHED;
	s_add_i32 s6, s56, s44
	v_lshl_add_u64 v[148:149], v[148:149], 0, s[40:41]
	s_mov_b32 m0, s6
	ds_read_b128 v[200:203], v163 offset:49152
	ds_read_b128 v[204:207], v163 offset:50176
	ds_read_b128 v[208:211], v163 offset:51200
	ds_read_b128 v[212:215], v163 offset:52224
	ds_read_b128 v[216:219], v163 offset:53248
	ds_read_b128 v[220:223], v163 offset:54272
	ds_read_b128 v[224:227], v163 offset:55296
	ds_read_b128 v[228:231], v163 offset:56320
	global_load_lds_dwordx4 v[148:149], off
	s_add_i32 m0, s6, 0x2000
	s_add_u32 s6, s60, 0xb0080
	v_lshl_add_u64 v[148:149], v[232:233], 0, s[40:41]
	s_addc_u32 s7, s61, 0
	s_add_i32 s56, s57, s44
	global_load_lds_dwordx4 v[148:149], off
	v_lshl_add_u64 v[148:149], s[6:7], 0, v[130:131]
	s_mov_b32 m0, s56
	s_nop 0
	global_load_lds_dwordx4 v[148:149], off
	v_lshl_add_u64 v[148:149], s[6:7], 0, v[134:135]
	s_add_i32 m0, s56, 0x2000
	s_nop 0
	global_load_lds_dwordx4 v[148:149], off
	v_lshl_add_u64 v[148:149], v[234:235], 0, s[40:41]
	s_mov_b32 m0, s31
	s_nop 0
	global_load_lds_dwordx4 v[148:149], off
	v_lshl_add_u64 v[148:149], v[236:237], 0, s[40:41]
	s_mov_b32 m0, s4
	s_nop 0
	global_load_lds_dwordx4 v[148:149], off
	s_waitcnt vmcnt(8)
	s_waitcnt lgkmcnt(0)
	s_barrier
	s_waitcnt lgkmcnt(0)
	v_mfma_f32_16x16x32_bf16 v[60:63], v[144:147], v[200:203], v[60:63]
	v_mfma_f32_16x16x32_bf16 v[56:59], v[172:175], v[200:203], v[56:59]
	v_mfma_f32_16x16x32_bf16 v[44:47], v[144:147], v[208:211], v[44:47]
	v_mfma_f32_16x16x32_bf16 v[40:43], v[172:175], v[208:211], v[40:43]
	v_mfma_f32_16x16x32_bf16 v[28:31], v[144:147], v[216:219], v[28:31]
	v_mfma_f32_16x16x32_bf16 v[24:27], v[172:175], v[216:219], v[24:27]
	v_mfma_f32_16x16x32_bf16 v[12:15], v[144:147], v[224:227], v[12:15]
	v_mfma_f32_16x16x32_bf16 v[8:11], v[172:175], v[224:227], v[8:11]
	v_mfma_f32_16x16x32_bf16 v[60:63], v[168:171], v[204:207], v[60:63]
	v_mfma_f32_16x16x32_bf16 v[56:59], v[176:179], v[204:207], v[56:59]
	v_mfma_f32_16x16x32_bf16 v[44:47], v[168:171], v[212:215], v[44:47]
	v_mfma_f32_16x16x32_bf16 v[40:43], v[176:179], v[212:215], v[40:43]
	v_mfma_f32_16x16x32_bf16 v[28:31], v[168:171], v[220:223], v[28:31]
	v_mfma_f32_16x16x32_bf16 v[24:27], v[176:179], v[220:223], v[24:27]
	v_mfma_f32_16x16x32_bf16 v[12:15], v[168:171], v[228:231], v[12:15]
	v_mfma_f32_16x16x32_bf16 v[8:11], v[176:179], v[228:231], v[8:11]
	v_mfma_f32_16x16x32_bf16 v[52:55], v[180:183], v[200:203], v[52:55]
	v_mfma_f32_16x16x32_bf16 v[48:51], v[188:191], v[200:203], v[48:51]
	v_mfma_f32_16x16x32_bf16 v[36:39], v[180:183], v[208:211], v[36:39]
	v_mfma_f32_16x16x32_bf16 v[32:35], v[188:191], v[208:211], v[32:35]
	v_mfma_f32_16x16x32_bf16 v[20:23], v[180:183], v[216:219], v[20:23]
	v_mfma_f32_16x16x32_bf16 v[16:19], v[188:191], v[216:219], v[16:19]
	v_mfma_f32_16x16x32_bf16 v[4:7], v[180:183], v[224:227], v[4:7]
	v_mfma_f32_16x16x32_bf16 v[0:3], v[188:191], v[224:227], v[0:3]
	v_mfma_f32_16x16x32_bf16 v[52:55], v[184:187], v[204:207], v[52:55]
	v_mfma_f32_16x16x32_bf16 v[48:51], v[196:199], v[204:207], v[48:51]
	v_mfma_f32_16x16x32_bf16 v[36:39], v[184:187], v[212:215], v[36:39]
	v_mfma_f32_16x16x32_bf16 v[32:35], v[196:199], v[212:215], v[32:35]
	v_mfma_f32_16x16x32_bf16 v[20:23], v[184:187], v[220:223], v[20:23]
	v_mfma_f32_16x16x32_bf16 v[16:19], v[196:199], v[220:223], v[16:19]
	v_mfma_f32_16x16x32_bf16 v[4:7], v[184:187], v[228:231], v[4:7]
	v_mfma_f32_16x16x32_bf16 v[0:3], v[196:199], v[228:231], v[0:3]
	s_barrier
	s_add_i32 s72, s72, 2
	s_add_u32 s33, s33, 0x100
	s_addc_u32 s80, s80, 0
	s_cmp_gt_u32 s72, 41
	s_mov_b64 s[56:57], s[58:59]
	s_cbranch_scc0 .LBB0_1014
	s_and_b64 vcc, exec, s[52:53]
	s_cbranch_vccz .LBB0_1017
	s_barrier

; #define PG8_STAGE(bufoff, gbase, voff) do { _Pragma("unroll") for (int _i = 0; _i < 2; ++_i) \
;         __builtin_amdgcn_global_load_lds((const unsigned*)((const char*)(gbase) + (voff)[_i]), (PG8_LAS unsigned*)(lds + (bufoff) + ldsw + _i * 8192), 16, 0, 0); } while (0)
; #define PG8_LDA(dst, b, h) do { _Pragma("unroll") for (int m = 0; m < 4; ++m) _Pragma("unroll") for (int k = 0; k < 2; ++k) dst[m][k] = *(const PG8_LAS bf16x8*)(lds + PG8_SA(b, h) + aoff + m * 2048 + k * 1024); } while (0)
; #define PG8_LDB(dst, b, h) do { _Pragma("unroll") for (int n = 0; n < 2; ++n) _Pragma("unroll") for (int k = 0; k < 2; ++k) dst[n][k] = *(const PG8_LAS bf16x8*)(lds + PG8_SB(b, h) + boff + n * 2048 + k * 1024); } while (0)
; #define PG8_MMA(ai, bj, At, Bt) do { __builtin_amdgcn_s_setprio(1); _Pragma("unroll") for (int m = 0; m < 4; ++m) _Pragma("unroll") for (int n = 0; n < 2; ++n) _Pragma("unroll") for (int k = 0; k < 2; ++k) \
;         acc[ai][bj][m][n] = __builtin_amdgcn_mfma_f32_16x16x32_bf16(Bt[n][k], At[m][k], acc[ai][bj][m][n], 0, 0, 0); __builtin_amdgcn_s_setprio(0); } while (0)
; #define PG8_WAIT_V(n) asm volatile("s_waitcnt vmcnt(" #n ")" ::: "memory")
; #define PG8_WAIT_L(n) asm volatile("s_waitcnt lgkmcnt(" #n ")" ::: "memory")
; #define PG8_BAR __builtin_amdgcn_s_barrier()
; #define PG8_SCHED __builtin_amdgcn_sched_barrier(0)
; template <class Epi, class Sched, bool ALIGN_EPI = false, bool SP2 = false>
; __device__ __forceinline__ void gemm_phase(PG8_LAS unsigned char* lds, const Gemm g, const Sched& S, const Epi& E) {
;     ...
;             const bool last = (t == nt - 2);
;             const char* a1 = cA + (size_t)(t + 1) * kstep;
;             const char* a2 = last ? nA : cA + (size_t)(t + 2) * kstep; const char* b2 = last ? nB : cB + (size_t)(t + 2) * kstep;
;             const char* a3 = a2 + kstep; const char* b3 = b2 + kstep;
;             if (last && has_next) S.a_ready(nxt);
;             if constexpr (SP2) {
;             PG8_LDB(B0, 0, 0); PG8_LDB(B1, 0, 1); PG8_SCHED; PG8_LDA(At, 0, 0); PG8_STAGE(PG8_SA(1, 1), a1 + hstep, voffA);
;             PG8_WAIT_V(8); PG8_WAIT_L(0); PG8_BAR; PG8_MMA(0, 0, At, B0); PG8_MMA(0, 1, At, B1); PG8_BAR; PG8_SCHED;
;             PG8_LDA(At, 0, 1); PG8_STAGE(PG8_SB(0, 0), b2, voffB); PG8_STAGE(PG8_SB(0, 1), b2 + hstep, voffB); PG8_STAGE(PG8_SA(0, 0), a2, voffA);
.LBB0_1392:
	ds_read_b128 v[144:147], v157
	ds_read_b128 v[166:169], v157 offset:1024
	ds_read_b128 v[170:173], v157 offset:2048
	ds_read_b128 v[174:177], v157 offset:3072
	ds_read_b128 v[178:181], v158
	ds_read_b128 v[182:185], v158 offset:1024
	ds_read_b128 v[186:189], v158 offset:2048
	ds_read_b128 v[196:199], v158 offset:3072
	s_add_u32 s6, s58, 0xfffc0080
	s_addc_u32 s7, s59, -1
	s_cmp_eq_u32 s72, 12
	s_cselect_b32 s79, s51, s7
	s_cselect_b32 s78, s75, s6
	s_cselect_b32 s61, s49, s33
	s_cselect_b32 s60, s76, s77
	v_lshl_add_u64 v[190:191], s[58:59], 0, v[136:137]
	s_add_i32 m0, s30, 0xc000
	ds_read_b128 v[200:203], v159
	ds_read_b128 v[204:207], v159 offset:1024
	ds_read_b128 v[208:211], v159 offset:2048
	ds_read_b128 v[212:215], v159 offset:3072
	ds_read_b128 v[216:219], v159 offset:4096
	ds_read_b128 v[220:223], v159 offset:5120
	ds_read_b128 v[224:227], v159 offset:6144
	ds_read_b128 v[228:231], v159 offset:7168
	global_load_lds_dwordx4 v[190:191], off
	v_lshl_add_u64 v[190:191], s[58:59], 0, v[138:139]
	s_add_i32 m0, s30, 0xe000
	s_nop 0
	global_load_lds_dwordx4 v[190:191], off
	s_waitcnt vmcnt(8)
	s_waitcnt lgkmcnt(0)
	s_barrier
	s_waitcnt lgkmcnt(0)
	v_mfma_f32_16x16x32_bf16 v[124:127], v[144:147], v[200:203], v[124:127]
	v_mfma_f32_16x16x32_bf16 v[120:123], v[170:173], v[200:203], v[120:123]
	v_mfma_f32_16x16x32_bf16 v[112:115], v[144:147], v[208:211], v[112:115]
	v_mfma_f32_16x16x32_bf16 v[104:107], v[170:173], v[208:211], v[104:107]
	v_mfma_f32_16x16x32_bf16 v[96:99], v[144:147], v[216:219], v[96:99]
	v_mfma_f32_16x16x32_bf16 v[88:91], v[170:173], v[216:219], v[88:91]
	v_mfma_f32_16x16x32_bf16 v[80:83], v[144:147], v[224:227], v[80:83]
	v_mfma_f32_16x16x32_bf16 v[72:75], v[170:173], v[224:227], v[72:75]
	v_mfma_f32_16x16x32_bf16 v[124:127], v[166:169], v[204:207], v[124:127]
	v_mfma_f32_16x16x32_bf16 v[120:123], v[174:177], v[204:207], v[120:123]
	v_mfma_f32_16x16x32_bf16 v[112:115], v[166:169], v[212:215], v[112:115]
	v_mfma_f32_16x16x32_bf16 v[104:107], v[174:177], v[212:215], v[104:107]
	v_mfma_f32_16x16x32_bf16 v[96:99], v[166:169], v[220:223], v[96:99]
	v_mfma_f32_16x16x32_bf16 v[88:91], v[174:177], v[220:223], v[88:91]
	v_mfma_f32_16x16x32_bf16 v[80:83], v[166:169], v[228:231], v[80:83]
	v_mfma_f32_16x16x32_bf16 v[72:75], v[174:177], v[228:231], v[72:75]
	v_mfma_f32_16x16x32_bf16 v[116:119], v[178:181], v[200:203], v[116:119]
	v_mfma_f32_16x16x32_bf16 v[108:111], v[186:189], v[200:203], v[108:111]
	v_mfma_f32_16x16x32_bf16 v[100:103], v[178:181], v[208:211], v[100:103]
	v_mfma_f32_16x16x32_bf16 v[92:95], v[186:189], v[208:211], v[92:95]
	v_mfma_f32_16x16x32_bf16 v[84:87], v[178:181], v[216:219], v[84:87]
	v_mfma_f32_16x16x32_bf16 v[76:79], v[186:189], v[216:219], v[76:79]
	v_mfma_f32_16x16x32_bf16 v[68:71], v[178:181], v[224:227], v[68:71]
	v_mfma_f32_16x16x32_bf16 v[64:67], v[186:189], v[224:227], v[64:67]
	v_mfma_f32_16x16x32_bf16 v[116:119], v[182:185], v[204:207], v[116:119]
	v_mfma_f32_16x16x32_bf16 v[108:111], v[196:199], v[204:207], v[108:111]
	v_mfma_f32_16x16x32_bf16 v[100:103], v[182:185], v[212:215], v[100:103]
	v_mfma_f32_16x16x32_bf16 v[92:95], v[196:199], v[212:215], v[92:95]
	v_mfma_f32_16x16x32_bf16 v[84:87], v[182:185], v[220:223], v[84:87]
	v_mfma_f32_16x16x32_bf16 v[76:79], v[196:199], v[220:223], v[76:79]
	v_mfma_f32_16x16x32_bf16 v[68:71], v[182:185], v[228:231], v[68:71]
	v_mfma_f32_16x16x32_bf16 v[64:67], v[196:199], v[228:231], v[64:67]
	s_barrier
	s_add_i32 s6, s57, s27
	v_lshl_add_u64 v[190:191], s[60:61], 0, v[130:131]
	s_mov_b32 m0, s6
	ds_read_b128 v[200:203], v159 offset:16384
	ds_read_b128 v[204:207], v159 offset:17408
	ds_read_b128 v[208:211], v159 offset:18432
	ds_read_b128 v[212:215], v159 offset:19456
	ds_read_b128 v[216:219], v159 offset:20480
	ds_read_b128 v[220:223], v159 offset:21504
	ds_read_b128 v[224:227], v159 offset:22528
	ds_read_b128 v[228:231], v159 offset:23552
	global_load_lds_dwordx4 v[190:191], off
	s_add_i32 m0, s6, 0x2000
	s_add_u32 s6, s60, 0x40000
	v_lshl_add_u64 v[232:233], s[60:61], 0, v[134:135]
	s_addc_u32 s7, s61, 0
	s_add_i32 s73, s67, s27
	global_load_lds_dwordx4 v[232:233], off
	v_lshl_add_u64 v[234:235], s[6:7], 0, v[130:131]
	s_mov_b32 m0, s73
	v_lshl_add_u64 v[236:237], s[78:79], 0, v[132:133]
	global_load_lds_dwordx4 v[234:235], off
	v_lshl_add_u64 v[234:235], s[6:7], 0, v[134:135]
	s_add_i32 m0, s73, 0x2000
	s_nop 0
	global_load_lds_dwordx4 v[234:235], off
	v_lshl_add_u64 v[234:235], s[78:79], 0, v[128:129]
	s_mov_b32 m0, s30
	s_nop 0
	global_load_lds_dwordx4 v[234:235], off
	s_mov_b32 m0, s31
	s_nop 0
	global_load_lds_dwordx4 v[236:237], off
	s_waitcnt vmcnt(8)
	s_waitcnt lgkmcnt(0)
	s_barrier
; #define PG8_STAGE(bufoff, gbase, voff) do { _Pragma("unroll") for (int _i = 0; _i < 2; ++_i) \
;         __builtin_amdgcn_global_load_lds((const unsigned*)((const char*)(gbase) + (voff)[_i]), (PG8_LAS unsigned*)(lds + (bufoff) + ldsw + _i * 8192), 16, 0, 0); } while (0)
; #define PG8_LDA(dst, b, h) do { _Pragma("unroll") for (int m = 0; m < 4; ++m) _Pragma("unroll") for (int k = 0; k < 2; ++k) dst[m][k] = *(const PG8_LAS bf16x8*)(lds + PG8_SA(b, h) + aoff + m * 2048 + k * 1024); } while (0)
; #define PG8_LDB(dst, b, h) do { _Pragma("unroll") for (int n = 0; n < 2; ++n) _Pragma("unroll") for (int k = 0; k < 2; ++k) dst[n][k] = *(const PG8_LAS bf16x8*)(lds + PG8_SB(b, h) + boff + n * 2048 + k * 1024); } while (0)
; #define PG8_MMA(ai, bj, At, Bt) do { __builtin_amdgcn_s_setprio(1); _Pragma("unroll") for (int m = 0; m < 4; ++m) _Pragma("unroll") for (int n = 0; n < 2; ++n) _Pragma("unroll") for (int k = 0; k < 2; ++k) \
;         acc[ai][bj][m][n] = __builtin_amdgcn_mfma_f32_16x16x32_bf16(Bt[n][k], At[m][k], acc[ai][bj][m][n], 0, 0, 0); __builtin_amdgcn_s_setprio(0); } while (0)
; #define PG8_WAIT_V(n) asm volatile("s_waitcnt vmcnt(" #n ")" ::: "memory")
; #define PG8_WAIT_L(n) asm volatile("s_waitcnt lgkmcnt(" #n ")" ::: "memory")
; #define PG8_BAR __builtin_amdgcn_s_barrier()
; #define PG8_SCHED __builtin_amdgcn_sched_barrier(0)
; template <class Epi, class Sched, bool ALIGN_EPI = false, bool SP2 = false>
; __device__ __forceinline__ void gemm_phase(PG8_LAS unsigned char* lds, const Gemm g, const Sched& S, const Epi& E) {
;     ...
;             PG8_WAIT_V(8); PG8_WAIT_L(0); PG8_BAR; PG8_MMA(1, 0, At, B0); PG8_MMA(1, 1, At, B1); PG8_BAR; PG8_SCHED;
;             PG8_LDB(B0, 1, 0); PG8_LDB(B1, 1, 1); PG8_SCHED; PG8_LDA(At, 1, 0); PG8_STAGE(PG8_SA(0, 1), a2 + hstep, voffA);
;             PG8_WAIT_V(8); PG8_WAIT_L(0); PG8_BAR; PG8_MMA(0, 0, At, B0); PG8_MMA(0, 1, At, B1); PG8_BAR; PG8_SCHED;
	s_waitcnt lgkmcnt(0)
	v_mfma_f32_16x16x32_bf16 v[60:63], v[144:147], v[200:203], v[60:63]
	v_mfma_f32_16x16x32_bf16 v[56:59], v[170:173], v[200:203], v[56:59]
	v_mfma_f32_16x16x32_bf16 v[52:55], v[144:147], v[208:211], v[52:55]
	v_mfma_f32_16x16x32_bf16 v[40:43], v[170:173], v[208:211], v[40:43]
	v_mfma_f32_16x16x32_bf16 v[36:39], v[144:147], v[216:219], v[36:39]
	v_mfma_f32_16x16x32_bf16 v[24:27], v[170:173], v[216:219], v[24:27]
	v_mfma_f32_16x16x32_bf16 v[20:23], v[144:147], v[224:227], v[20:23]
	v_mfma_f32_16x16x32_bf16 v[8:11], v[170:173], v[224:227], v[8:11]
	v_mfma_f32_16x16x32_bf16 v[60:63], v[166:169], v[204:207], v[60:63]
	v_mfma_f32_16x16x32_bf16 v[56:59], v[174:177], v[204:207], v[56:59]
	v_mfma_f32_16x16x32_bf16 v[52:55], v[166:169], v[212:215], v[52:55]
	v_mfma_f32_16x16x32_bf16 v[40:43], v[174:177], v[212:215], v[40:43]
	v_mfma_f32_16x16x32_bf16 v[36:39], v[166:169], v[220:223], v[36:39]
	v_mfma_f32_16x16x32_bf16 v[24:27], v[174:177], v[220:223], v[24:27]
	v_mfma_f32_16x16x32_bf16 v[20:23], v[166:169], v[228:231], v[20:23]
	v_mfma_f32_16x16x32_bf16 v[8:11], v[174:177], v[228:231], v[8:11]
	v_mfma_f32_16x16x32_bf16 v[48:51], v[178:181], v[200:203], v[48:51]
	v_mfma_f32_16x16x32_bf16 v[44:47], v[186:189], v[200:203], v[44:47]
	v_mfma_f32_16x16x32_bf16 v[32:35], v[178:181], v[208:211], v[32:35]
	v_mfma_f32_16x16x32_bf16 v[28:31], v[186:189], v[208:211], v[28:31]
	v_mfma_f32_16x16x32_bf16 v[16:19], v[178:181], v[216:219], v[16:19]
	v_mfma_f32_16x16x32_bf16 v[12:15], v[186:189], v[216:219], v[12:15]
	v_mfma_f32_16x16x32_bf16 v[4:7], v[178:181], v[224:227], v[4:7]
	v_mfma_f32_16x16x32_bf16 v[0:3], v[186:189], v[224:227], v[0:3]
	v_mfma_f32_16x16x32_bf16 v[48:51], v[182:185], v[204:207], v[48:51]
	v_mfma_f32_16x16x32_bf16 v[44:47], v[196:199], v[204:207], v[44:47]
	v_mfma_f32_16x16x32_bf16 v[32:35], v[182:185], v[212:215], v[32:35]
	v_mfma_f32_16x16x32_bf16 v[28:31], v[196:199], v[212:215], v[28:31]
	v_mfma_f32_16x16x32_bf16 v[16:19], v[182:185], v[220:223], v[16:19]
	v_mfma_f32_16x16x32_bf16 v[12:15], v[196:199], v[220:223], v[12:15]
	v_mfma_f32_16x16x32_bf16 v[4:7], v[182:185], v[228:231], v[4:7]
	v_mfma_f32_16x16x32_bf16 v[0:3], v[196:199], v[228:231], v[0:3]
	s_barrier
	s_add_i32 s73, 0, 0x18000
	v_add_u32_e32 v163, s73, v149
	s_add_i32 s80, 0, 0x1c000
	ds_read_b128 v[144:147], v163
	ds_read_b128 v[166:169], v163 offset:1024
	ds_read_b128 v[170:173], v163 offset:2048
	ds_read_b128 v[174:177], v163 offset:3072
	v_add_u32_e32 v163, s80, v149
	ds_read_b128 v[178:181], v163
	ds_read_b128 v[182:185], v163 offset:1024
	ds_read_b128 v[186:189], v163 offset:2048
	ds_read_b128 v[196:199], v163 offset:3072
	s_add_u32 s6, s78, 0x40000
	s_addc_u32 s7, s79, 0
	s_mov_b32 m0, s42
	v_lshl_add_u64 v[238:239], s[6:7], 0, v[128:129]
	ds_read_b128 v[200:203], v159 offset:32768
	ds_read_b128 v[204:207], v159 offset:33792
	ds_read_b128 v[208:211], v159 offset:34816
	ds_read_b128 v[212:215], v159 offset:35840
	ds_read_b128 v[216:219], v159 offset:36864
	ds_read_b128 v[220:223], v159 offset:37888
	ds_read_b128 v[224:227], v159 offset:38912
	ds_read_b128 v[228:231], v159 offset:39936
	global_load_lds_dwordx4 v[238:239], off
	v_lshl_add_u64 v[238:239], s[6:7], 0, v[132:133]
	s_mov_b32 m0, s43
	s_nop 0
	global_load_lds_dwordx4 v[238:239], off
	s_waitcnt vmcnt(8)
	s_waitcnt lgkmcnt(0)
	s_barrier
	s_waitcnt lgkmcnt(0)
	v_mfma_f32_16x16x32_bf16 v[124:127], v[144:147], v[200:203], v[124:127]
	v_mfma_f32_16x16x32_bf16 v[120:123], v[170:173], v[200:203], v[120:123]
	v_mfma_f32_16x16x32_bf16 v[112:115], v[144:147], v[208:211], v[112:115]
	v_mfma_f32_16x16x32_bf16 v[104:107], v[170:173], v[208:211], v[104:107]
	v_mfma_f32_16x16x32_bf16 v[96:99], v[144:147], v[216:219], v[96:99]
	v_mfma_f32_16x16x32_bf16 v[88:91], v[170:173], v[216:219], v[88:91]
	v_mfma_f32_16x16x32_bf16 v[80:83], v[144:147], v[224:227], v[80:83]
	v_mfma_f32_16x16x32_bf16 v[72:75], v[170:173], v[224:227], v[72:75]
	v_mfma_f32_16x16x32_bf16 v[124:127], v[166:169], v[204:207], v[124:127]
	v_mfma_f32_16x16x32_bf16 v[120:123], v[174:177], v[204:207], v[120:123]
	v_mfma_f32_16x16x32_bf16 v[112:115], v[166:169], v[212:215], v[112:115]
	v_mfma_f32_16x16x32_bf16 v[104:107], v[174:177], v[212:215], v[104:107]
	v_mfma_f32_16x16x32_bf16 v[96:99], v[166:169], v[220:223], v[96:99]
	v_mfma_f32_16x16x32_bf16 v[88:91], v[174:177], v[220:223], v[88:91]
	v_mfma_f32_16x16x32_bf16 v[80:83], v[166:169], v[228:231], v[80:83]
	v_mfma_f32_16x16x32_bf16 v[72:75], v[174:177], v[228:231], v[72:75]
	v_mfma_f32_16x16x32_bf16 v[116:119], v[178:181], v[200:203], v[116:119]
	v_mfma_f32_16x16x32_bf16 v[108:111], v[186:189], v[200:203], v[108:111]
	v_mfma_f32_16x16x32_bf16 v[100:103], v[178:181], v[208:211], v[100:103]
	v_mfma_f32_16x16x32_bf16 v[92:95], v[186:189], v[208:211], v[92:95]
	v_mfma_f32_16x16x32_bf16 v[84:87], v[178:181], v[216:219], v[84:87]
	v_mfma_f32_16x16x32_bf16 v[76:79], v[186:189], v[216:219], v[76:79]
	v_mfma_f32_16x16x32_bf16 v[68:71], v[178:181], v[224:227], v[68:71]
	v_mfma_f32_16x16x32_bf16 v[64:67], v[186:189], v[224:227], v[64:67]
	v_mfma_f32_16x16x32_bf16 v[116:119], v[182:185], v[204:207], v[116:119]
	v_mfma_f32_16x16x32_bf16 v[108:111], v[196:199], v[204:207], v[108:111]
	v_mfma_f32_16x16x32_bf16 v[100:103], v[182:185], v[212:215], v[100:103]
	v_mfma_f32_16x16x32_bf16 v[92:95], v[196:199], v[212:215], v[92:95]
	v_mfma_f32_16x16x32_bf16 v[84:87], v[182:185], v[220:223], v[84:87]
	v_mfma_f32_16x16x32_bf16 v[76:79], v[196:199], v[220:223], v[76:79]
	v_mfma_f32_16x16x32_bf16 v[68:71], v[182:185], v[228:231], v[68:71]
	v_mfma_f32_16x16x32_bf16 v[64:67], v[196:199], v[228:231], v[64:67]
	s_barrier
; #define PG8_STAGE(bufoff, gbase, voff) do { _Pragma("unroll") for (int _i = 0; _i < 2; ++_i) \
;         __builtin_amdgcn_global_load_lds((const unsigned*)((const char*)(gbase) + (voff)[_i]), (PG8_LAS unsigned*)(lds + (bufoff) + ldsw + _i * 8192), 16, 0, 0); } while (0)
; #define PG8_LDA(dst, b, h) do { _Pragma("unroll") for (int m = 0; m < 4; ++m) _Pragma("unroll") for (int k = 0; k < 2; ++k) dst[m][k] = *(const PG8_LAS bf16x8*)(lds + PG8_SA(b, h) + aoff + m * 2048 + k * 1024); } while (0)
; #define PG8_MMA(ai, bj, At, Bt) do { __builtin_amdgcn_s_setprio(1); _Pragma("unroll") for (int m = 0; m < 4; ++m) _Pragma("unroll") for (int n = 0; n < 2; ++n) _Pragma("unroll") for (int k = 0; k < 2; ++k) \
;         acc[ai][bj][m][n] = __builtin_amdgcn_mfma_f32_16x16x32_bf16(Bt[n][k], At[m][k], acc[ai][bj][m][n], 0, 0, 0); __builtin_amdgcn_s_setprio(0); } while (0)
; #define PG8_WAIT_V(n) asm volatile("s_waitcnt vmcnt(" #n ")" ::: "memory")
; #define PG8_WAIT_L(n) asm volatile("s_waitcnt lgkmcnt(" #n ")" ::: "memory")
; #define PG8_BAR __builtin_amdgcn_s_barrier()
; #define PG8_SCHED __builtin_amdgcn_sched_barrier(0)
; template <class Epi, class Sched, bool ALIGN_EPI = false, bool SP2 = false>
; __device__ __forceinline__ void gemm_phase(PG8_LAS unsigned char* lds, const Gemm g, const Sched& S, const Epi& E) {
;     ...
;             PG8_LDA(At, 1, 1); PG8_STAGE(PG8_SB(1, 0), b3, voffB); PG8_STAGE(PG8_SB(1, 1), b3 + hstep, voffB); PG8_STAGE(PG8_SA(1, 0), a3, voffA);
;             PG8_WAIT_V(8); PG8_WAIT_L(0); PG8_BAR; PG8_MMA(1, 0, At, B0); PG8_MMA(1, 1, At, B1); PG8_BAR; PG8_SCHED;
	s_add_i32 s6, s73, s27
	v_lshl_add_u64 v[190:191], v[190:191], 0, s[38:39]
	s_mov_b32 m0, s6
	ds_read_b128 v[200:203], v159 offset:49152
	ds_read_b128 v[204:207], v159 offset:50176
	ds_read_b128 v[208:211], v159 offset:51200
	ds_read_b128 v[212:215], v159 offset:52224
	ds_read_b128 v[216:219], v159 offset:53248
	ds_read_b128 v[220:223], v159 offset:54272
	ds_read_b128 v[224:227], v159 offset:55296
	ds_read_b128 v[228:231], v159 offset:56320
	global_load_lds_dwordx4 v[190:191], off
	s_add_i32 m0, s6, 0x2000
	s_add_u32 s6, s60, 0x40080
	v_lshl_add_u64 v[190:191], v[232:233], 0, s[38:39]
	s_addc_u32 s7, s61, 0
	s_add_i32 s60, s80, s27
	global_load_lds_dwordx4 v[190:191], off
	v_lshl_add_u64 v[190:191], s[6:7], 0, v[130:131]
	s_mov_b32 m0, s60
	s_nop 0
	global_load_lds_dwordx4 v[190:191], off
	v_lshl_add_u64 v[190:191], s[6:7], 0, v[134:135]
	s_add_i32 m0, s60, 0x2000
	s_nop 0
	global_load_lds_dwordx4 v[190:191], off
	v_lshl_add_u64 v[190:191], v[234:235], 0, s[38:39]
	s_mov_b32 m0, s44
	s_nop 0
	global_load_lds_dwordx4 v[190:191], off
	v_lshl_add_u64 v[190:191], v[236:237], 0, s[38:39]
	s_mov_b32 m0, s45
	s_nop 0
	global_load_lds_dwordx4 v[190:191], off
	s_waitcnt vmcnt(8)
	s_waitcnt lgkmcnt(0)
	s_barrier
	s_waitcnt lgkmcnt(0)
	v_mfma_f32_16x16x32_bf16 v[60:63], v[144:147], v[200:203], v[60:63]
	v_mfma_f32_16x16x32_bf16 v[56:59], v[170:173], v[200:203], v[56:59]
	v_mfma_f32_16x16x32_bf16 v[52:55], v[144:147], v[208:211], v[52:55]
	v_mfma_f32_16x16x32_bf16 v[40:43], v[170:173], v[208:211], v[40:43]
	v_mfma_f32_16x16x32_bf16 v[36:39], v[144:147], v[216:219], v[36:39]
	v_mfma_f32_16x16x32_bf16 v[24:27], v[170:173], v[216:219], v[24:27]
	v_mfma_f32_16x16x32_bf16 v[20:23], v[144:147], v[224:227], v[20:23]
	v_mfma_f32_16x16x32_bf16 v[8:11], v[170:173], v[224:227], v[8:11]
	v_mfma_f32_16x16x32_bf16 v[60:63], v[166:169], v[204:207], v[60:63]
	v_mfma_f32_16x16x32_bf16 v[56:59], v[174:177], v[204:207], v[56:59]
	v_mfma_f32_16x16x32_bf16 v[52:55], v[166:169], v[212:215], v[52:55]
	v_mfma_f32_16x16x32_bf16 v[40:43], v[174:177], v[212:215], v[40:43]
	v_mfma_f32_16x16x32_bf16 v[36:39], v[166:169], v[220:223], v[36:39]
	v_mfma_f32_16x16x32_bf16 v[24:27], v[174:177], v[220:223], v[24:27]
	v_mfma_f32_16x16x32_bf16 v[20:23], v[166:169], v[228:231], v[20:23]
	v_mfma_f32_16x16x32_bf16 v[8:11], v[174:177], v[228:231], v[8:11]
	v_mfma_f32_16x16x32_bf16 v[48:51], v[178:181], v[200:203], v[48:51]
	v_mfma_f32_16x16x32_bf16 v[44:47], v[186:189], v[200:203], v[44:47]
	v_mfma_f32_16x16x32_bf16 v[32:35], v[178:181], v[208:211], v[32:35]
	v_mfma_f32_16x16x32_bf16 v[28:31], v[186:189], v[208:211], v[28:31]
	v_mfma_f32_16x16x32_bf16 v[16:19], v[178:181], v[216:219], v[16:19]
	v_mfma_f32_16x16x32_bf16 v[12:15], v[186:189], v[216:219], v[12:15]
	v_mfma_f32_16x16x32_bf16 v[4:7], v[178:181], v[224:227], v[4:7]
	v_mfma_f32_16x16x32_bf16 v[0:3], v[186:189], v[224:227], v[0:3]
	v_mfma_f32_16x16x32_bf16 v[48:51], v[182:185], v[204:207], v[48:51]
	v_mfma_f32_16x16x32_bf16 v[44:47], v[196:199], v[204:207], v[44:47]
	v_mfma_f32_16x16x32_bf16 v[32:35], v[182:185], v[212:215], v[32:35]
	v_mfma_f32_16x16x32_bf16 v[28:31], v[196:199], v[212:215], v[28:31]
	v_mfma_f32_16x16x32_bf16 v[16:19], v[182:185], v[220:223], v[16:19]
	v_mfma_f32_16x16x32_bf16 v[12:15], v[196:199], v[220:223], v[12:15]
	v_mfma_f32_16x16x32_bf16 v[4:7], v[182:185], v[228:231], v[4:7]
	v_mfma_f32_16x16x32_bf16 v[0:3], v[196:199], v[228:231], v[0:3]
	s_barrier
	s_add_i32 s72, s72, 2
	s_add_u32 s58, s58, 0x100
	s_addc_u32 s59, s59, 0
	s_add_u32 s77, s77, 0x100
	s_addc_u32 s33, s33, 0
	s_cmp_gt_u32 s72, 13
	s_cbranch_scc0 .LBB0_1392
	s_and_b64 vcc, exec, s[40:41]
	s_cbranch_vccz .LBB0_1395
	s_barrier

; #define PG8_STAGE(bufoff, gbase, voff) do { _Pragma("unroll") for (int _i = 0; _i < 2; ++_i) \
;         __builtin_amdgcn_global_load_lds((const unsigned*)((const char*)(gbase) + (voff)[_i]), (PG8_LAS unsigned*)(lds + (bufoff) + ldsw + _i * 8192), 16, 0, 0); } while (0)
; #define PG8_LDA(dst, b, h) do { _Pragma("unroll") for (int m = 0; m < 4; ++m) _Pragma("unroll") for (int k = 0; k < 2; ++k) dst[m][k] = *(const PG8_LAS bf16x8*)(lds + PG8_SA(b, h) + aoff + m * 2048 + k * 1024); } while (0)
; #define PG8_LDB(dst, b, h) do { _Pragma("unroll") for (int n = 0; n < 2; ++n) _Pragma("unroll") for (int k = 0; k < 2; ++k) dst[n][k] = *(const PG8_LAS bf16x8*)(lds + PG8_SB(b, h) + boff + n * 2048 + k * 1024); } while (0)
; #define PG8_MMA(ai, bj, At, Bt) do { __builtin_amdgcn_s_setprio(1); _Pragma("unroll") for (int m = 0; m < 4; ++m) _Pragma("unroll") for (int n = 0; n < 2; ++n) _Pragma("unroll") for (int k = 0; k < 2; ++k) \
;         acc[ai][bj][m][n] = __builtin_amdgcn_mfma_f32_16x16x32_bf16(Bt[n][k], At[m][k], acc[ai][bj][m][n], 0, 0, 0); __builtin_amdgcn_s_setprio(0); } while (0)
; #define PG8_WAIT_V(n) asm volatile("s_waitcnt vmcnt(" #n ")" ::: "memory")
; #define PG8_WAIT_L(n) asm volatile("s_waitcnt lgkmcnt(" #n ")" ::: "memory")
; #define PG8_BAR __builtin_amdgcn_s_barrier()
; #define PG8_SCHED __builtin_amdgcn_sched_barrier(0)
; template <class Epi, class Sched, bool ALIGN_EPI = false, bool SP2 = false>
; __device__ __forceinline__ void gemm_phase(PG8_LAS unsigned char* lds, const Gemm g, const Sched& S, const Epi& E) {
;     ...
;             const bool last = (t == nt - 2);
;             const char* a1 = cA + (size_t)(t + 1) * kstep;
;             const char* a2 = last ? nA : cA + (size_t)(t + 2) * kstep; const char* b2 = last ? nB : cB + (size_t)(t + 2) * kstep;
;             const char* a3 = a2 + kstep; const char* b3 = b2 + kstep;
;             if (last && has_next) S.a_ready(nxt);
;             if constexpr (SP2) {
;             PG8_LDB(B0, 0, 0); PG8_LDB(B1, 0, 1); PG8_SCHED; PG8_LDA(At, 0, 0); PG8_STAGE(PG8_SA(1, 1), a1 + hstep, voffA);
;             PG8_WAIT_V(8); PG8_WAIT_L(0); PG8_BAR; PG8_MMA(0, 0, At, B0); PG8_MMA(0, 1, At, B1); PG8_BAR; PG8_SCHED;
;             PG8_LDA(At, 0, 1); PG8_STAGE(PG8_SB(0, 0), b2, voffB); PG8_STAGE(PG8_SB(0, 1), b2 + hstep, voffB); PG8_STAGE(PG8_SA(0, 0), a2, voffA);
.LBB0_1617:
	ds_read_b128 v[32:35], v191
	ds_read_b128 v[36:39], v191 offset:1024
	ds_read_b128 v[48:51], v191 offset:2048
	ds_read_b128 v[52:55], v191 offset:3072
	ds_read_b128 v[128:131], v195
	ds_read_b128 v[148:151], v195 offset:1024
	ds_read_b128 v[152:155], v195 offset:2048
	ds_read_b128 v[180:183], v195 offset:3072
	s_add_u32 s6, s56, 0xfffc0080
	s_addc_u32 s7, s57, -1
	s_cmp_eq_u32 s69, 12
	s_cselect_b32 s61, s26, s7
	s_cselect_b32 s60, s29, s6
	s_cselect_b32 s59, s49, s33
	s_cselect_b32 s58, s51, s68
	v_lshl_add_u64 v[188:189], s[56:57], 0, v[172:173]
	s_add_i32 m0, s78, 0xc000
	ds_read_b128 v[184:187], v198
	ds_read_b128 v[200:203], v198 offset:1024
	ds_read_b128 v[204:207], v198 offset:2048
	ds_read_b128 v[208:211], v198 offset:3072
	ds_read_b128 v[212:215], v198 offset:4096
	ds_read_b128 v[216:219], v198 offset:5120
	ds_read_b128 v[220:223], v198 offset:6144
	ds_read_b128 v[224:227], v198 offset:7168
	global_load_lds_dwordx4 v[188:189], off
	v_lshl_add_u64 v[188:189], s[56:57], 0, v[174:175]
	s_add_i32 m0, s78, 0xe000
	s_nop 0
	global_load_lds_dwordx4 v[188:189], off
	s_waitcnt vmcnt(8)
	s_waitcnt lgkmcnt(0)
	s_barrier
	s_waitcnt lgkmcnt(0)
	v_mfma_f32_16x16x32_bf16 v[144:147], v[32:35], v[184:187], v[144:147]
	v_mfma_f32_16x16x32_bf16 v[140:143], v[48:51], v[184:187], v[140:143]
	v_mfma_f32_16x16x32_bf16 v[124:127], v[32:35], v[204:207], v[124:127]
	v_mfma_f32_16x16x32_bf16 v[120:123], v[48:51], v[204:207], v[120:123]
	v_mfma_f32_16x16x32_bf16 v[108:111], v[32:35], v[212:215], v[108:111]
	v_mfma_f32_16x16x32_bf16 v[104:107], v[48:51], v[212:215], v[104:107]
	v_mfma_f32_16x16x32_bf16 v[92:95], v[32:35], v[220:223], v[92:95]
	v_mfma_f32_16x16x32_bf16 v[88:91], v[48:51], v[220:223], v[88:91]
	v_mfma_f32_16x16x32_bf16 v[144:147], v[36:39], v[200:203], v[144:147]
	v_mfma_f32_16x16x32_bf16 v[140:143], v[52:55], v[200:203], v[140:143]
	v_mfma_f32_16x16x32_bf16 v[124:127], v[36:39], v[208:211], v[124:127]
	v_mfma_f32_16x16x32_bf16 v[120:123], v[52:55], v[208:211], v[120:123]
	v_mfma_f32_16x16x32_bf16 v[108:111], v[36:39], v[216:219], v[108:111]
	v_mfma_f32_16x16x32_bf16 v[104:107], v[52:55], v[216:219], v[104:107]
	v_mfma_f32_16x16x32_bf16 v[92:95], v[36:39], v[224:227], v[92:95]
	v_mfma_f32_16x16x32_bf16 v[88:91], v[52:55], v[224:227], v[88:91]
	v_mfma_f32_16x16x32_bf16 v[136:139], v[128:131], v[184:187], v[136:139]
	v_mfma_f32_16x16x32_bf16 v[132:135], v[152:155], v[184:187], v[132:135]
	v_mfma_f32_16x16x32_bf16 v[116:119], v[128:131], v[204:207], v[116:119]
	v_mfma_f32_16x16x32_bf16 v[112:115], v[152:155], v[204:207], v[112:115]
	v_mfma_f32_16x16x32_bf16 v[100:103], v[128:131], v[212:215], v[100:103]
	v_mfma_f32_16x16x32_bf16 v[96:99], v[152:155], v[212:215], v[96:99]
	v_mfma_f32_16x16x32_bf16 v[84:87], v[128:131], v[220:223], v[84:87]
	v_mfma_f32_16x16x32_bf16 v[80:83], v[152:155], v[220:223], v[80:83]
	v_mfma_f32_16x16x32_bf16 v[136:139], v[148:151], v[200:203], v[136:139]
	v_mfma_f32_16x16x32_bf16 v[132:135], v[180:183], v[200:203], v[132:135]
	v_mfma_f32_16x16x32_bf16 v[116:119], v[148:151], v[208:211], v[116:119]
	v_mfma_f32_16x16x32_bf16 v[112:115], v[180:183], v[208:211], v[112:115]
	v_mfma_f32_16x16x32_bf16 v[100:103], v[148:151], v[216:219], v[100:103]
	v_mfma_f32_16x16x32_bf16 v[96:99], v[180:183], v[216:219], v[96:99]
	v_mfma_f32_16x16x32_bf16 v[84:87], v[148:151], v[224:227], v[84:87]
	v_mfma_f32_16x16x32_bf16 v[80:83], v[180:183], v[224:227], v[80:83]
	s_barrier
	s_add_i32 s6, s43, s67
	v_lshl_add_u64 v[188:189], s[58:59], 0, v[158:159]
	s_mov_b32 m0, s6
	ds_read_b128 v[184:187], v198 offset:16384
	ds_read_b128 v[200:203], v198 offset:17408
	ds_read_b128 v[204:207], v198 offset:18432
	ds_read_b128 v[208:211], v198 offset:19456
	ds_read_b128 v[212:215], v198 offset:20480
	ds_read_b128 v[216:219], v198 offset:21504
	ds_read_b128 v[220:223], v198 offset:22528
	ds_read_b128 v[224:227], v198 offset:23552
	global_load_lds_dwordx4 v[188:189], off
	s_add_i32 m0, s6, 0x2000
	s_add_u32 s6, s58, 0x40000
	v_lshl_add_u64 v[228:229], s[58:59], 0, v[170:171]
	s_addc_u32 s7, s59, 0
	s_add_i32 s72, s76, s67
	global_load_lds_dwordx4 v[228:229], off
	v_lshl_add_u64 v[230:231], s[6:7], 0, v[158:159]
	s_mov_b32 m0, s72
	v_lshl_add_u64 v[232:233], s[60:61], 0, v[164:165]
	global_load_lds_dwordx4 v[230:231], off
	v_lshl_add_u64 v[230:231], s[6:7], 0, v[170:171]
	s_add_i32 m0, s72, 0x2000
	s_nop 0
	global_load_lds_dwordx4 v[230:231], off
	v_lshl_add_u64 v[230:231], s[60:61], 0, v[156:157]
	s_mov_b32 m0, s78
	s_nop 0
	global_load_lds_dwordx4 v[230:231], off
	s_mov_b32 m0, s79
	s_nop 0
	global_load_lds_dwordx4 v[232:233], off
	s_waitcnt vmcnt(8)
	s_waitcnt lgkmcnt(0)
	s_barrier
; #define PG8_STAGE(bufoff, gbase, voff) do { _Pragma("unroll") for (int _i = 0; _i < 2; ++_i) \
;         __builtin_amdgcn_global_load_lds((const unsigned*)((const char*)(gbase) + (voff)[_i]), (PG8_LAS unsigned*)(lds + (bufoff) + ldsw + _i * 8192), 16, 0, 0); } while (0)
; #define PG8_LDA(dst, b, h) do { _Pragma("unroll") for (int m = 0; m < 4; ++m) _Pragma("unroll") for (int k = 0; k < 2; ++k) dst[m][k] = *(const PG8_LAS bf16x8*)(lds + PG8_SA(b, h) + aoff + m * 2048 + k * 1024); } while (0)
; #define PG8_LDB(dst, b, h) do { _Pragma("unroll") for (int n = 0; n < 2; ++n) _Pragma("unroll") for (int k = 0; k < 2; ++k) dst[n][k] = *(const PG8_LAS bf16x8*)(lds + PG8_SB(b, h) + boff + n * 2048 + k * 1024); } while (0)
; #define PG8_MMA(ai, bj, At, Bt) do { __builtin_amdgcn_s_setprio(1); _Pragma("unroll") for (int m = 0; m < 4; ++m) _Pragma("unroll") for (int n = 0; n < 2; ++n) _Pragma("unroll") for (int k = 0; k < 2; ++k) \
;         acc[ai][bj][m][n] = __builtin_amdgcn_mfma_f32_16x16x32_bf16(Bt[n][k], At[m][k], acc[ai][bj][m][n], 0, 0, 0); __builtin_amdgcn_s_setprio(0); } while (0)
; #define PG8_WAIT_V(n) asm volatile("s_waitcnt vmcnt(" #n ")" ::: "memory")
; #define PG8_WAIT_L(n) asm volatile("s_waitcnt lgkmcnt(" #n ")" ::: "memory")
; #define PG8_BAR __builtin_amdgcn_s_barrier()
; #define PG8_SCHED __builtin_amdgcn_sched_barrier(0)
; template <class Epi, class Sched, bool ALIGN_EPI = false, bool SP2 = false>
; __device__ __forceinline__ void gemm_phase(PG8_LAS unsigned char* lds, const Gemm g, const Sched& S, const Epi& E) {
;     ...
;             PG8_WAIT_V(8); PG8_WAIT_L(0); PG8_BAR; PG8_MMA(1, 0, At, B0); PG8_MMA(1, 1, At, B1); PG8_BAR; PG8_SCHED;
;             PG8_LDB(B0, 1, 0); PG8_LDB(B1, 1, 1); PG8_SCHED; PG8_LDA(At, 1, 0); PG8_STAGE(PG8_SA(0, 1), a2 + hstep, voffA);
;             PG8_WAIT_V(8); PG8_WAIT_L(0); PG8_BAR; PG8_MMA(0, 0, At, B0); PG8_MMA(0, 1, At, B1); PG8_BAR; PG8_SCHED;
	s_waitcnt lgkmcnt(0)
	v_mfma_f32_16x16x32_bf16 v[76:79], v[32:35], v[184:187], v[76:79]
	v_mfma_f32_16x16x32_bf16 v[72:75], v[48:51], v[184:187], v[72:75]
	v_mfma_f32_16x16x32_bf16 v[60:63], v[32:35], v[204:207], v[60:63]
	v_mfma_f32_16x16x32_bf16 v[56:59], v[48:51], v[204:207], v[56:59]
	v_mfma_f32_16x16x32_bf16 v[28:31], v[32:35], v[212:215], v[28:31]
	v_mfma_f32_16x16x32_bf16 v[24:27], v[48:51], v[212:215], v[24:27]
	v_mfma_f32_16x16x32_bf16 v[12:15], v[32:35], v[220:223], v[12:15]
	v_mfma_f32_16x16x32_bf16 v[8:11], v[48:51], v[220:223], v[8:11]
	v_mfma_f32_16x16x32_bf16 v[76:79], v[36:39], v[200:203], v[76:79]
	v_mfma_f32_16x16x32_bf16 v[72:75], v[52:55], v[200:203], v[72:75]
	v_mfma_f32_16x16x32_bf16 v[60:63], v[36:39], v[208:211], v[60:63]
	v_mfma_f32_16x16x32_bf16 v[56:59], v[52:55], v[208:211], v[56:59]
	v_mfma_f32_16x16x32_bf16 v[28:31], v[36:39], v[216:219], v[28:31]
	v_mfma_f32_16x16x32_bf16 v[24:27], v[52:55], v[216:219], v[24:27]
	v_mfma_f32_16x16x32_bf16 v[12:15], v[36:39], v[224:227], v[12:15]
	v_mfma_f32_16x16x32_bf16 v[8:11], v[52:55], v[224:227], v[8:11]
	v_mfma_f32_16x16x32_bf16 v[44:47], v[128:131], v[204:207], v[44:47]
	v_mfma_f32_16x16x32_bf16 v[40:43], v[152:155], v[204:207], v[40:43]
	v_mfma_f32_16x16x32_bf16 v[20:23], v[128:131], v[212:215], v[20:23]
	v_mfma_f32_16x16x32_bf16 v[16:19], v[152:155], v[212:215], v[16:19]
	v_mfma_f32_16x16x32_bf16 v[4:7], v[128:131], v[220:223], v[4:7]
	v_mfma_f32_16x16x32_bf16 v[0:3], v[152:155], v[220:223], v[0:3]
	v_mfma_f32_16x16x32_bf16 v[32:35], v[128:131], v[184:187], v[68:71]
	v_mfma_f32_16x16x32_bf16 v[36:39], v[152:155], v[184:187], v[64:67]
	v_mfma_f32_16x16x32_bf16 v[44:47], v[148:151], v[208:211], v[44:47]
	v_mfma_f32_16x16x32_bf16 v[40:43], v[180:183], v[208:211], v[40:43]
	v_mfma_f32_16x16x32_bf16 v[20:23], v[148:151], v[216:219], v[20:23]
	v_mfma_f32_16x16x32_bf16 v[16:19], v[180:183], v[216:219], v[16:19]
	v_mfma_f32_16x16x32_bf16 v[4:7], v[148:151], v[224:227], v[4:7]
	v_mfma_f32_16x16x32_bf16 v[0:3], v[180:183], v[224:227], v[0:3]
	v_mfma_f32_16x16x32_bf16 v[32:35], v[148:151], v[200:203], v[32:35]
	v_mfma_f32_16x16x32_bf16 v[36:39], v[180:183], v[200:203], v[36:39]
	s_barrier
	s_add_i32 s72, 0, 0x18000
	s_add_i32 s73, 0, 0x1c000
	v_add_u32_e32 v68, s72, v169
	v_add_u32_e32 v180, s73, v169
	ds_read_b128 v[48:51], v68
	ds_read_b128 v[52:55], v68 offset:1024
	ds_read_b128 v[64:67], v68 offset:2048
	ds_read_b128 v[68:71], v68 offset:3072
	ds_read_b128 v[128:131], v180
	ds_read_b128 v[148:151], v180 offset:1024
	ds_read_b128 v[152:155], v180 offset:2048
	ds_read_b128 v[180:183], v180 offset:3072
	s_add_u32 s6, s60, 0x40000
	s_addc_u32 s7, s61, 0
	s_mov_b32 m0, s80
	v_lshl_add_u64 v[234:235], s[6:7], 0, v[156:157]
	ds_read_b128 v[184:187], v198 offset:32768
	ds_read_b128 v[200:203], v198 offset:33792
	ds_read_b128 v[204:207], v198 offset:34816
	ds_read_b128 v[208:211], v198 offset:35840
	ds_read_b128 v[212:215], v198 offset:36864
	ds_read_b128 v[216:219], v198 offset:37888
	ds_read_b128 v[220:223], v198 offset:38912
	ds_read_b128 v[224:227], v198 offset:39936
	global_load_lds_dwordx4 v[234:235], off
	v_lshl_add_u64 v[234:235], s[6:7], 0, v[164:165]
	s_mov_b32 m0, s81
	s_nop 0
	global_load_lds_dwordx4 v[234:235], off
	s_waitcnt vmcnt(8)
	s_waitcnt lgkmcnt(0)
	s_barrier
	s_waitcnt lgkmcnt(0)
	v_mfma_f32_16x16x32_bf16 v[144:147], v[48:51], v[184:187], v[144:147]
	v_mfma_f32_16x16x32_bf16 v[140:143], v[64:67], v[184:187], v[140:143]
	v_mfma_f32_16x16x32_bf16 v[124:127], v[48:51], v[204:207], v[124:127]
	v_mfma_f32_16x16x32_bf16 v[120:123], v[64:67], v[204:207], v[120:123]
	v_mfma_f32_16x16x32_bf16 v[108:111], v[48:51], v[212:215], v[108:111]
	v_mfma_f32_16x16x32_bf16 v[104:107], v[64:67], v[212:215], v[104:107]
	v_mfma_f32_16x16x32_bf16 v[92:95], v[48:51], v[220:223], v[92:95]
	v_mfma_f32_16x16x32_bf16 v[88:91], v[64:67], v[220:223], v[88:91]
	v_mfma_f32_16x16x32_bf16 v[144:147], v[52:55], v[200:203], v[144:147]
	v_mfma_f32_16x16x32_bf16 v[140:143], v[68:71], v[200:203], v[140:143]
	v_mfma_f32_16x16x32_bf16 v[124:127], v[52:55], v[208:211], v[124:127]
	v_mfma_f32_16x16x32_bf16 v[120:123], v[68:71], v[208:211], v[120:123]
	v_mfma_f32_16x16x32_bf16 v[108:111], v[52:55], v[216:219], v[108:111]
	v_mfma_f32_16x16x32_bf16 v[104:107], v[68:71], v[216:219], v[104:107]
	v_mfma_f32_16x16x32_bf16 v[92:95], v[52:55], v[224:227], v[92:95]
	v_mfma_f32_16x16x32_bf16 v[88:91], v[68:71], v[224:227], v[88:91]
	v_mfma_f32_16x16x32_bf16 v[136:139], v[128:131], v[184:187], v[136:139]
	v_mfma_f32_16x16x32_bf16 v[132:135], v[152:155], v[184:187], v[132:135]
	v_mfma_f32_16x16x32_bf16 v[116:119], v[128:131], v[204:207], v[116:119]
	v_mfma_f32_16x16x32_bf16 v[112:115], v[152:155], v[204:207], v[112:115]
	v_mfma_f32_16x16x32_bf16 v[100:103], v[128:131], v[212:215], v[100:103]
	v_mfma_f32_16x16x32_bf16 v[96:99], v[152:155], v[212:215], v[96:99]
	v_mfma_f32_16x16x32_bf16 v[84:87], v[128:131], v[220:223], v[84:87]
	v_mfma_f32_16x16x32_bf16 v[80:83], v[152:155], v[220:223], v[80:83]
	v_mfma_f32_16x16x32_bf16 v[136:139], v[148:151], v[200:203], v[136:139]
	v_mfma_f32_16x16x32_bf16 v[132:135], v[180:183], v[200:203], v[132:135]
	v_mfma_f32_16x16x32_bf16 v[116:119], v[148:151], v[208:211], v[116:119]
	v_mfma_f32_16x16x32_bf16 v[112:115], v[180:183], v[208:211], v[112:115]
	v_mfma_f32_16x16x32_bf16 v[100:103], v[148:151], v[216:219], v[100:103]
	v_mfma_f32_16x16x32_bf16 v[96:99], v[180:183], v[216:219], v[96:99]
	v_mfma_f32_16x16x32_bf16 v[84:87], v[148:151], v[224:227], v[84:87]
	v_mfma_f32_16x16x32_bf16 v[80:83], v[180:183], v[224:227], v[80:83]
	s_barrier
; #define PG8_STAGE(bufoff, gbase, voff) do { _Pragma("unroll") for (int _i = 0; _i < 2; ++_i) \
;         __builtin_amdgcn_global_load_lds((const unsigned*)((const char*)(gbase) + (voff)[_i]), (PG8_LAS unsigned*)(lds + (bufoff) + ldsw + _i * 8192), 16, 0, 0); } while (0)
; #define PG8_LDA(dst, b, h) do { _Pragma("unroll") for (int m = 0; m < 4; ++m) _Pragma("unroll") for (int k = 0; k < 2; ++k) dst[m][k] = *(const PG8_LAS bf16x8*)(lds + PG8_SA(b, h) + aoff + m * 2048 + k * 1024); } while (0)
; #define PG8_MMA(ai, bj, At, Bt) do { __builtin_amdgcn_s_setprio(1); _Pragma("unroll") for (int m = 0; m < 4; ++m) _Pragma("unroll") for (int n = 0; n < 2; ++n) _Pragma("unroll") for (int k = 0; k < 2; ++k) \
;         acc[ai][bj][m][n] = __builtin_amdgcn_mfma_f32_16x16x32_bf16(Bt[n][k], At[m][k], acc[ai][bj][m][n], 0, 0, 0); __builtin_amdgcn_s_setprio(0); } while (0)
; #define PG8_WAIT_V(n) asm volatile("s_waitcnt vmcnt(" #n ")" ::: "memory")
; #define PG8_WAIT_L(n) asm volatile("s_waitcnt lgkmcnt(" #n ")" ::: "memory")
; #define PG8_BAR __builtin_amdgcn_s_barrier()
; #define PG8_SCHED __builtin_amdgcn_sched_barrier(0)
; template <class Epi, class Sched, bool ALIGN_EPI = false, bool SP2 = false>
; __device__ __forceinline__ void gemm_phase(PG8_LAS unsigned char* lds, const Gemm g, const Sched& S, const Epi& E) {
;     ...
;             PG8_LDA(At, 1, 1); PG8_STAGE(PG8_SB(1, 0), b3, voffB); PG8_STAGE(PG8_SB(1, 1), b3 + hstep, voffB); PG8_STAGE(PG8_SA(1, 0), a3, voffA);
;             PG8_WAIT_V(8); PG8_WAIT_L(0); PG8_BAR; PG8_MMA(1, 0, At, B0); PG8_MMA(1, 1, At, B1); PG8_BAR; PG8_SCHED;
	s_add_i32 s6, s72, s67
	v_lshl_add_u64 v[188:189], v[188:189], 0, s[38:39]
	s_mov_b32 m0, s6
	ds_read_b128 v[184:187], v198 offset:49152
	ds_read_b128 v[200:203], v198 offset:50176
	ds_read_b128 v[204:207], v198 offset:51200
	ds_read_b128 v[208:211], v198 offset:52224
	ds_read_b128 v[212:215], v198 offset:53248
	ds_read_b128 v[216:219], v198 offset:54272
	ds_read_b128 v[220:223], v198 offset:55296
	ds_read_b128 v[224:227], v198 offset:56320
	global_load_lds_dwordx4 v[188:189], off
	s_add_i32 m0, s6, 0x2000
	s_add_u32 s6, s58, 0x40080
	v_lshl_add_u64 v[188:189], v[228:229], 0, s[38:39]
	s_addc_u32 s7, s59, 0
	s_add_i32 s58, s73, s67
	global_load_lds_dwordx4 v[188:189], off
	v_lshl_add_u64 v[188:189], s[6:7], 0, v[158:159]
	s_mov_b32 m0, s58
	s_nop 0
	global_load_lds_dwordx4 v[188:189], off
	v_lshl_add_u64 v[188:189], s[6:7], 0, v[170:171]
	s_add_i32 m0, s58, 0x2000
	s_nop 0
	global_load_lds_dwordx4 v[188:189], off
	v_lshl_add_u64 v[188:189], v[230:231], 0, s[38:39]
	s_mov_b32 m0, s45
	s_nop 0
	global_load_lds_dwordx4 v[188:189], off
	v_lshl_add_u64 v[188:189], v[232:233], 0, s[38:39]
	s_mov_b32 m0, s42
	s_nop 0
	global_load_lds_dwordx4 v[188:189], off
	s_waitcnt vmcnt(8)
	s_waitcnt lgkmcnt(0)
	s_barrier
	s_waitcnt lgkmcnt(0)
	v_mfma_f32_16x16x32_bf16 v[76:79], v[48:51], v[184:187], v[76:79]
	v_mfma_f32_16x16x32_bf16 v[72:75], v[64:67], v[184:187], v[72:75]
	v_mfma_f32_16x16x32_bf16 v[60:63], v[48:51], v[204:207], v[60:63]
	v_mfma_f32_16x16x32_bf16 v[56:59], v[64:67], v[204:207], v[56:59]
	v_mfma_f32_16x16x32_bf16 v[28:31], v[48:51], v[212:215], v[28:31]
	v_mfma_f32_16x16x32_bf16 v[24:27], v[64:67], v[212:215], v[24:27]
	v_mfma_f32_16x16x32_bf16 v[12:15], v[48:51], v[220:223], v[12:15]
	v_mfma_f32_16x16x32_bf16 v[8:11], v[64:67], v[220:223], v[8:11]
	v_mfma_f32_16x16x32_bf16 v[76:79], v[52:55], v[200:203], v[76:79]
	v_mfma_f32_16x16x32_bf16 v[72:75], v[68:71], v[200:203], v[72:75]
	v_mfma_f32_16x16x32_bf16 v[60:63], v[52:55], v[208:211], v[60:63]
	v_mfma_f32_16x16x32_bf16 v[56:59], v[68:71], v[208:211], v[56:59]
	v_mfma_f32_16x16x32_bf16 v[28:31], v[52:55], v[216:219], v[28:31]
	v_mfma_f32_16x16x32_bf16 v[24:27], v[68:71], v[216:219], v[24:27]
	v_mfma_f32_16x16x32_bf16 v[12:15], v[52:55], v[224:227], v[12:15]
	v_mfma_f32_16x16x32_bf16 v[8:11], v[68:71], v[224:227], v[8:11]
	v_mfma_f32_16x16x32_bf16 v[32:35], v[128:131], v[184:187], v[32:35]
	v_mfma_f32_16x16x32_bf16 v[68:71], v[148:151], v[200:203], v[32:35]
	v_mfma_f32_16x16x32_bf16 v[32:35], v[152:155], v[184:187], v[36:39]
	v_mfma_f32_16x16x32_bf16 v[64:67], v[180:183], v[200:203], v[32:35]
	v_mfma_f32_16x16x32_bf16 v[32:35], v[128:131], v[204:207], v[44:47]
	v_mfma_f32_16x16x32_bf16 v[44:47], v[148:151], v[208:211], v[32:35]
	v_mfma_f32_16x16x32_bf16 v[32:35], v[152:155], v[204:207], v[40:43]
	v_mfma_f32_16x16x32_bf16 v[20:23], v[128:131], v[212:215], v[20:23]
	v_mfma_f32_16x16x32_bf16 v[16:19], v[152:155], v[212:215], v[16:19]
	v_mfma_f32_16x16x32_bf16 v[4:7], v[128:131], v[220:223], v[4:7]
	v_mfma_f32_16x16x32_bf16 v[0:3], v[152:155], v[220:223], v[0:3]
	v_mfma_f32_16x16x32_bf16 v[40:43], v[180:183], v[208:211], v[32:35]
	v_mfma_f32_16x16x32_bf16 v[20:23], v[148:151], v[216:219], v[20:23]
	v_mfma_f32_16x16x32_bf16 v[16:19], v[180:183], v[216:219], v[16:19]
	v_mfma_f32_16x16x32_bf16 v[4:7], v[148:151], v[224:227], v[4:7]
	v_mfma_f32_16x16x32_bf16 v[0:3], v[180:183], v[224:227], v[0:3]
	s_barrier
	s_add_i32 s69, s69, 2
	s_add_u32 s56, s56, 0x100
	s_addc_u32 s57, s57, 0
	s_add_u32 s68, s68, 0x100
	s_addc_u32 s33, s33, 0
	s_cmp_gt_u32 s69, 13
	s_cbranch_scc0 .LBB0_1617
	v_readlane_b32 s68, v243, 59
	s_and_b64 vcc, exec, s[40:41]
	v_readlane_b32 s69, v243, 60
	s_cbranch_vccz .LBB0_1620
	s_barrier

; #define PG8_STAGE(bufoff, gbase, voff) do { _Pragma("unroll") for (int _i = 0; _i < 2; ++_i) \
;         __builtin_amdgcn_global_load_lds((const unsigned*)((const char*)(gbase) + (voff)[_i]), (PG8_LAS unsigned*)(lds + (bufoff) + ldsw + _i * 8192), 16, 0, 0); } while (0)
; #define PG8_LDA(dst, b, h) do { _Pragma("unroll") for (int m = 0; m < 4; ++m) _Pragma("unroll") for (int k = 0; k < 2; ++k) dst[m][k] = *(const PG8_LAS bf16x8*)(lds + PG8_SA(b, h) + aoff + m * 2048 + k * 1024); } while (0)
; #define PG8_LDB(dst, b, h) do { _Pragma("unroll") for (int n = 0; n < 2; ++n) _Pragma("unroll") for (int k = 0; k < 2; ++k) dst[n][k] = *(const PG8_LAS bf16x8*)(lds + PG8_SB(b, h) + boff + n * 2048 + k * 1024); } while (0)
; #define PG8_MMA(ai, bj, At, Bt) do { __builtin_amdgcn_s_setprio(1); _Pragma("unroll") for (int m = 0; m < 4; ++m) _Pragma("unroll") for (int n = 0; n < 2; ++n) _Pragma("unroll") for (int k = 0; k < 2; ++k) \
;         acc[ai][bj][m][n] = __builtin_amdgcn_mfma_f32_16x16x32_bf16(Bt[n][k], At[m][k], acc[ai][bj][m][n], 0, 0, 0); __builtin_amdgcn_s_setprio(0); } while (0)
; #define PG8_WAIT_V(n) asm volatile("s_waitcnt vmcnt(" #n ")" ::: "memory")
; #define PG8_WAIT_L(n) asm volatile("s_waitcnt lgkmcnt(" #n ")" ::: "memory")
; #define PG8_BAR __builtin_amdgcn_s_barrier()
; #define PG8_SCHED __builtin_amdgcn_sched_barrier(0)
; template <class Epi, class Sched, bool ALIGN_EPI = false, bool SP2 = false>
; __device__ __forceinline__ void gemm_phase(PG8_LAS unsigned char* lds, const Gemm g, const Sched& S, const Epi& E) {
;     ...
;             const bool last = (t == nt - 2);
;             const char* a1 = cA + (size_t)(t + 1) * kstep;
;             const char* a2 = last ? nA : cA + (size_t)(t + 2) * kstep; const char* b2 = last ? nB : cB + (size_t)(t + 2) * kstep;
;             const char* a3 = a2 + kstep; const char* b3 = b2 + kstep;
;             if (last && has_next) S.a_ready(nxt);
;             if constexpr (SP2) {
;             PG8_LDB(B0, 0, 0); PG8_LDB(B1, 0, 1); PG8_SCHED; PG8_LDA(At, 0, 0); PG8_STAGE(PG8_SA(1, 1), a1 + hstep, voffA);
;             PG8_WAIT_V(8); PG8_WAIT_L(0); PG8_BAR; PG8_MMA(0, 0, At, B0); PG8_MMA(0, 1, At, B1); PG8_BAR; PG8_SCHED;
;             PG8_LDA(At, 0, 1); PG8_STAGE(PG8_SB(0, 0), b2, voffB); PG8_STAGE(PG8_SB(0, 1), b2 + hstep, voffB); PG8_STAGE(PG8_SA(0, 0), a2, voffA);
.LBB0_1698:
	ds_read_b128 v[144:147], v153
	ds_read_b128 v[170:173], v153 offset:1024
	ds_read_b128 v[174:177], v153 offset:2048
	ds_read_b128 v[178:181], v153 offset:3072
	ds_read_b128 v[182:185], v154
	ds_read_b128 v[186:189], v154 offset:1024
	ds_read_b128 v[198:201], v154 offset:2048
	ds_read_b128 v[202:205], v154 offset:3072
	s_add_u32 s6, s60, 0xfffc0080
	s_addc_u32 s7, s61, -1
	s_cmp_eq_u32 s72, 12
	s_cselect_b32 s81, s29, s7
	s_cselect_b32 s80, s55, s6
	s_cselect_b32 s79, s53, s33
	s_cselect_b32 s78, s68, s69
	v_lshl_add_u64 v[148:149], s[60:61], 0, v[136:137]
	s_add_i32 m0, s43, 0xc000
	ds_read_b128 v[206:209], v155
	ds_read_b128 v[210:213], v155 offset:1024
	ds_read_b128 v[214:217], v155 offset:2048
	ds_read_b128 v[218:221], v155 offset:3072
	ds_read_b128 v[222:225], v155 offset:4096
	ds_read_b128 v[226:229], v155 offset:5120
	ds_read_b128 v[230:233], v155 offset:6144
	ds_read_b128 v[234:237], v155 offset:7168
	global_load_lds_dwordx4 v[148:149], off
	v_lshl_add_u64 v[148:149], s[60:61], 0, v[138:139]
	s_add_i32 m0, s43, 0xe000
	s_nop 0
	global_load_lds_dwordx4 v[148:149], off
	s_waitcnt vmcnt(8)
	s_waitcnt lgkmcnt(0)
	s_barrier
	s_waitcnt lgkmcnt(0)
	v_mfma_f32_16x16x32_bf16 v[124:127], v[144:147], v[206:209], v[124:127]
	v_mfma_f32_16x16x32_bf16 v[120:123], v[174:177], v[206:209], v[120:123]
	v_mfma_f32_16x16x32_bf16 v[108:111], v[144:147], v[214:217], v[108:111]
	v_mfma_f32_16x16x32_bf16 v[104:107], v[174:177], v[214:217], v[104:107]
	v_mfma_f32_16x16x32_bf16 v[92:95], v[144:147], v[222:225], v[92:95]
	v_mfma_f32_16x16x32_bf16 v[88:91], v[174:177], v[222:225], v[88:91]
	v_mfma_f32_16x16x32_bf16 v[76:79], v[144:147], v[230:233], v[76:79]
	v_mfma_f32_16x16x32_bf16 v[72:75], v[174:177], v[230:233], v[72:75]
	v_mfma_f32_16x16x32_bf16 v[124:127], v[170:173], v[210:213], v[124:127]
	v_mfma_f32_16x16x32_bf16 v[120:123], v[178:181], v[210:213], v[120:123]
	v_mfma_f32_16x16x32_bf16 v[108:111], v[170:173], v[218:221], v[108:111]
	v_mfma_f32_16x16x32_bf16 v[104:107], v[178:181], v[218:221], v[104:107]
	v_mfma_f32_16x16x32_bf16 v[92:95], v[170:173], v[226:229], v[92:95]
	v_mfma_f32_16x16x32_bf16 v[88:91], v[178:181], v[226:229], v[88:91]
	v_mfma_f32_16x16x32_bf16 v[76:79], v[170:173], v[234:237], v[76:79]
	v_mfma_f32_16x16x32_bf16 v[72:75], v[178:181], v[234:237], v[72:75]
	v_mfma_f32_16x16x32_bf16 v[116:119], v[182:185], v[206:209], v[116:119]
	v_mfma_f32_16x16x32_bf16 v[112:115], v[198:201], v[206:209], v[112:115]
	v_mfma_f32_16x16x32_bf16 v[100:103], v[182:185], v[214:217], v[100:103]
	v_mfma_f32_16x16x32_bf16 v[96:99], v[198:201], v[214:217], v[96:99]
	v_mfma_f32_16x16x32_bf16 v[84:87], v[182:185], v[222:225], v[84:87]
	v_mfma_f32_16x16x32_bf16 v[80:83], v[198:201], v[222:225], v[80:83]
	v_mfma_f32_16x16x32_bf16 v[68:71], v[182:185], v[230:233], v[68:71]
	v_mfma_f32_16x16x32_bf16 v[64:67], v[198:201], v[230:233], v[64:67]
	v_mfma_f32_16x16x32_bf16 v[116:119], v[186:189], v[210:213], v[116:119]
	v_mfma_f32_16x16x32_bf16 v[112:115], v[202:205], v[210:213], v[112:115]
	v_mfma_f32_16x16x32_bf16 v[100:103], v[186:189], v[218:221], v[100:103]
	v_mfma_f32_16x16x32_bf16 v[96:99], v[202:205], v[218:221], v[96:99]
	v_mfma_f32_16x16x32_bf16 v[84:87], v[186:189], v[226:229], v[84:87]
	v_mfma_f32_16x16x32_bf16 v[80:83], v[202:205], v[226:229], v[80:83]
	v_mfma_f32_16x16x32_bf16 v[68:71], v[186:189], v[234:237], v[68:71]
	v_mfma_f32_16x16x32_bf16 v[64:67], v[202:205], v[234:237], v[64:67]
	s_barrier
	s_add_i32 s6, s26, s42
	v_lshl_add_u64 v[148:149], s[78:79], 0, v[130:131]
	s_mov_b32 m0, s6
	ds_read_b128 v[206:209], v155 offset:16384
	ds_read_b128 v[210:213], v155 offset:17408
	ds_read_b128 v[214:217], v155 offset:18432
	ds_read_b128 v[218:221], v155 offset:19456
	ds_read_b128 v[222:225], v155 offset:20480
	ds_read_b128 v[226:229], v155 offset:21504
	ds_read_b128 v[230:233], v155 offset:22528
	ds_read_b128 v[234:237], v155 offset:23552
	global_load_lds_dwordx4 v[148:149], off
	s_add_i32 m0, s6, 0x2000
	s_add_u32 s6, s78, 0x40000
	v_lshl_add_u64 v[158:159], s[78:79], 0, v[134:135]
	s_addc_u32 s7, s79, 0
	s_add_i32 s73, s74, s42
	global_load_lds_dwordx4 v[158:159], off
	v_lshl_add_u64 v[164:165], s[6:7], 0, v[130:131]
	s_mov_b32 m0, s73
	v_lshl_add_u64 v[190:191], s[80:81], 0, v[132:133]
	global_load_lds_dwordx4 v[164:165], off
	v_lshl_add_u64 v[164:165], s[6:7], 0, v[134:135]
	s_add_i32 m0, s73, 0x2000
	s_nop 0
	global_load_lds_dwordx4 v[164:165], off
	v_lshl_add_u64 v[164:165], s[80:81], 0, v[128:129]
	s_mov_b32 m0, s43
	s_nop 0
	global_load_lds_dwordx4 v[164:165], off
	s_mov_b32 m0, s44
	s_nop 0
	global_load_lds_dwordx4 v[190:191], off
	s_waitcnt vmcnt(8)
	s_waitcnt lgkmcnt(0)
	s_barrier
; #define PG8_STAGE(bufoff, gbase, voff) do { _Pragma("unroll") for (int _i = 0; _i < 2; ++_i) \
;         __builtin_amdgcn_global_load_lds((const unsigned*)((const char*)(gbase) + (voff)[_i]), (PG8_LAS unsigned*)(lds + (bufoff) + ldsw + _i * 8192), 16, 0, 0); } while (0)
; #define PG8_LDA(dst, b, h) do { _Pragma("unroll") for (int m = 0; m < 4; ++m) _Pragma("unroll") for (int k = 0; k < 2; ++k) dst[m][k] = *(const PG8_LAS bf16x8*)(lds + PG8_SA(b, h) + aoff + m * 2048 + k * 1024); } while (0)
; #define PG8_LDB(dst, b, h) do { _Pragma("unroll") for (int n = 0; n < 2; ++n) _Pragma("unroll") for (int k = 0; k < 2; ++k) dst[n][k] = *(const PG8_LAS bf16x8*)(lds + PG8_SB(b, h) + boff + n * 2048 + k * 1024); } while (0)
; #define PG8_MMA(ai, bj, At, Bt) do { __builtin_amdgcn_s_setprio(1); _Pragma("unroll") for (int m = 0; m < 4; ++m) _Pragma("unroll") for (int n = 0; n < 2; ++n) _Pragma("unroll") for (int k = 0; k < 2; ++k) \
;         acc[ai][bj][m][n] = __builtin_amdgcn_mfma_f32_16x16x32_bf16(Bt[n][k], At[m][k], acc[ai][bj][m][n], 0, 0, 0); __builtin_amdgcn_s_setprio(0); } while (0)
; #define PG8_WAIT_V(n) asm volatile("s_waitcnt vmcnt(" #n ")" ::: "memory")
; #define PG8_WAIT_L(n) asm volatile("s_waitcnt lgkmcnt(" #n ")" ::: "memory")
; #define PG8_BAR __builtin_amdgcn_s_barrier()
; #define PG8_SCHED __builtin_amdgcn_sched_barrier(0)
; template <class Epi, class Sched, bool ALIGN_EPI = false, bool SP2 = false>
; __device__ __forceinline__ void gemm_phase(PG8_LAS unsigned char* lds, const Gemm g, const Sched& S, const Epi& E) {
;     ...
;             PG8_WAIT_V(8); PG8_WAIT_L(0); PG8_BAR; PG8_MMA(1, 0, At, B0); PG8_MMA(1, 1, At, B1); PG8_BAR; PG8_SCHED;
;             PG8_LDB(B0, 1, 0); PG8_LDB(B1, 1, 1); PG8_SCHED; PG8_LDA(At, 1, 0); PG8_STAGE(PG8_SA(0, 1), a2 + hstep, voffA);
;             PG8_WAIT_V(8); PG8_WAIT_L(0); PG8_BAR; PG8_MMA(0, 0, At, B0); PG8_MMA(0, 1, At, B1); PG8_BAR; PG8_SCHED;
	s_waitcnt lgkmcnt(0)
	v_mfma_f32_16x16x32_bf16 v[60:63], v[144:147], v[206:209], v[60:63]
	v_mfma_f32_16x16x32_bf16 v[56:59], v[174:177], v[206:209], v[56:59]
	v_mfma_f32_16x16x32_bf16 v[44:47], v[144:147], v[214:217], v[44:47]
	v_mfma_f32_16x16x32_bf16 v[40:43], v[174:177], v[214:217], v[40:43]
	v_mfma_f32_16x16x32_bf16 v[28:31], v[144:147], v[222:225], v[28:31]
	v_mfma_f32_16x16x32_bf16 v[24:27], v[174:177], v[222:225], v[24:27]
	v_mfma_f32_16x16x32_bf16 v[12:15], v[144:147], v[230:233], v[12:15]
	v_mfma_f32_16x16x32_bf16 v[8:11], v[174:177], v[230:233], v[8:11]
	v_mfma_f32_16x16x32_bf16 v[60:63], v[170:173], v[210:213], v[60:63]
	v_mfma_f32_16x16x32_bf16 v[56:59], v[178:181], v[210:213], v[56:59]
	v_mfma_f32_16x16x32_bf16 v[44:47], v[170:173], v[218:221], v[44:47]
	v_mfma_f32_16x16x32_bf16 v[40:43], v[178:181], v[218:221], v[40:43]
	v_mfma_f32_16x16x32_bf16 v[28:31], v[170:173], v[226:229], v[28:31]
	v_mfma_f32_16x16x32_bf16 v[24:27], v[178:181], v[226:229], v[24:27]
	v_mfma_f32_16x16x32_bf16 v[12:15], v[170:173], v[234:237], v[12:15]
	v_mfma_f32_16x16x32_bf16 v[8:11], v[178:181], v[234:237], v[8:11]
	v_mfma_f32_16x16x32_bf16 v[52:55], v[182:185], v[206:209], v[52:55]
	v_mfma_f32_16x16x32_bf16 v[48:51], v[198:201], v[206:209], v[48:51]
	v_mfma_f32_16x16x32_bf16 v[36:39], v[182:185], v[214:217], v[36:39]
	v_mfma_f32_16x16x32_bf16 v[32:35], v[198:201], v[214:217], v[32:35]
	v_mfma_f32_16x16x32_bf16 v[20:23], v[182:185], v[222:225], v[20:23]
	v_mfma_f32_16x16x32_bf16 v[16:19], v[198:201], v[222:225], v[16:19]
	v_mfma_f32_16x16x32_bf16 v[4:7], v[182:185], v[230:233], v[4:7]
	v_mfma_f32_16x16x32_bf16 v[0:3], v[198:201], v[230:233], v[0:3]
	v_mfma_f32_16x16x32_bf16 v[52:55], v[186:189], v[210:213], v[52:55]
	v_mfma_f32_16x16x32_bf16 v[48:51], v[202:205], v[210:213], v[48:51]
	v_mfma_f32_16x16x32_bf16 v[36:39], v[186:189], v[218:221], v[36:39]
	v_mfma_f32_16x16x32_bf16 v[32:35], v[202:205], v[218:221], v[32:35]
	v_mfma_f32_16x16x32_bf16 v[20:23], v[186:189], v[226:229], v[20:23]
	v_mfma_f32_16x16x32_bf16 v[16:19], v[202:205], v[226:229], v[16:19]
	v_mfma_f32_16x16x32_bf16 v[4:7], v[186:189], v[234:237], v[4:7]
	v_mfma_f32_16x16x32_bf16 v[0:3], v[202:205], v[234:237], v[0:3]
	s_barrier
	s_add_i32 s73, 0, 0x18000
	v_add_u32_e32 v157, s73, v151
	s_add_i32 s82, 0, 0x1c000
	ds_read_b128 v[144:147], v157
	ds_read_b128 v[170:173], v157 offset:1024
	ds_read_b128 v[174:177], v157 offset:2048
	ds_read_b128 v[178:181], v157 offset:3072
	v_add_u32_e32 v157, s82, v151
	ds_read_b128 v[182:185], v157
	ds_read_b128 v[186:189], v157 offset:1024
	ds_read_b128 v[198:201], v157 offset:2048
	ds_read_b128 v[202:205], v157 offset:3072
	s_add_u32 s6, s80, 0x40000
	s_addc_u32 s7, s81, 0
	s_mov_b32 m0, s45
	v_lshl_add_u64 v[238:239], s[6:7], 0, v[128:129]
	ds_read_b128 v[206:209], v155 offset:32768
	ds_read_b128 v[210:213], v155 offset:33792
	ds_read_b128 v[214:217], v155 offset:34816
	ds_read_b128 v[218:221], v155 offset:35840
	ds_read_b128 v[222:225], v155 offset:36864
	ds_read_b128 v[226:229], v155 offset:37888
	ds_read_b128 v[230:233], v155 offset:38912
	ds_read_b128 v[234:237], v155 offset:39936
	global_load_lds_dwordx4 v[238:239], off
	v_lshl_add_u64 v[238:239], s[6:7], 0, v[132:133]
	s_mov_b32 m0, s67
	s_nop 0
	global_load_lds_dwordx4 v[238:239], off
	s_waitcnt vmcnt(8)
	s_waitcnt lgkmcnt(0)
	s_barrier
	s_waitcnt lgkmcnt(0)
	v_mfma_f32_16x16x32_bf16 v[124:127], v[144:147], v[206:209], v[124:127]
	v_mfma_f32_16x16x32_bf16 v[120:123], v[174:177], v[206:209], v[120:123]
	v_mfma_f32_16x16x32_bf16 v[108:111], v[144:147], v[214:217], v[108:111]
	v_mfma_f32_16x16x32_bf16 v[104:107], v[174:177], v[214:217], v[104:107]
	v_mfma_f32_16x16x32_bf16 v[92:95], v[144:147], v[222:225], v[92:95]
	v_mfma_f32_16x16x32_bf16 v[88:91], v[174:177], v[222:225], v[88:91]
	v_mfma_f32_16x16x32_bf16 v[76:79], v[144:147], v[230:233], v[76:79]
	v_mfma_f32_16x16x32_bf16 v[72:75], v[174:177], v[230:233], v[72:75]
	v_mfma_f32_16x16x32_bf16 v[124:127], v[170:173], v[210:213], v[124:127]
	v_mfma_f32_16x16x32_bf16 v[120:123], v[178:181], v[210:213], v[120:123]
	v_mfma_f32_16x16x32_bf16 v[108:111], v[170:173], v[218:221], v[108:111]
	v_mfma_f32_16x16x32_bf16 v[104:107], v[178:181], v[218:221], v[104:107]
	v_mfma_f32_16x16x32_bf16 v[92:95], v[170:173], v[226:229], v[92:95]
	v_mfma_f32_16x16x32_bf16 v[88:91], v[178:181], v[226:229], v[88:91]
	v_mfma_f32_16x16x32_bf16 v[76:79], v[170:173], v[234:237], v[76:79]
	v_mfma_f32_16x16x32_bf16 v[72:75], v[178:181], v[234:237], v[72:75]
	v_mfma_f32_16x16x32_bf16 v[116:119], v[182:185], v[206:209], v[116:119]
	v_mfma_f32_16x16x32_bf16 v[112:115], v[198:201], v[206:209], v[112:115]
	v_mfma_f32_16x16x32_bf16 v[100:103], v[182:185], v[214:217], v[100:103]
	v_mfma_f32_16x16x32_bf16 v[96:99], v[198:201], v[214:217], v[96:99]
	v_mfma_f32_16x16x32_bf16 v[84:87], v[182:185], v[222:225], v[84:87]
	v_mfma_f32_16x16x32_bf16 v[80:83], v[198:201], v[222:225], v[80:83]
	v_mfma_f32_16x16x32_bf16 v[68:71], v[182:185], v[230:233], v[68:71]
	v_mfma_f32_16x16x32_bf16 v[64:67], v[198:201], v[230:233], v[64:67]
	v_mfma_f32_16x16x32_bf16 v[116:119], v[186:189], v[210:213], v[116:119]
	v_mfma_f32_16x16x32_bf16 v[112:115], v[202:205], v[210:213], v[112:115]
	v_mfma_f32_16x16x32_bf16 v[100:103], v[186:189], v[218:221], v[100:103]
	v_mfma_f32_16x16x32_bf16 v[96:99], v[202:205], v[218:221], v[96:99]
	v_mfma_f32_16x16x32_bf16 v[84:87], v[186:189], v[226:229], v[84:87]
	v_mfma_f32_16x16x32_bf16 v[80:83], v[202:205], v[226:229], v[80:83]
	v_mfma_f32_16x16x32_bf16 v[68:71], v[186:189], v[234:237], v[68:71]
	v_mfma_f32_16x16x32_bf16 v[64:67], v[202:205], v[234:237], v[64:67]
	s_barrier
; #define PG8_STAGE(bufoff, gbase, voff) do { _Pragma("unroll") for (int _i = 0; _i < 2; ++_i) \
;         __builtin_amdgcn_global_load_lds((const unsigned*)((const char*)(gbase) + (voff)[_i]), (PG8_LAS unsigned*)(lds + (bufoff) + ldsw + _i * 8192), 16, 0, 0); } while (0)
; #define PG8_LDA(dst, b, h) do { _Pragma("unroll") for (int m = 0; m < 4; ++m) _Pragma("unroll") for (int k = 0; k < 2; ++k) dst[m][k] = *(const PG8_LAS bf16x8*)(lds + PG8_SA(b, h) + aoff + m * 2048 + k * 1024); } while (0)
; #define PG8_MMA(ai, bj, At, Bt) do { __builtin_amdgcn_s_setprio(1); _Pragma("unroll") for (int m = 0; m < 4; ++m) _Pragma("unroll") for (int n = 0; n < 2; ++n) _Pragma("unroll") for (int k = 0; k < 2; ++k) \
;         acc[ai][bj][m][n] = __builtin_amdgcn_mfma_f32_16x16x32_bf16(Bt[n][k], At[m][k], acc[ai][bj][m][n], 0, 0, 0); __builtin_amdgcn_s_setprio(0); } while (0)
; #define PG8_WAIT_V(n) asm volatile("s_waitcnt vmcnt(" #n ")" ::: "memory")
; #define PG8_WAIT_L(n) asm volatile("s_waitcnt lgkmcnt(" #n ")" ::: "memory")
; #define PG8_BAR __builtin_amdgcn_s_barrier()
; #define PG8_SCHED __builtin_amdgcn_sched_barrier(0)
; template <class Epi, class Sched, bool ALIGN_EPI = false, bool SP2 = false>
; __device__ __forceinline__ void gemm_phase(PG8_LAS unsigned char* lds, const Gemm g, const Sched& S, const Epi& E) {
;     ...
;             PG8_LDA(At, 1, 1); PG8_STAGE(PG8_SB(1, 0), b3, voffB); PG8_STAGE(PG8_SB(1, 1), b3 + hstep, voffB); PG8_STAGE(PG8_SA(1, 0), a3, voffA);
;             PG8_WAIT_V(8); PG8_WAIT_L(0); PG8_BAR; PG8_MMA(1, 0, At, B0); PG8_MMA(1, 1, At, B1); PG8_BAR; PG8_SCHED;
	s_add_i32 s6, s73, s42
	v_lshl_add_u64 v[148:149], v[148:149], 0, s[40:41]
	s_mov_b32 m0, s6
	ds_read_b128 v[206:209], v155 offset:49152
	ds_read_b128 v[210:213], v155 offset:50176
	ds_read_b128 v[214:217], v155 offset:51200
	ds_read_b128 v[218:221], v155 offset:52224
	ds_read_b128 v[222:225], v155 offset:53248
	ds_read_b128 v[226:229], v155 offset:54272
	ds_read_b128 v[230:233], v155 offset:55296
	ds_read_b128 v[234:237], v155 offset:56320
	global_load_lds_dwordx4 v[148:149], off
	s_add_i32 m0, s6, 0x2000
	s_add_u32 s6, s78, 0x40080
	v_lshl_add_u64 v[148:149], v[158:159], 0, s[40:41]
	s_addc_u32 s7, s79, 0
	s_add_i32 s73, s82, s42
	global_load_lds_dwordx4 v[148:149], off
	v_lshl_add_u64 v[148:149], s[6:7], 0, v[130:131]
	s_mov_b32 m0, s73
	s_nop 0
	global_load_lds_dwordx4 v[148:149], off
	v_lshl_add_u64 v[148:149], s[6:7], 0, v[134:135]
	s_add_i32 m0, s73, 0x2000
	s_nop 0
	global_load_lds_dwordx4 v[148:149], off
	v_lshl_add_u64 v[148:149], v[164:165], 0, s[40:41]
	s_mov_b32 m0, s4
	s_nop 0
	global_load_lds_dwordx4 v[148:149], off
	v_lshl_add_u64 v[148:149], v[190:191], 0, s[40:41]
	s_mov_b32 m0, s77
	s_nop 0
	global_load_lds_dwordx4 v[148:149], off
	s_waitcnt vmcnt(8)
	s_waitcnt lgkmcnt(0)
	s_barrier
	s_waitcnt lgkmcnt(0)
	v_mfma_f32_16x16x32_bf16 v[60:63], v[144:147], v[206:209], v[60:63]
	v_mfma_f32_16x16x32_bf16 v[56:59], v[174:177], v[206:209], v[56:59]
	v_mfma_f32_16x16x32_bf16 v[44:47], v[144:147], v[214:217], v[44:47]
	v_mfma_f32_16x16x32_bf16 v[40:43], v[174:177], v[214:217], v[40:43]
	v_mfma_f32_16x16x32_bf16 v[28:31], v[144:147], v[222:225], v[28:31]
	v_mfma_f32_16x16x32_bf16 v[24:27], v[174:177], v[222:225], v[24:27]
	v_mfma_f32_16x16x32_bf16 v[12:15], v[144:147], v[230:233], v[12:15]
	v_mfma_f32_16x16x32_bf16 v[8:11], v[174:177], v[230:233], v[8:11]
	v_mfma_f32_16x16x32_bf16 v[60:63], v[170:173], v[210:213], v[60:63]
	v_mfma_f32_16x16x32_bf16 v[56:59], v[178:181], v[210:213], v[56:59]
	v_mfma_f32_16x16x32_bf16 v[44:47], v[170:173], v[218:221], v[44:47]
	v_mfma_f32_16x16x32_bf16 v[40:43], v[178:181], v[218:221], v[40:43]
	v_mfma_f32_16x16x32_bf16 v[28:31], v[170:173], v[226:229], v[28:31]
	v_mfma_f32_16x16x32_bf16 v[24:27], v[178:181], v[226:229], v[24:27]
	v_mfma_f32_16x16x32_bf16 v[12:15], v[170:173], v[234:237], v[12:15]
	v_mfma_f32_16x16x32_bf16 v[8:11], v[178:181], v[234:237], v[8:11]
	v_mfma_f32_16x16x32_bf16 v[52:55], v[182:185], v[206:209], v[52:55]
	v_mfma_f32_16x16x32_bf16 v[48:51], v[198:201], v[206:209], v[48:51]
	v_mfma_f32_16x16x32_bf16 v[36:39], v[182:185], v[214:217], v[36:39]
	v_mfma_f32_16x16x32_bf16 v[32:35], v[198:201], v[214:217], v[32:35]
	v_mfma_f32_16x16x32_bf16 v[20:23], v[182:185], v[222:225], v[20:23]
	v_mfma_f32_16x16x32_bf16 v[16:19], v[198:201], v[222:225], v[16:19]
	v_mfma_f32_16x16x32_bf16 v[4:7], v[182:185], v[230:233], v[4:7]
	v_mfma_f32_16x16x32_bf16 v[0:3], v[198:201], v[230:233], v[0:3]
	v_mfma_f32_16x16x32_bf16 v[52:55], v[186:189], v[210:213], v[52:55]
	v_mfma_f32_16x16x32_bf16 v[48:51], v[202:205], v[210:213], v[48:51]
	v_mfma_f32_16x16x32_bf16 v[36:39], v[186:189], v[218:221], v[36:39]
	v_mfma_f32_16x16x32_bf16 v[32:35], v[202:205], v[218:221], v[32:35]
	v_mfma_f32_16x16x32_bf16 v[20:23], v[186:189], v[226:229], v[20:23]
	v_mfma_f32_16x16x32_bf16 v[16:19], v[202:205], v[226:229], v[16:19]
	v_mfma_f32_16x16x32_bf16 v[4:7], v[186:189], v[234:237], v[4:7]
	v_mfma_f32_16x16x32_bf16 v[0:3], v[202:205], v[234:237], v[0:3]
	s_barrier
	s_add_i32 s72, s72, 2
	s_add_u32 s60, s60, 0x100
	s_addc_u32 s61, s61, 0
	s_add_u32 s69, s69, 0x100
	s_addc_u32 s33, s33, 0
	s_cmp_gt_u32 s72, 13
	s_cbranch_scc0 .LBB0_1698
	s_and_b64 vcc, exec, s[50:51]
	s_cbranch_vccz .LBB0_1701
	s_barrier

; #define PG8_STAGE(bufoff, gbase, voff) do { _Pragma("unroll") for (int _i = 0; _i < 2; ++_i) \
;         __builtin_amdgcn_global_load_lds((const unsigned*)((const char*)(gbase) + (voff)[_i]), (PG8_LAS unsigned*)(lds + (bufoff) + ldsw + _i * 8192), 16, 0, 0); } while (0)
; #define PG8_LDA(dst, b, h) do { _Pragma("unroll") for (int m = 0; m < 4; ++m) _Pragma("unroll") for (int k = 0; k < 2; ++k) dst[m][k] = *(const PG8_LAS bf16x8*)(lds + PG8_SA(b, h) + aoff + m * 2048 + k * 1024); } while (0)
; #define PG8_LDB(dst, b, h) do { _Pragma("unroll") for (int n = 0; n < 2; ++n) _Pragma("unroll") for (int k = 0; k < 2; ++k) dst[n][k] = *(const PG8_LAS bf16x8*)(lds + PG8_SB(b, h) + boff + n * 2048 + k * 1024); } while (0)
; #define PG8_MMA(ai, bj, At, Bt) do { __builtin_amdgcn_s_setprio(1); _Pragma("unroll") for (int m = 0; m < 4; ++m) _Pragma("unroll") for (int n = 0; n < 2; ++n) _Pragma("unroll") for (int k = 0; k < 2; ++k) \
;         acc[ai][bj][m][n] = __builtin_amdgcn_mfma_f32_16x16x32_bf16(Bt[n][k], At[m][k], acc[ai][bj][m][n], 0, 0, 0); __builtin_amdgcn_s_setprio(0); } while (0)
; #define PG8_WAIT_V(n) asm volatile("s_waitcnt vmcnt(" #n ")" ::: "memory")
; #define PG8_BAR __builtin_amdgcn_s_barrier()
; template <class Epi, class Sched, bool ALIGN_EPI = false, bool SP2 = false>
; __device__ __forceinline__ void gemm_phase(PG8_LAS unsigned char* lds, const Gemm g, const Sched& S, const Epi& E) {
;     ...
;         for (int t = 0; t < nt; t += 2) {
;             const bool last = (t == nt - 2);
;             const char* a1 = cA + (size_t)(t + 1) * kstep;
;             const char* a2 = last ? nA : cA + (size_t)(t + 2) * kstep; const char* b2 = last ? nB : cB + (size_t)(t + 2) * kstep;
;             const char* a3 = a2 + kstep; const char* b3 = b2 + kstep;
;             if (last && has_next) S.a_ready(nxt);
;             if constexpr (SP2) {
;             PG8_LDB(B0, 0, 0); PG8_LDB(B1, 0, 1); PG8_SCHED; PG8_LDA(At, 0, 0); PG8_STAGE(PG8_SA(1, 1), a1 + hstep, voffA);
;             PG8_WAIT_V(8); PG8_WAIT_L(0); PG8_BAR; PG8_MMA(0, 0, At, B0); PG8_MMA(0, 1, At, B1); PG8_BAR; PG8_SCHED;
;             PG8_LDA(At, 0, 1); PG8_STAGE(PG8_SB(0, 0), b2, voffB); PG8_STAGE(PG8_SB(0, 1), b2 + hstep, voffB); PG8_STAGE(PG8_SA(0, 0), a2, voffA);
;             PG8_WAIT_V(8); PG8_WAIT_L(0); PG8_BAR; PG8_MMA(1, 0, At, B0); PG8_MMA(1, 1, At, B1); PG8_BAR; PG8_SCHED;
.LBB0_1822:
	ds_read_b128 v[144:147], v154
	ds_read_b128 v[168:171], v154 offset:1024
	ds_read_b128 v[172:175], v154 offset:2048
	ds_read_b128 v[176:179], v154 offset:3072
	ds_read_b128 v[180:183], v155
	ds_read_b128 v[184:187], v155 offset:1024
	ds_read_b128 v[188:191], v155 offset:2048
	ds_read_b128 v[198:201], v155 offset:3072
	s_add_u32 s6, s50, 0xfffc0080
	s_addc_u32 s7, s51, -1
	s_cmp_eq_u32 s72, 12
	s_cselect_b32 s55, s39, s7
	s_cselect_b32 s54, s69, s6
	s_cselect_b32 s53, s37, s33
	s_cselect_b32 s52, s74, s75
	v_lshl_add_u64 v[148:149], s[50:51], 0, v[136:137]
	s_add_i32 m0, s27, 0xc000
	ds_read_b128 v[202:205], v156
	ds_read_b128 v[206:209], v156 offset:1024
	ds_read_b128 v[210:213], v156 offset:2048
	ds_read_b128 v[214:217], v156 offset:3072
	ds_read_b128 v[218:221], v156 offset:4096
	ds_read_b128 v[222:225], v156 offset:5120
	ds_read_b128 v[226:229], v156 offset:6144
	ds_read_b128 v[230:233], v156 offset:7168
	global_load_lds_dwordx4 v[148:149], off
	v_lshl_add_u64 v[148:149], s[50:51], 0, v[138:139]
	s_add_i32 m0, s27, 0xe000
	s_nop 0
	global_load_lds_dwordx4 v[148:149], off
	s_waitcnt vmcnt(8)
	s_waitcnt lgkmcnt(0)
	s_barrier
	s_waitcnt lgkmcnt(0)
	v_mfma_f32_16x16x32_bf16 v[124:127], v[144:147], v[202:205], v[124:127]
	v_mfma_f32_16x16x32_bf16 v[116:119], v[172:175], v[202:205], v[116:119]
	v_mfma_f32_16x16x32_bf16 v[108:111], v[144:147], v[210:213], v[108:111]
	v_mfma_f32_16x16x32_bf16 v[100:103], v[172:175], v[210:213], v[100:103]
	v_mfma_f32_16x16x32_bf16 v[92:95], v[144:147], v[218:221], v[92:95]
	v_mfma_f32_16x16x32_bf16 v[84:87], v[172:175], v[218:221], v[84:87]
	v_mfma_f32_16x16x32_bf16 v[76:79], v[144:147], v[226:229], v[76:79]
	v_mfma_f32_16x16x32_bf16 v[68:71], v[172:175], v[226:229], v[68:71]
	v_mfma_f32_16x16x32_bf16 v[124:127], v[168:171], v[206:209], v[124:127]
	v_mfma_f32_16x16x32_bf16 v[116:119], v[176:179], v[206:209], v[116:119]
	v_mfma_f32_16x16x32_bf16 v[108:111], v[168:171], v[214:217], v[108:111]
	v_mfma_f32_16x16x32_bf16 v[100:103], v[176:179], v[214:217], v[100:103]
	v_mfma_f32_16x16x32_bf16 v[92:95], v[168:171], v[222:225], v[92:95]
	v_mfma_f32_16x16x32_bf16 v[84:87], v[176:179], v[222:225], v[84:87]
	v_mfma_f32_16x16x32_bf16 v[76:79], v[168:171], v[230:233], v[76:79]
	v_mfma_f32_16x16x32_bf16 v[68:71], v[176:179], v[230:233], v[68:71]
	v_mfma_f32_16x16x32_bf16 v[120:123], v[180:183], v[202:205], v[120:123]
	v_mfma_f32_16x16x32_bf16 v[112:115], v[188:191], v[202:205], v[112:115]
	v_mfma_f32_16x16x32_bf16 v[104:107], v[180:183], v[210:213], v[104:107]
	v_mfma_f32_16x16x32_bf16 v[96:99], v[188:191], v[210:213], v[96:99]
	v_mfma_f32_16x16x32_bf16 v[88:91], v[180:183], v[218:221], v[88:91]
	v_mfma_f32_16x16x32_bf16 v[80:83], v[188:191], v[218:221], v[80:83]
	v_mfma_f32_16x16x32_bf16 v[72:75], v[180:183], v[226:229], v[72:75]
	v_mfma_f32_16x16x32_bf16 v[64:67], v[188:191], v[226:229], v[64:67]
	v_mfma_f32_16x16x32_bf16 v[120:123], v[184:187], v[206:209], v[120:123]
	v_mfma_f32_16x16x32_bf16 v[112:115], v[198:201], v[206:209], v[112:115]
	v_mfma_f32_16x16x32_bf16 v[104:107], v[184:187], v[214:217], v[104:107]
	v_mfma_f32_16x16x32_bf16 v[96:99], v[198:201], v[214:217], v[96:99]
	v_mfma_f32_16x16x32_bf16 v[88:91], v[184:187], v[222:225], v[88:91]
	v_mfma_f32_16x16x32_bf16 v[80:83], v[198:201], v[222:225], v[80:83]
	v_mfma_f32_16x16x32_bf16 v[72:75], v[184:187], v[230:233], v[72:75]
	v_mfma_f32_16x16x32_bf16 v[64:67], v[198:201], v[230:233], v[64:67]
	s_barrier
	s_add_i32 s6, s59, s26
	v_lshl_add_u64 v[148:149], s[52:53], 0, v[132:133]
	s_mov_b32 m0, s6
	ds_read_b128 v[202:205], v156 offset:16384
	ds_read_b128 v[206:209], v156 offset:17408
	ds_read_b128 v[210:213], v156 offset:18432
	ds_read_b128 v[214:217], v156 offset:19456
	ds_read_b128 v[218:221], v156 offset:20480
	ds_read_b128 v[222:225], v156 offset:21504
	ds_read_b128 v[226:229], v156 offset:22528
	ds_read_b128 v[230:233], v156 offset:23552
	global_load_lds_dwordx4 v[148:149], off
	s_add_i32 m0, s6, 0x2000
	s_add_u32 s6, s52, 0x40000
	v_lshl_add_u64 v[158:159], s[52:53], 0, v[128:129]
	s_addc_u32 s7, s53, 0
	s_add_i32 s73, s60, s26
	global_load_lds_dwordx4 v[158:159], off
	v_lshl_add_u64 v[164:165], s[6:7], 0, v[132:133]
	s_mov_b32 m0, s73
	v_lshl_add_u64 v[234:235], s[54:55], 0, v[130:131]
	global_load_lds_dwordx4 v[164:165], off
	v_lshl_add_u64 v[164:165], s[6:7], 0, v[128:129]
	s_add_i32 m0, s73, 0x2000
	s_nop 0
	global_load_lds_dwordx4 v[164:165], off
	v_lshl_add_u64 v[164:165], s[54:55], 0, v[134:135]
	s_mov_b32 m0, s27
	s_nop 0
	global_load_lds_dwordx4 v[164:165], off
	s_mov_b32 m0, s42
	s_nop 0
	global_load_lds_dwordx4 v[234:235], off
	s_waitcnt vmcnt(8)
	s_waitcnt lgkmcnt(0)
	s_barrier
; #define PG8_STAGE(bufoff, gbase, voff) do { _Pragma("unroll") for (int _i = 0; _i < 2; ++_i) \
;         __builtin_amdgcn_global_load_lds((const unsigned*)((const char*)(gbase) + (voff)[_i]), (PG8_LAS unsigned*)(lds + (bufoff) + ldsw + _i * 8192), 16, 0, 0); } while (0)
; #define PG8_LDA(dst, b, h) do { _Pragma("unroll") for (int m = 0; m < 4; ++m) _Pragma("unroll") for (int k = 0; k < 2; ++k) dst[m][k] = *(const PG8_LAS bf16x8*)(lds + PG8_SA(b, h) + aoff + m * 2048 + k * 1024); } while (0)
; #define PG8_LDB(dst, b, h) do { _Pragma("unroll") for (int n = 0; n < 2; ++n) _Pragma("unroll") for (int k = 0; k < 2; ++k) dst[n][k] = *(const PG8_LAS bf16x8*)(lds + PG8_SB(b, h) + boff + n * 2048 + k * 1024); } while (0)
; #define PG8_MMA(ai, bj, At, Bt) do { __builtin_amdgcn_s_setprio(1); _Pragma("unroll") for (int m = 0; m < 4; ++m) _Pragma("unroll") for (int n = 0; n < 2; ++n) _Pragma("unroll") for (int k = 0; k < 2; ++k) \
;         acc[ai][bj][m][n] = __builtin_amdgcn_mfma_f32_16x16x32_bf16(Bt[n][k], At[m][k], acc[ai][bj][m][n], 0, 0, 0); __builtin_amdgcn_s_setprio(0); } while (0)
; #define PG8_WAIT_V(n) asm volatile("s_waitcnt vmcnt(" #n ")" ::: "memory")
; #define PG8_WAIT_L(n) asm volatile("s_waitcnt lgkmcnt(" #n ")" ::: "memory")
; #define PG8_BAR __builtin_amdgcn_s_barrier()
; #define PG8_SCHED __builtin_amdgcn_sched_barrier(0)
; template <class Epi, class Sched, bool ALIGN_EPI = false, bool SP2 = false>
; __device__ __forceinline__ void gemm_phase(PG8_LAS unsigned char* lds, const Gemm g, const Sched& S, const Epi& E) {
;     ...
;             PG8_WAIT_V(8); PG8_WAIT_L(0); PG8_BAR; PG8_MMA(1, 0, At, B0); PG8_MMA(1, 1, At, B1); PG8_BAR; PG8_SCHED;
;             PG8_LDB(B0, 1, 0); PG8_LDB(B1, 1, 1); PG8_SCHED; PG8_LDA(At, 1, 0); PG8_STAGE(PG8_SA(0, 1), a2 + hstep, voffA);
;             PG8_WAIT_V(8); PG8_WAIT_L(0); PG8_BAR; PG8_MMA(0, 0, At, B0); PG8_MMA(0, 1, At, B1); PG8_BAR; PG8_SCHED;
	s_waitcnt lgkmcnt(0)
	v_mfma_f32_16x16x32_bf16 v[60:63], v[144:147], v[202:205], v[60:63]
	v_mfma_f32_16x16x32_bf16 v[52:55], v[172:175], v[202:205], v[52:55]
	v_mfma_f32_16x16x32_bf16 v[44:47], v[144:147], v[210:213], v[44:47]
	v_mfma_f32_16x16x32_bf16 v[36:39], v[172:175], v[210:213], v[36:39]
	v_mfma_f32_16x16x32_bf16 v[28:31], v[144:147], v[218:221], v[28:31]
	v_mfma_f32_16x16x32_bf16 v[20:23], v[172:175], v[218:221], v[20:23]
	v_mfma_f32_16x16x32_bf16 v[12:15], v[144:147], v[226:229], v[12:15]
	v_mfma_f32_16x16x32_bf16 v[4:7], v[172:175], v[226:229], v[4:7]
	v_mfma_f32_16x16x32_bf16 v[60:63], v[168:171], v[206:209], v[60:63]
	v_mfma_f32_16x16x32_bf16 v[52:55], v[176:179], v[206:209], v[52:55]
	v_mfma_f32_16x16x32_bf16 v[44:47], v[168:171], v[214:217], v[44:47]
	v_mfma_f32_16x16x32_bf16 v[36:39], v[176:179], v[214:217], v[36:39]
	v_mfma_f32_16x16x32_bf16 v[28:31], v[168:171], v[222:225], v[28:31]
	v_mfma_f32_16x16x32_bf16 v[20:23], v[176:179], v[222:225], v[20:23]
	v_mfma_f32_16x16x32_bf16 v[12:15], v[168:171], v[230:233], v[12:15]
	v_mfma_f32_16x16x32_bf16 v[4:7], v[176:179], v[230:233], v[4:7]
	v_mfma_f32_16x16x32_bf16 v[56:59], v[180:183], v[202:205], v[56:59]
	v_mfma_f32_16x16x32_bf16 v[48:51], v[188:191], v[202:205], v[48:51]
	v_mfma_f32_16x16x32_bf16 v[40:43], v[180:183], v[210:213], v[40:43]
	v_mfma_f32_16x16x32_bf16 v[32:35], v[188:191], v[210:213], v[32:35]
	v_mfma_f32_16x16x32_bf16 v[24:27], v[180:183], v[218:221], v[24:27]
	v_mfma_f32_16x16x32_bf16 v[16:19], v[188:191], v[218:221], v[16:19]
	v_mfma_f32_16x16x32_bf16 v[8:11], v[180:183], v[226:229], v[8:11]
	v_mfma_f32_16x16x32_bf16 v[0:3], v[188:191], v[226:229], v[0:3]
	v_mfma_f32_16x16x32_bf16 v[56:59], v[184:187], v[206:209], v[56:59]
	v_mfma_f32_16x16x32_bf16 v[48:51], v[198:201], v[206:209], v[48:51]
	v_mfma_f32_16x16x32_bf16 v[40:43], v[184:187], v[214:217], v[40:43]
	v_mfma_f32_16x16x32_bf16 v[32:35], v[198:201], v[214:217], v[32:35]
	v_mfma_f32_16x16x32_bf16 v[24:27], v[184:187], v[222:225], v[24:27]
	v_mfma_f32_16x16x32_bf16 v[16:19], v[198:201], v[222:225], v[16:19]
	v_mfma_f32_16x16x32_bf16 v[8:11], v[184:187], v[230:233], v[8:11]
	v_mfma_f32_16x16x32_bf16 v[0:3], v[198:201], v[230:233], v[0:3]
	s_barrier
	s_add_i32 s73, 0, 0x18000
	v_add_u32_e32 v157, s73, v151
	s_add_i32 s76, 0, 0x1c000
	ds_read_b128 v[144:147], v157
	ds_read_b128 v[168:171], v157 offset:1024
	ds_read_b128 v[172:175], v157 offset:2048
	ds_read_b128 v[176:179], v157 offset:3072
	v_add_u32_e32 v157, s76, v151
	ds_read_b128 v[180:183], v157
	ds_read_b128 v[184:187], v157 offset:1024
	ds_read_b128 v[188:191], v157 offset:2048
	ds_read_b128 v[198:201], v157 offset:3072
	s_add_u32 s6, s54, 0x40000
	s_addc_u32 s7, s55, 0
	s_mov_b32 m0, s43
	v_lshl_add_u64 v[236:237], s[6:7], 0, v[134:135]
	ds_read_b128 v[202:205], v156 offset:32768
	ds_read_b128 v[206:209], v156 offset:33792
	ds_read_b128 v[210:213], v156 offset:34816
	ds_read_b128 v[214:217], v156 offset:35840
	ds_read_b128 v[218:221], v156 offset:36864
	ds_read_b128 v[222:225], v156 offset:37888
	ds_read_b128 v[226:229], v156 offset:38912
	ds_read_b128 v[230:233], v156 offset:39936
	global_load_lds_dwordx4 v[236:237], off
	v_lshl_add_u64 v[236:237], s[6:7], 0, v[130:131]
	s_mov_b32 m0, s56
	s_nop 0
	global_load_lds_dwordx4 v[236:237], off
	s_waitcnt vmcnt(8)
	s_waitcnt lgkmcnt(0)
	s_barrier
	s_waitcnt lgkmcnt(0)
	v_mfma_f32_16x16x32_bf16 v[124:127], v[144:147], v[202:205], v[124:127]
	v_mfma_f32_16x16x32_bf16 v[116:119], v[172:175], v[202:205], v[116:119]
	v_mfma_f32_16x16x32_bf16 v[108:111], v[144:147], v[210:213], v[108:111]
	v_mfma_f32_16x16x32_bf16 v[100:103], v[172:175], v[210:213], v[100:103]
	v_mfma_f32_16x16x32_bf16 v[92:95], v[144:147], v[218:221], v[92:95]
	v_mfma_f32_16x16x32_bf16 v[84:87], v[172:175], v[218:221], v[84:87]
	v_mfma_f32_16x16x32_bf16 v[76:79], v[144:147], v[226:229], v[76:79]
	v_mfma_f32_16x16x32_bf16 v[68:71], v[172:175], v[226:229], v[68:71]
	v_mfma_f32_16x16x32_bf16 v[124:127], v[168:171], v[206:209], v[124:127]
	v_mfma_f32_16x16x32_bf16 v[116:119], v[176:179], v[206:209], v[116:119]
	v_mfma_f32_16x16x32_bf16 v[108:111], v[168:171], v[214:217], v[108:111]
	v_mfma_f32_16x16x32_bf16 v[100:103], v[176:179], v[214:217], v[100:103]
	v_mfma_f32_16x16x32_bf16 v[92:95], v[168:171], v[222:225], v[92:95]
	v_mfma_f32_16x16x32_bf16 v[84:87], v[176:179], v[222:225], v[84:87]
	v_mfma_f32_16x16x32_bf16 v[76:79], v[168:171], v[230:233], v[76:79]
	v_mfma_f32_16x16x32_bf16 v[68:71], v[176:179], v[230:233], v[68:71]
	v_mfma_f32_16x16x32_bf16 v[120:123], v[180:183], v[202:205], v[120:123]
	v_mfma_f32_16x16x32_bf16 v[112:115], v[188:191], v[202:205], v[112:115]
	v_mfma_f32_16x16x32_bf16 v[104:107], v[180:183], v[210:213], v[104:107]
	v_mfma_f32_16x16x32_bf16 v[96:99], v[188:191], v[210:213], v[96:99]
	v_mfma_f32_16x16x32_bf16 v[88:91], v[180:183], v[218:221], v[88:91]
	v_mfma_f32_16x16x32_bf16 v[80:83], v[188:191], v[218:221], v[80:83]
	v_mfma_f32_16x16x32_bf16 v[72:75], v[180:183], v[226:229], v[72:75]
	v_mfma_f32_16x16x32_bf16 v[64:67], v[188:191], v[226:229], v[64:67]
	v_mfma_f32_16x16x32_bf16 v[120:123], v[184:187], v[206:209], v[120:123]
	v_mfma_f32_16x16x32_bf16 v[112:115], v[198:201], v[206:209], v[112:115]
	v_mfma_f32_16x16x32_bf16 v[104:107], v[184:187], v[214:217], v[104:107]
	v_mfma_f32_16x16x32_bf16 v[96:99], v[198:201], v[214:217], v[96:99]
	v_mfma_f32_16x16x32_bf16 v[88:91], v[184:187], v[222:225], v[88:91]
	v_mfma_f32_16x16x32_bf16 v[80:83], v[198:201], v[222:225], v[80:83]
	v_mfma_f32_16x16x32_bf16 v[72:75], v[184:187], v[230:233], v[72:75]
	v_mfma_f32_16x16x32_bf16 v[64:67], v[198:201], v[230:233], v[64:67]
	s_barrier
; #define PG8_STAGE(bufoff, gbase, voff) do { _Pragma("unroll") for (int _i = 0; _i < 2; ++_i) \
;         __builtin_amdgcn_global_load_lds((const unsigned*)((const char*)(gbase) + (voff)[_i]), (PG8_LAS unsigned*)(lds + (bufoff) + ldsw + _i * 8192), 16, 0, 0); } while (0)
; #define PG8_LDA(dst, b, h) do { _Pragma("unroll") for (int m = 0; m < 4; ++m) _Pragma("unroll") for (int k = 0; k < 2; ++k) dst[m][k] = *(const PG8_LAS bf16x8*)(lds + PG8_SA(b, h) + aoff + m * 2048 + k * 1024); } while (0)
; #define PG8_MMA(ai, bj, At, Bt) do { __builtin_amdgcn_s_setprio(1); _Pragma("unroll") for (int m = 0; m < 4; ++m) _Pragma("unroll") for (int n = 0; n < 2; ++n) _Pragma("unroll") for (int k = 0; k < 2; ++k) \
;         acc[ai][bj][m][n] = __builtin_amdgcn_mfma_f32_16x16x32_bf16(Bt[n][k], At[m][k], acc[ai][bj][m][n], 0, 0, 0); __builtin_amdgcn_s_setprio(0); } while (0)
; #define PG8_WAIT_V(n) asm volatile("s_waitcnt vmcnt(" #n ")" ::: "memory")
; #define PG8_WAIT_L(n) asm volatile("s_waitcnt lgkmcnt(" #n ")" ::: "memory")
; #define PG8_BAR __builtin_amdgcn_s_barrier()
; #define PG8_SCHED __builtin_amdgcn_sched_barrier(0)
; template <class Epi, class Sched, bool ALIGN_EPI = false, bool SP2 = false>
; __device__ __forceinline__ void gemm_phase(PG8_LAS unsigned char* lds, const Gemm g, const Sched& S, const Epi& E) {
;     ...
;         for (int t = 0; t < nt; t += 2) {
;             const bool last = (t == nt - 2);
;             const char* a1 = cA + (size_t)(t + 1) * kstep;
;             const char* a2 = last ? nA : cA + (size_t)(t + 2) * kstep; const char* b2 = last ? nB : cB + (size_t)(t + 2) * kstep;
;     ...
;             PG8_LDA(At, 1, 1); PG8_STAGE(PG8_SB(1, 0), b3, voffB); PG8_STAGE(PG8_SB(1, 1), b3 + hstep, voffB); PG8_STAGE(PG8_SA(1, 0), a3, voffA);
;             PG8_WAIT_V(8); PG8_WAIT_L(0); PG8_BAR; PG8_MMA(1, 0, At, B0); PG8_MMA(1, 1, At, B1); PG8_BAR; PG8_SCHED;
	s_add_i32 s6, s73, s26
	v_lshl_add_u64 v[148:149], v[148:149], 0, s[30:31]
	s_mov_b32 m0, s6
	ds_read_b128 v[202:205], v156 offset:49152
	ds_read_b128 v[206:209], v156 offset:50176
	ds_read_b128 v[210:213], v156 offset:51200
	ds_read_b128 v[214:217], v156 offset:52224
	ds_read_b128 v[218:221], v156 offset:53248
	ds_read_b128 v[222:225], v156 offset:54272
	ds_read_b128 v[226:229], v156 offset:55296
	ds_read_b128 v[230:233], v156 offset:56320
	global_load_lds_dwordx4 v[148:149], off
	s_add_i32 m0, s6, 0x2000
	s_add_u32 s6, s52, 0x40080
	v_lshl_add_u64 v[148:149], v[158:159], 0, s[30:31]
	s_addc_u32 s7, s53, 0
	s_add_i32 s52, s76, s26
	global_load_lds_dwordx4 v[148:149], off
	v_lshl_add_u64 v[148:149], s[6:7], 0, v[132:133]
	s_mov_b32 m0, s52
	s_nop 0
	global_load_lds_dwordx4 v[148:149], off
	v_lshl_add_u64 v[148:149], s[6:7], 0, v[128:129]
	s_add_i32 m0, s52, 0x2000
	s_nop 0
	global_load_lds_dwordx4 v[148:149], off
	v_lshl_add_u64 v[148:149], v[164:165], 0, s[30:31]
	s_mov_b32 m0, s57
	s_nop 0
	global_load_lds_dwordx4 v[148:149], off
	v_lshl_add_u64 v[148:149], v[234:235], 0, s[30:31]
	s_mov_b32 m0, s58
	s_nop 0
	global_load_lds_dwordx4 v[148:149], off
	s_waitcnt vmcnt(8)
	s_waitcnt lgkmcnt(0)
	s_barrier
	s_waitcnt lgkmcnt(0)
	v_mfma_f32_16x16x32_bf16 v[60:63], v[144:147], v[202:205], v[60:63]
	v_mfma_f32_16x16x32_bf16 v[52:55], v[172:175], v[202:205], v[52:55]
	v_mfma_f32_16x16x32_bf16 v[44:47], v[144:147], v[210:213], v[44:47]
	v_mfma_f32_16x16x32_bf16 v[36:39], v[172:175], v[210:213], v[36:39]
	v_mfma_f32_16x16x32_bf16 v[28:31], v[144:147], v[218:221], v[28:31]
	v_mfma_f32_16x16x32_bf16 v[20:23], v[172:175], v[218:221], v[20:23]
	v_mfma_f32_16x16x32_bf16 v[12:15], v[144:147], v[226:229], v[12:15]
	v_mfma_f32_16x16x32_bf16 v[4:7], v[172:175], v[226:229], v[4:7]
	v_mfma_f32_16x16x32_bf16 v[60:63], v[168:171], v[206:209], v[60:63]
	v_mfma_f32_16x16x32_bf16 v[52:55], v[176:179], v[206:209], v[52:55]
	v_mfma_f32_16x16x32_bf16 v[44:47], v[168:171], v[214:217], v[44:47]
	v_mfma_f32_16x16x32_bf16 v[36:39], v[176:179], v[214:217], v[36:39]
	v_mfma_f32_16x16x32_bf16 v[28:31], v[168:171], v[222:225], v[28:31]
	v_mfma_f32_16x16x32_bf16 v[20:23], v[176:179], v[222:225], v[20:23]
	v_mfma_f32_16x16x32_bf16 v[12:15], v[168:171], v[230:233], v[12:15]
	v_mfma_f32_16x16x32_bf16 v[4:7], v[176:179], v[230:233], v[4:7]
	v_mfma_f32_16x16x32_bf16 v[56:59], v[180:183], v[202:205], v[56:59]
	v_mfma_f32_16x16x32_bf16 v[48:51], v[188:191], v[202:205], v[48:51]
	v_mfma_f32_16x16x32_bf16 v[40:43], v[180:183], v[210:213], v[40:43]
	v_mfma_f32_16x16x32_bf16 v[32:35], v[188:191], v[210:213], v[32:35]
	v_mfma_f32_16x16x32_bf16 v[24:27], v[180:183], v[218:221], v[24:27]
	v_mfma_f32_16x16x32_bf16 v[16:19], v[188:191], v[218:221], v[16:19]
	v_mfma_f32_16x16x32_bf16 v[8:11], v[180:183], v[226:229], v[8:11]
	v_mfma_f32_16x16x32_bf16 v[0:3], v[188:191], v[226:229], v[0:3]
	v_mfma_f32_16x16x32_bf16 v[56:59], v[184:187], v[206:209], v[56:59]
	v_mfma_f32_16x16x32_bf16 v[48:51], v[198:201], v[206:209], v[48:51]
	v_mfma_f32_16x16x32_bf16 v[40:43], v[184:187], v[214:217], v[40:43]
	v_mfma_f32_16x16x32_bf16 v[32:35], v[198:201], v[214:217], v[32:35]
	v_mfma_f32_16x16x32_bf16 v[24:27], v[184:187], v[222:225], v[24:27]
	v_mfma_f32_16x16x32_bf16 v[16:19], v[198:201], v[222:225], v[16:19]
	v_mfma_f32_16x16x32_bf16 v[8:11], v[184:187], v[230:233], v[8:11]
	v_mfma_f32_16x16x32_bf16 v[0:3], v[198:201], v[230:233], v[0:3]
	s_barrier
	s_add_i32 s72, s72, 2
	s_add_u32 s50, s50, 0x100
	s_addc_u32 s51, s51, 0
	s_add_u32 s75, s75, 0x100
	s_addc_u32 s33, s33, 0
	s_cmp_gt_u32 s72, 13
	s_cbranch_scc0 .LBB0_1822
	v_readlane_b32 s74, v243, 57
	s_and_b64 vcc, exec, s[34:35]
	v_readlane_b32 s75, v243, 58
	s_cbranch_vccz .LBB0_1825
	s_barrier

; #define PG8_STAGE(bufoff, gbase, voff) do { _Pragma("unroll") for (int _i = 0; _i < 2; ++_i) \
;         __builtin_amdgcn_global_load_lds((const unsigned*)((const char*)(gbase) + (voff)[_i]), (PG8_LAS unsigned*)(lds + (bufoff) + ldsw + _i * 8192), 16, 0, 0); } while (0)
; #define PG8_LDA(dst, b, h) do { _Pragma("unroll") for (int m = 0; m < 4; ++m) _Pragma("unroll") for (int k = 0; k < 2; ++k) dst[m][k] = *(const PG8_LAS bf16x8*)(lds + PG8_SA(b, h) + aoff + m * 2048 + k * 1024); } while (0)
; #define PG8_LDB(dst, b, h) do { _Pragma("unroll") for (int n = 0; n < 2; ++n) _Pragma("unroll") for (int k = 0; k < 2; ++k) dst[n][k] = *(const PG8_LAS bf16x8*)(lds + PG8_SB(b, h) + boff + n * 2048 + k * 1024); } while (0)
; #define PG8_MMA(ai, bj, At, Bt) do { __builtin_amdgcn_s_setprio(1); _Pragma("unroll") for (int m = 0; m < 4; ++m) _Pragma("unroll") for (int n = 0; n < 2; ++n) _Pragma("unroll") for (int k = 0; k < 2; ++k) \
;         acc[ai][bj][m][n] = __builtin_amdgcn_mfma_f32_16x16x32_bf16(Bt[n][k], At[m][k], acc[ai][bj][m][n], 0, 0, 0); __builtin_amdgcn_s_setprio(0); } while (0)
; #define PG8_WAIT_V(n) asm volatile("s_waitcnt vmcnt(" #n ")" ::: "memory")
; #define PG8_BAR __builtin_amdgcn_s_barrier()
; template <class Epi, class Sched, bool ALIGN_EPI = false, bool SP2 = false>
; __device__ __forceinline__ void gemm_phase(PG8_LAS unsigned char* lds, const Gemm g, const Sched& S, const Epi& E) {
;     ...
;         for (int t = 0; t < nt; t += 2) {
;             const bool last = (t == nt - 2);
;             const char* a1 = cA + (size_t)(t + 1) * kstep;
;             const char* a2 = last ? nA : cA + (size_t)(t + 2) * kstep; const char* b2 = last ? nB : cB + (size_t)(t + 2) * kstep;
;             const char* a3 = a2 + kstep; const char* b3 = b2 + kstep;
;             if (last && has_next) S.a_ready(nxt);
;             if constexpr (SP2) {
;             PG8_LDB(B0, 0, 0); PG8_LDB(B1, 0, 1); PG8_SCHED; PG8_LDA(At, 0, 0); PG8_STAGE(PG8_SA(1, 1), a1 + hstep, voffA);
;             PG8_WAIT_V(8); PG8_WAIT_L(0); PG8_BAR; PG8_MMA(0, 0, At, B0); PG8_MMA(0, 1, At, B1); PG8_BAR; PG8_SCHED;
;             PG8_LDA(At, 0, 1); PG8_STAGE(PG8_SB(0, 0), b2, voffB); PG8_STAGE(PG8_SB(0, 1), b2 + hstep, voffB); PG8_STAGE(PG8_SA(0, 0), a2, voffA);
;             PG8_WAIT_V(8); PG8_WAIT_L(0); PG8_BAR; PG8_MMA(1, 0, At, B0); PG8_MMA(1, 1, At, B1); PG8_BAR; PG8_SCHED;
.LBB0_1935:
	ds_read_b128 v[144:147], v153
	ds_read_b128 v[168:171], v153 offset:1024
	ds_read_b128 v[172:175], v153 offset:2048
	ds_read_b128 v[176:179], v153 offset:3072
	ds_read_b128 v[180:183], v154
	ds_read_b128 v[184:187], v154 offset:1024
	ds_read_b128 v[188:191], v154 offset:2048
	ds_read_b128 v[198:201], v154 offset:3072
	s_add_u32 s50, s48, 0x100
	s_addc_u32 s51, s49, 0
	s_cmp_eq_u32 s72, 40
	s_cselect_b32 s55, s41, s51
	s_cselect_b32 s54, s40, s50
	s_cselect_b32 s53, s47, s77
	s_cselect_b32 s52, s46, s33
	v_lshl_add_u64 v[148:149], s[48:49], 0, v[136:137]
	s_add_i32 m0, s58, 0xc000
	ds_read_b128 v[202:205], v155
	ds_read_b128 v[206:209], v155 offset:1024
	ds_read_b128 v[210:213], v155 offset:2048
	ds_read_b128 v[214:217], v155 offset:3072
	ds_read_b128 v[218:221], v155 offset:4096
	ds_read_b128 v[222:225], v155 offset:5120
	ds_read_b128 v[226:229], v155 offset:6144
	ds_read_b128 v[230:233], v155 offset:7168
	global_load_lds_dwordx4 v[148:149], off
	v_lshl_add_u64 v[148:149], s[48:49], 0, v[138:139]
	s_add_i32 m0, s58, 0xe000
	s_nop 0
	global_load_lds_dwordx4 v[148:149], off
	s_waitcnt vmcnt(8)
	s_waitcnt lgkmcnt(0)
	s_barrier
	s_waitcnt lgkmcnt(0)
	v_mfma_f32_16x16x32_bf16 v[124:127], v[144:147], v[202:205], v[124:127]
	v_mfma_f32_16x16x32_bf16 v[120:123], v[172:175], v[202:205], v[120:123]
	v_mfma_f32_16x16x32_bf16 v[108:111], v[144:147], v[210:213], v[108:111]
	v_mfma_f32_16x16x32_bf16 v[104:107], v[172:175], v[210:213], v[104:107]
	v_mfma_f32_16x16x32_bf16 v[92:95], v[144:147], v[218:221], v[92:95]
	v_mfma_f32_16x16x32_bf16 v[88:91], v[172:175], v[218:221], v[88:91]
	v_mfma_f32_16x16x32_bf16 v[76:79], v[144:147], v[226:229], v[76:79]
	v_mfma_f32_16x16x32_bf16 v[72:75], v[172:175], v[226:229], v[72:75]
	v_mfma_f32_16x16x32_bf16 v[124:127], v[168:171], v[206:209], v[124:127]
	v_mfma_f32_16x16x32_bf16 v[120:123], v[176:179], v[206:209], v[120:123]
	v_mfma_f32_16x16x32_bf16 v[108:111], v[168:171], v[214:217], v[108:111]
	v_mfma_f32_16x16x32_bf16 v[104:107], v[176:179], v[214:217], v[104:107]
	v_mfma_f32_16x16x32_bf16 v[92:95], v[168:171], v[222:225], v[92:95]
	v_mfma_f32_16x16x32_bf16 v[88:91], v[176:179], v[222:225], v[88:91]
	v_mfma_f32_16x16x32_bf16 v[76:79], v[168:171], v[230:233], v[76:79]
	v_mfma_f32_16x16x32_bf16 v[72:75], v[176:179], v[230:233], v[72:75]
	v_mfma_f32_16x16x32_bf16 v[116:119], v[180:183], v[202:205], v[116:119]
	v_mfma_f32_16x16x32_bf16 v[112:115], v[188:191], v[202:205], v[112:115]
	v_mfma_f32_16x16x32_bf16 v[100:103], v[180:183], v[210:213], v[100:103]
	v_mfma_f32_16x16x32_bf16 v[96:99], v[188:191], v[210:213], v[96:99]
	v_mfma_f32_16x16x32_bf16 v[84:87], v[180:183], v[218:221], v[84:87]
	v_mfma_f32_16x16x32_bf16 v[80:83], v[188:191], v[218:221], v[80:83]
	v_mfma_f32_16x16x32_bf16 v[68:71], v[180:183], v[226:229], v[68:71]
	v_mfma_f32_16x16x32_bf16 v[64:67], v[188:191], v[226:229], v[64:67]
	v_mfma_f32_16x16x32_bf16 v[116:119], v[184:187], v[206:209], v[116:119]
	v_mfma_f32_16x16x32_bf16 v[112:115], v[198:201], v[206:209], v[112:115]
	v_mfma_f32_16x16x32_bf16 v[100:103], v[184:187], v[214:217], v[100:103]
	v_mfma_f32_16x16x32_bf16 v[96:99], v[198:201], v[214:217], v[96:99]
	v_mfma_f32_16x16x32_bf16 v[84:87], v[184:187], v[222:225], v[84:87]
	v_mfma_f32_16x16x32_bf16 v[80:83], v[198:201], v[222:225], v[80:83]
	v_mfma_f32_16x16x32_bf16 v[68:71], v[184:187], v[230:233], v[68:71]
	v_mfma_f32_16x16x32_bf16 v[64:67], v[198:201], v[230:233], v[64:67]
	s_barrier
	s_add_i32 s6, s26, s57
	v_lshl_add_u64 v[148:149], s[52:53], 0, v[130:131]
	s_mov_b32 m0, s6
	ds_read_b128 v[202:205], v155 offset:16384
	ds_read_b128 v[206:209], v155 offset:17408
	ds_read_b128 v[210:213], v155 offset:18432
	ds_read_b128 v[214:217], v155 offset:19456
	ds_read_b128 v[218:221], v155 offset:20480
	ds_read_b128 v[222:225], v155 offset:21504
	ds_read_b128 v[226:229], v155 offset:22528
	ds_read_b128 v[230:233], v155 offset:23552
	global_load_lds_dwordx4 v[148:149], off
	s_add_i32 m0, s6, 0x2000
	s_add_u32 s6, s52, 0xb0000
	v_lshl_add_u64 v[158:159], s[52:53], 0, v[134:135]
	s_addc_u32 s7, s53, 0
	s_add_i32 s48, s74, s57
	global_load_lds_dwordx4 v[158:159], off
	v_lshl_add_u64 v[164:165], s[6:7], 0, v[130:131]
	s_mov_b32 m0, s48
	v_lshl_add_u64 v[234:235], s[54:55], 0, v[132:133]
	global_load_lds_dwordx4 v[164:165], off
	v_lshl_add_u64 v[164:165], s[6:7], 0, v[134:135]
	s_add_i32 m0, s48, 0x2000
	s_nop 0
	global_load_lds_dwordx4 v[164:165], off
	v_lshl_add_u64 v[164:165], s[54:55], 0, v[128:129]
	s_mov_b32 m0, s58
	s_nop 0
	global_load_lds_dwordx4 v[164:165], off
	s_mov_b32 m0, s59
	s_nop 0
	global_load_lds_dwordx4 v[234:235], off
	s_waitcnt vmcnt(8)
	s_waitcnt lgkmcnt(0)
	s_barrier
; #define PG8_STAGE(bufoff, gbase, voff) do { _Pragma("unroll") for (int _i = 0; _i < 2; ++_i) \
;         __builtin_amdgcn_global_load_lds((const unsigned*)((const char*)(gbase) + (voff)[_i]), (PG8_LAS unsigned*)(lds + (bufoff) + ldsw + _i * 8192), 16, 0, 0); } while (0)
; #define PG8_LDA(dst, b, h) do { _Pragma("unroll") for (int m = 0; m < 4; ++m) _Pragma("unroll") for (int k = 0; k < 2; ++k) dst[m][k] = *(const PG8_LAS bf16x8*)(lds + PG8_SA(b, h) + aoff + m * 2048 + k * 1024); } while (0)
; #define PG8_LDB(dst, b, h) do { _Pragma("unroll") for (int n = 0; n < 2; ++n) _Pragma("unroll") for (int k = 0; k < 2; ++k) dst[n][k] = *(const PG8_LAS bf16x8*)(lds + PG8_SB(b, h) + boff + n * 2048 + k * 1024); } while (0)
; #define PG8_MMA(ai, bj, At, Bt) do { __builtin_amdgcn_s_setprio(1); _Pragma("unroll") for (int m = 0; m < 4; ++m) _Pragma("unroll") for (int n = 0; n < 2; ++n) _Pragma("unroll") for (int k = 0; k < 2; ++k) \
;         acc[ai][bj][m][n] = __builtin_amdgcn_mfma_f32_16x16x32_bf16(Bt[n][k], At[m][k], acc[ai][bj][m][n], 0, 0, 0); __builtin_amdgcn_s_setprio(0); } while (0)
; #define PG8_WAIT_V(n) asm volatile("s_waitcnt vmcnt(" #n ")" ::: "memory")
; #define PG8_WAIT_L(n) asm volatile("s_waitcnt lgkmcnt(" #n ")" ::: "memory")
; #define PG8_BAR __builtin_amdgcn_s_barrier()
; #define PG8_SCHED __builtin_amdgcn_sched_barrier(0)
; template <class Epi, class Sched, bool ALIGN_EPI = false, bool SP2 = false>
; __device__ __forceinline__ void gemm_phase(PG8_LAS unsigned char* lds, const Gemm g, const Sched& S, const Epi& E) {
;     ...
;             PG8_WAIT_V(8); PG8_WAIT_L(0); PG8_BAR; PG8_MMA(1, 0, At, B0); PG8_MMA(1, 1, At, B1); PG8_BAR; PG8_SCHED;
;             PG8_LDB(B0, 1, 0); PG8_LDB(B1, 1, 1); PG8_SCHED; PG8_LDA(At, 1, 0); PG8_STAGE(PG8_SA(0, 1), a2 + hstep, voffA);
;             PG8_WAIT_V(8); PG8_WAIT_L(0); PG8_BAR; PG8_MMA(0, 0, At, B0); PG8_MMA(0, 1, At, B1); PG8_BAR; PG8_SCHED;
	s_waitcnt lgkmcnt(0)
	v_mfma_f32_16x16x32_bf16 v[60:63], v[144:147], v[202:205], v[60:63]
	v_mfma_f32_16x16x32_bf16 v[56:59], v[172:175], v[202:205], v[56:59]
	v_mfma_f32_16x16x32_bf16 v[44:47], v[144:147], v[210:213], v[44:47]
	v_mfma_f32_16x16x32_bf16 v[40:43], v[172:175], v[210:213], v[40:43]
	v_mfma_f32_16x16x32_bf16 v[28:31], v[144:147], v[218:221], v[28:31]
	v_mfma_f32_16x16x32_bf16 v[24:27], v[172:175], v[218:221], v[24:27]
	v_mfma_f32_16x16x32_bf16 v[12:15], v[144:147], v[226:229], v[12:15]
	v_mfma_f32_16x16x32_bf16 v[8:11], v[172:175], v[226:229], v[8:11]
	v_mfma_f32_16x16x32_bf16 v[60:63], v[168:171], v[206:209], v[60:63]
	v_mfma_f32_16x16x32_bf16 v[56:59], v[176:179], v[206:209], v[56:59]
	v_mfma_f32_16x16x32_bf16 v[44:47], v[168:171], v[214:217], v[44:47]
	v_mfma_f32_16x16x32_bf16 v[40:43], v[176:179], v[214:217], v[40:43]
	v_mfma_f32_16x16x32_bf16 v[28:31], v[168:171], v[222:225], v[28:31]
	v_mfma_f32_16x16x32_bf16 v[24:27], v[176:179], v[222:225], v[24:27]
	v_mfma_f32_16x16x32_bf16 v[12:15], v[168:171], v[230:233], v[12:15]
	v_mfma_f32_16x16x32_bf16 v[8:11], v[176:179], v[230:233], v[8:11]
	v_mfma_f32_16x16x32_bf16 v[52:55], v[180:183], v[202:205], v[52:55]
	v_mfma_f32_16x16x32_bf16 v[48:51], v[188:191], v[202:205], v[48:51]
	v_mfma_f32_16x16x32_bf16 v[36:39], v[180:183], v[210:213], v[36:39]
	v_mfma_f32_16x16x32_bf16 v[32:35], v[188:191], v[210:213], v[32:35]
	v_mfma_f32_16x16x32_bf16 v[20:23], v[180:183], v[218:221], v[20:23]
	v_mfma_f32_16x16x32_bf16 v[16:19], v[188:191], v[218:221], v[16:19]
	v_mfma_f32_16x16x32_bf16 v[4:7], v[180:183], v[226:229], v[4:7]
	v_mfma_f32_16x16x32_bf16 v[0:3], v[188:191], v[226:229], v[0:3]
	v_mfma_f32_16x16x32_bf16 v[52:55], v[184:187], v[206:209], v[52:55]
	v_mfma_f32_16x16x32_bf16 v[48:51], v[198:201], v[206:209], v[48:51]
	v_mfma_f32_16x16x32_bf16 v[36:39], v[184:187], v[214:217], v[36:39]
	v_mfma_f32_16x16x32_bf16 v[32:35], v[198:201], v[214:217], v[32:35]
	v_mfma_f32_16x16x32_bf16 v[20:23], v[184:187], v[222:225], v[20:23]
	v_mfma_f32_16x16x32_bf16 v[16:19], v[198:201], v[222:225], v[16:19]
	v_mfma_f32_16x16x32_bf16 v[4:7], v[184:187], v[230:233], v[4:7]
	v_mfma_f32_16x16x32_bf16 v[0:3], v[198:201], v[230:233], v[0:3]
	s_barrier
	s_add_i32 s48, 0, 0x18000
	v_add_u32_e32 v157, s48, v151
	s_add_i32 s49, 0, 0x1c000
	ds_read_b128 v[144:147], v157
	ds_read_b128 v[168:171], v157 offset:1024
	ds_read_b128 v[172:175], v157 offset:2048
	ds_read_b128 v[176:179], v157 offset:3072
	v_add_u32_e32 v157, s49, v151
	ds_read_b128 v[180:183], v157
	ds_read_b128 v[184:187], v157 offset:1024
	ds_read_b128 v[188:191], v157 offset:2048
	ds_read_b128 v[198:201], v157 offset:3072
	s_add_u32 s6, s54, 0xb0000
	s_addc_u32 s7, s55, 0
	s_mov_b32 m0, s60
	v_lshl_add_u64 v[236:237], s[6:7], 0, v[128:129]
	ds_read_b128 v[202:205], v155 offset:32768
	ds_read_b128 v[206:209], v155 offset:33792
	ds_read_b128 v[210:213], v155 offset:34816
	ds_read_b128 v[214:217], v155 offset:35840
	ds_read_b128 v[218:221], v155 offset:36864
	ds_read_b128 v[222:225], v155 offset:37888
	ds_read_b128 v[226:229], v155 offset:38912
	ds_read_b128 v[230:233], v155 offset:39936
	global_load_lds_dwordx4 v[236:237], off
	v_lshl_add_u64 v[236:237], s[6:7], 0, v[132:133]
	s_mov_b32 m0, s61
	s_nop 0
	global_load_lds_dwordx4 v[236:237], off
	s_waitcnt vmcnt(8)
	s_waitcnt lgkmcnt(0)
	s_barrier
	s_waitcnt lgkmcnt(0)
	v_mfma_f32_16x16x32_bf16 v[124:127], v[144:147], v[202:205], v[124:127]
	v_mfma_f32_16x16x32_bf16 v[120:123], v[172:175], v[202:205], v[120:123]
	v_mfma_f32_16x16x32_bf16 v[108:111], v[144:147], v[210:213], v[108:111]
	v_mfma_f32_16x16x32_bf16 v[104:107], v[172:175], v[210:213], v[104:107]
	v_mfma_f32_16x16x32_bf16 v[92:95], v[144:147], v[218:221], v[92:95]
	v_mfma_f32_16x16x32_bf16 v[88:91], v[172:175], v[218:221], v[88:91]
	v_mfma_f32_16x16x32_bf16 v[76:79], v[144:147], v[226:229], v[76:79]
	v_mfma_f32_16x16x32_bf16 v[72:75], v[172:175], v[226:229], v[72:75]
	v_mfma_f32_16x16x32_bf16 v[124:127], v[168:171], v[206:209], v[124:127]
	v_mfma_f32_16x16x32_bf16 v[120:123], v[176:179], v[206:209], v[120:123]
	v_mfma_f32_16x16x32_bf16 v[108:111], v[168:171], v[214:217], v[108:111]
	v_mfma_f32_16x16x32_bf16 v[104:107], v[176:179], v[214:217], v[104:107]
	v_mfma_f32_16x16x32_bf16 v[92:95], v[168:171], v[222:225], v[92:95]
	v_mfma_f32_16x16x32_bf16 v[88:91], v[176:179], v[222:225], v[88:91]
	v_mfma_f32_16x16x32_bf16 v[76:79], v[168:171], v[230:233], v[76:79]
	v_mfma_f32_16x16x32_bf16 v[72:75], v[176:179], v[230:233], v[72:75]
	v_mfma_f32_16x16x32_bf16 v[116:119], v[180:183], v[202:205], v[116:119]
	v_mfma_f32_16x16x32_bf16 v[112:115], v[188:191], v[202:205], v[112:115]
	v_mfma_f32_16x16x32_bf16 v[100:103], v[180:183], v[210:213], v[100:103]
	v_mfma_f32_16x16x32_bf16 v[96:99], v[188:191], v[210:213], v[96:99]
	v_mfma_f32_16x16x32_bf16 v[84:87], v[180:183], v[218:221], v[84:87]
	v_mfma_f32_16x16x32_bf16 v[80:83], v[188:191], v[218:221], v[80:83]
	v_mfma_f32_16x16x32_bf16 v[68:71], v[180:183], v[226:229], v[68:71]
	v_mfma_f32_16x16x32_bf16 v[64:67], v[188:191], v[226:229], v[64:67]
	v_mfma_f32_16x16x32_bf16 v[116:119], v[184:187], v[206:209], v[116:119]
	v_mfma_f32_16x16x32_bf16 v[112:115], v[198:201], v[206:209], v[112:115]
	v_mfma_f32_16x16x32_bf16 v[100:103], v[184:187], v[214:217], v[100:103]
	v_mfma_f32_16x16x32_bf16 v[96:99], v[198:201], v[214:217], v[96:99]
	v_mfma_f32_16x16x32_bf16 v[84:87], v[184:187], v[222:225], v[84:87]
	v_mfma_f32_16x16x32_bf16 v[80:83], v[198:201], v[222:225], v[80:83]
	v_mfma_f32_16x16x32_bf16 v[68:71], v[184:187], v[230:233], v[68:71]
	v_mfma_f32_16x16x32_bf16 v[64:67], v[198:201], v[230:233], v[64:67]
	s_barrier
; #define PG8_STAGE(bufoff, gbase, voff) do { _Pragma("unroll") for (int _i = 0; _i < 2; ++_i) \
;         __builtin_amdgcn_global_load_lds((const unsigned*)((const char*)(gbase) + (voff)[_i]), (PG8_LAS unsigned*)(lds + (bufoff) + ldsw + _i * 8192), 16, 0, 0); } while (0)
; #define PG8_LDA(dst, b, h) do { _Pragma("unroll") for (int m = 0; m < 4; ++m) _Pragma("unroll") for (int k = 0; k < 2; ++k) dst[m][k] = *(const PG8_LAS bf16x8*)(lds + PG8_SA(b, h) + aoff + m * 2048 + k * 1024); } while (0)
; #define PG8_MMA(ai, bj, At, Bt) do { __builtin_amdgcn_s_setprio(1); _Pragma("unroll") for (int m = 0; m < 4; ++m) _Pragma("unroll") for (int n = 0; n < 2; ++n) _Pragma("unroll") for (int k = 0; k < 2; ++k) \
;         acc[ai][bj][m][n] = __builtin_amdgcn_mfma_f32_16x16x32_bf16(Bt[n][k], At[m][k], acc[ai][bj][m][n], 0, 0, 0); __builtin_amdgcn_s_setprio(0); } while (0)
; #define PG8_WAIT_V(n) asm volatile("s_waitcnt vmcnt(" #n ")" ::: "memory")
; #define PG8_WAIT_L(n) asm volatile("s_waitcnt lgkmcnt(" #n ")" ::: "memory")
; #define PG8_BAR __builtin_amdgcn_s_barrier()
; #define PG8_SCHED __builtin_amdgcn_sched_barrier(0)
; template <class Epi, class Sched, bool ALIGN_EPI = false, bool SP2 = false>
; __device__ __forceinline__ void gemm_phase(PG8_LAS unsigned char* lds, const Gemm g, const Sched& S, const Epi& E) {
;     ...
;         for (int t = 0; t < nt; t += 2) {
;             const bool last = (t == nt - 2);
;             const char* a1 = cA + (size_t)(t + 1) * kstep;
;             const char* a2 = last ? nA : cA + (size_t)(t + 2) * kstep; const char* b2 = last ? nB : cB + (size_t)(t + 2) * kstep;
;     ...
;             PG8_LDA(At, 1, 1); PG8_STAGE(PG8_SB(1, 0), b3, voffB); PG8_STAGE(PG8_SB(1, 1), b3 + hstep, voffB); PG8_STAGE(PG8_SA(1, 0), a3, voffA);
;             PG8_WAIT_V(8); PG8_WAIT_L(0); PG8_BAR; PG8_MMA(1, 0, At, B0); PG8_MMA(1, 1, At, B1); PG8_BAR; PG8_SCHED;
	s_add_i32 s6, s48, s57
	v_lshl_add_u64 v[148:149], v[148:149], 0, s[36:37]
	s_mov_b32 m0, s6
	ds_read_b128 v[202:205], v155 offset:49152
	ds_read_b128 v[206:209], v155 offset:50176
	ds_read_b128 v[210:213], v155 offset:51200
	ds_read_b128 v[214:217], v155 offset:52224
	ds_read_b128 v[218:221], v155 offset:53248
	ds_read_b128 v[222:225], v155 offset:54272
	ds_read_b128 v[226:229], v155 offset:55296
	ds_read_b128 v[230:233], v155 offset:56320
	global_load_lds_dwordx4 v[148:149], off
	s_add_i32 m0, s6, 0x2000
	s_add_u32 s6, s52, 0xb0080
	v_lshl_add_u64 v[148:149], v[158:159], 0, s[36:37]
	s_addc_u32 s7, s53, 0
	s_add_i32 s48, s49, s57
	global_load_lds_dwordx4 v[148:149], off
	v_lshl_add_u64 v[148:149], s[6:7], 0, v[130:131]
	s_mov_b32 m0, s48
	s_nop 0
	global_load_lds_dwordx4 v[148:149], off
	v_lshl_add_u64 v[148:149], s[6:7], 0, v[134:135]
	s_add_i32 m0, s48, 0x2000
	s_nop 0
	global_load_lds_dwordx4 v[148:149], off
	v_lshl_add_u64 v[148:149], v[164:165], 0, s[36:37]
	s_mov_b32 m0, s76
	s_nop 0
	global_load_lds_dwordx4 v[148:149], off
	v_lshl_add_u64 v[148:149], v[234:235], 0, s[36:37]
	s_mov_b32 m0, s4
	s_nop 0
	global_load_lds_dwordx4 v[148:149], off
	s_waitcnt vmcnt(8)
	s_waitcnt lgkmcnt(0)
	s_barrier
	s_waitcnt lgkmcnt(0)
	v_mfma_f32_16x16x32_bf16 v[60:63], v[144:147], v[202:205], v[60:63]
	v_mfma_f32_16x16x32_bf16 v[56:59], v[172:175], v[202:205], v[56:59]
	v_mfma_f32_16x16x32_bf16 v[44:47], v[144:147], v[210:213], v[44:47]
	v_mfma_f32_16x16x32_bf16 v[40:43], v[172:175], v[210:213], v[40:43]
	v_mfma_f32_16x16x32_bf16 v[28:31], v[144:147], v[218:221], v[28:31]
	v_mfma_f32_16x16x32_bf16 v[24:27], v[172:175], v[218:221], v[24:27]
	v_mfma_f32_16x16x32_bf16 v[12:15], v[144:147], v[226:229], v[12:15]
	v_mfma_f32_16x16x32_bf16 v[8:11], v[172:175], v[226:229], v[8:11]
	v_mfma_f32_16x16x32_bf16 v[60:63], v[168:171], v[206:209], v[60:63]
	v_mfma_f32_16x16x32_bf16 v[56:59], v[176:179], v[206:209], v[56:59]
	v_mfma_f32_16x16x32_bf16 v[44:47], v[168:171], v[214:217], v[44:47]
	v_mfma_f32_16x16x32_bf16 v[40:43], v[176:179], v[214:217], v[40:43]
	v_mfma_f32_16x16x32_bf16 v[28:31], v[168:171], v[222:225], v[28:31]
	v_mfma_f32_16x16x32_bf16 v[24:27], v[176:179], v[222:225], v[24:27]
	v_mfma_f32_16x16x32_bf16 v[12:15], v[168:171], v[230:233], v[12:15]
	v_mfma_f32_16x16x32_bf16 v[8:11], v[176:179], v[230:233], v[8:11]
	v_mfma_f32_16x16x32_bf16 v[52:55], v[180:183], v[202:205], v[52:55]
	v_mfma_f32_16x16x32_bf16 v[48:51], v[188:191], v[202:205], v[48:51]
	v_mfma_f32_16x16x32_bf16 v[36:39], v[180:183], v[210:213], v[36:39]
	v_mfma_f32_16x16x32_bf16 v[32:35], v[188:191], v[210:213], v[32:35]
	v_mfma_f32_16x16x32_bf16 v[20:23], v[180:183], v[218:221], v[20:23]
	v_mfma_f32_16x16x32_bf16 v[16:19], v[188:191], v[218:221], v[16:19]
	v_mfma_f32_16x16x32_bf16 v[4:7], v[180:183], v[226:229], v[4:7]
	v_mfma_f32_16x16x32_bf16 v[0:3], v[188:191], v[226:229], v[0:3]
	v_mfma_f32_16x16x32_bf16 v[52:55], v[184:187], v[206:209], v[52:55]
	v_mfma_f32_16x16x32_bf16 v[48:51], v[198:201], v[206:209], v[48:51]
	v_mfma_f32_16x16x32_bf16 v[36:39], v[184:187], v[214:217], v[36:39]
	v_mfma_f32_16x16x32_bf16 v[32:35], v[198:201], v[214:217], v[32:35]
	v_mfma_f32_16x16x32_bf16 v[20:23], v[184:187], v[222:225], v[20:23]
	v_mfma_f32_16x16x32_bf16 v[16:19], v[198:201], v[222:225], v[16:19]
	v_mfma_f32_16x16x32_bf16 v[4:7], v[184:187], v[230:233], v[4:7]
	v_mfma_f32_16x16x32_bf16 v[0:3], v[198:201], v[230:233], v[0:3]
	s_barrier
	s_add_i32 s72, s72, 2
	s_add_u32 s33, s33, 0x100
	s_addc_u32 s77, s77, 0
	s_cmp_gt_u32 s72, 41
	s_mov_b64 s[48:49], s[50:51]
	s_cbranch_scc0 .LBB0_1935
	s_and_b64 vcc, exec, s[38:39]
	s_cbranch_vccz .LBB0_1938
	s_barrier
